# GEMM K-loops: s_setprio 1 moved from after to before the barrier that starts each MFMA segment
# baseline (speedup 1.0000x reference)
; #define PG8_STAGE(bufoff, gbase, voff) do { _Pragma("unroll") for (int _i = 0; _i < 2; ++_i) \
;         __builtin_amdgcn_global_load_lds((const unsigned*)((const char*)(gbase) + (voff)[_i]), (LAS unsigned*)(lds + (bufoff) + ldsw + _i * 8192), 16, 0, 0); } while (0)
; #define PG8_LDA(dst, b, h) do { _Pragma("unroll") for (int m = 0; m < 4; ++m) _Pragma("unroll") for (int k = 0; k < 2; ++k) dst[m][k] = *(const LAS bf16x8*)(lds + PG8_SA(b, h) + aoff + m * 2048 + k * 1024); } while (0)
; #define PG8_LDB(dst, b, h) do { _Pragma("unroll") for (int n = 0; n < 2; ++n) _Pragma("unroll") for (int k = 0; k < 2; ++k) dst[n][k] = *(const LAS bf16x8*)(lds + PG8_SB(b, h) + boff + n * 2048 + k * 1024); } while (0)
; template <class Epi, class Sched, bool ALIGN_EPI, bool LAST_FUSED = false, bool PERM = false, bool CARRY = false>
; __device__ __forceinline__ void gemm_phase(LAS unsigned char* lds, const int tid, const int K, const int lda, const int ldb, const Sched& S, const Epi& E) {
;     ...
;         for (int t = 0; t < nt; t += 2) {
;             const bool last = (t == nt - 2);
;             const char* a1 = cA + (size_t)(t + 1) * kstep;
;             const char* a2 = last ? nA : cA + (size_t)(t + 2) * kstep; const char* b2 = last ? nB : cB + (size_t)(t + 2) * kstep;
;             const char* a3 = a2 + kstep; const char* b3 = b2 + kstep;
;             PG8_LDB(B0, 0, 0); PG8_LDB(B1, 0, 1); PG8_SCHED; PG8_LDA(At, 0, 0); PG8_STAGE(PG8_SA(1, 1), a1 + hstepA, voffA);
;             PG8_WAIT_V(8); PG8_WAIT_L(0); PG8_BAR; PG8_MMA(0, 0, At, B0); PG8_MMA(0, 1, At, B1); PG8_BAR; PG8_SCHED;
;             PG8_LDA(At, 0, 1); PG8_STAGE(PG8_SB(0, 0), b2, voffB); PG8_STAGE(PG8_SB(0, 1), b2 + hstepB, voffB); PG8_STAGE(PG8_SA(0, 0), a2, voffA);
;             PG8_WAIT_V(8); PG8_WAIT_L(0); PG8_BAR; PG8_MMA(1, 0, At, B0); PG8_MMA(1, 1, At, B1); PG8_BAR; PG8_SCHED;
;             PG8_LDB(B0, 1, 0); PG8_LDB(B1, 1, 1); PG8_SCHED; PG8_LDA(At, 1, 0); PG8_STAGE(PG8_SA(0, 1), a2 + hstepA, voffA);
;             PG8_WAIT_V(8); PG8_WAIT_L(0); PG8_BAR; PG8_MMA(0, 0, At, B0); PG8_MMA(0, 1, At, B1); PG8_BAR; PG8_SCHED;
;             PG8_LDA(At, 1, 1); PG8_STAGE(PG8_SB(1, 0), b3, voffB); PG8_STAGE(PG8_SB(1, 1), b3 + hstepB, voffB); PG8_STAGE(PG8_SA(1, 0), a3, voffA);
;             PG8_WAIT_V(8); PG8_WAIT_L(0); PG8_BAR; PG8_MMA(1, 0, At, B0); PG8_MMA(1, 1, At, B1); PG8_BAR; PG8_SCHED;
.LBB0_279:
	s_add_u32 s4, s2, 0xfff80080
	s_addc_u32 s5, s3, -1
	s_add_i32 s28, 0, 0x10000
	s_cmp_eq_u32 s27, 28
	s_cselect_b32 s37, s43, s5
	s_cselect_b32 s36, s42, s4
	s_cselect_b32 s5, s71, s23
	s_cselect_b32 s4, s70, s22
	s_add_i32 s31, 0, 0x14000
	v_add_u32_e32 v154, s28, v144
	v_add_u32_e32 v170, s31, v144
	ds_read_b128 v[136:139], v154
	ds_read_b128 v[146:149], v154 offset:1024
	ds_read_b128 v[150:153], v154 offset:2048
	ds_read_b128 v[154:157], v154 offset:3072
	ds_read_b128 v[158:161], v170
	ds_read_b128 v[162:165], v170 offset:1024
	ds_read_b128 v[166:169], v170 offset:2048
	ds_read_b128 v[170:173], v170 offset:3072
	v_lshl_add_u64 v[206:207], s[2:3], 0, v[132:133]
	s_add_i32 m0, s52, 0xc000
	ds_read_b128 v[174:177], v145
	ds_read_b128 v[178:181], v145 offset:1024
	ds_read_b128 v[182:185], v145 offset:2048
	ds_read_b128 v[186:189], v145 offset:3072
	ds_read_b128 v[190:193], v145 offset:4096
	ds_read_b128 v[194:197], v145 offset:5120
	ds_read_b128 v[198:201], v145 offset:6144
	ds_read_b128 v[202:205], v145 offset:7168
	global_load_lds_dwordx4 v[206:207], off
	v_lshl_add_u64 v[206:207], s[2:3], 0, v[134:135]
	s_add_i32 m0, s52, 0xe000
	s_nop 0
	global_load_lds_dwordx4 v[206:207], off
	s_waitcnt vmcnt(8)
	s_waitcnt lgkmcnt(0)
	s_setprio 1
	s_barrier
	v_mfma_f32_16x16x32_bf16 v[126:129], v[136:139], v[174:177], v[126:129]
	v_mfma_f32_16x16x32_bf16 v[122:125], v[150:153], v[174:177], v[122:125]
	v_mfma_f32_16x16x32_bf16 v[110:113], v[136:139], v[182:185], v[110:113]
	v_mfma_f32_16x16x32_bf16 v[106:109], v[150:153], v[182:185], v[106:109]
	v_mfma_f32_16x16x32_bf16 v[94:97], v[136:139], v[190:193], v[94:97]
	v_mfma_f32_16x16x32_bf16 v[90:93], v[150:153], v[190:193], v[90:93]
	v_mfma_f32_16x16x32_bf16 v[78:81], v[136:139], v[198:201], v[78:81]
	v_mfma_f32_16x16x32_bf16 v[74:77], v[150:153], v[198:201], v[74:77]
	v_mfma_f32_16x16x32_bf16 v[126:129], v[146:149], v[178:181], v[126:129]
	v_mfma_f32_16x16x32_bf16 v[122:125], v[154:157], v[178:181], v[122:125]
	v_mfma_f32_16x16x32_bf16 v[110:113], v[146:149], v[186:189], v[110:113]
	v_mfma_f32_16x16x32_bf16 v[106:109], v[154:157], v[186:189], v[106:109]
	v_mfma_f32_16x16x32_bf16 v[94:97], v[146:149], v[194:197], v[94:97]
	v_mfma_f32_16x16x32_bf16 v[90:93], v[154:157], v[194:197], v[90:93]
	v_mfma_f32_16x16x32_bf16 v[78:81], v[146:149], v[202:205], v[78:81]
	v_mfma_f32_16x16x32_bf16 v[74:77], v[154:157], v[202:205], v[74:77]
	s_setprio 0
	s_setprio 1
	v_mfma_f32_16x16x32_bf16 v[118:121], v[158:161], v[174:177], v[118:121]
	v_mfma_f32_16x16x32_bf16 v[114:117], v[166:169], v[174:177], v[114:117]
	v_mfma_f32_16x16x32_bf16 v[102:105], v[158:161], v[182:185], v[102:105]
	v_mfma_f32_16x16x32_bf16 v[98:101], v[166:169], v[182:185], v[98:101]
	v_mfma_f32_16x16x32_bf16 v[86:89], v[158:161], v[190:193], v[86:89]
	v_mfma_f32_16x16x32_bf16 v[82:85], v[166:169], v[190:193], v[82:85]
	v_mfma_f32_16x16x32_bf16 v[70:73], v[158:161], v[198:201], v[70:73]
	v_mfma_f32_16x16x32_bf16 v[66:69], v[166:169], v[198:201], v[66:69]
	v_mfma_f32_16x16x32_bf16 v[118:121], v[162:165], v[178:181], v[118:121]
	v_mfma_f32_16x16x32_bf16 v[114:117], v[170:173], v[178:181], v[114:117]
	v_mfma_f32_16x16x32_bf16 v[102:105], v[162:165], v[186:189], v[102:105]
	v_mfma_f32_16x16x32_bf16 v[98:101], v[170:173], v[186:189], v[98:101]
	v_mfma_f32_16x16x32_bf16 v[86:89], v[162:165], v[194:197], v[86:89]
	v_mfma_f32_16x16x32_bf16 v[82:85], v[170:173], v[194:197], v[82:85]
	v_mfma_f32_16x16x32_bf16 v[70:73], v[162:165], v[202:205], v[70:73]
	v_mfma_f32_16x16x32_bf16 v[66:69], v[170:173], v[202:205], v[66:69]
	s_barrier
	s_setprio 0
	s_add_i32 s28, s28, s51
	v_lshl_add_u64 v[206:207], s[4:5], 0, v[0:1]
	s_mov_b32 m0, s28
	ds_read_b128 v[174:177], v145 offset:16384
	ds_read_b128 v[178:181], v145 offset:17408
	ds_read_b128 v[182:185], v145 offset:18432
	ds_read_b128 v[186:189], v145 offset:19456
	ds_read_b128 v[190:193], v145 offset:20480
	ds_read_b128 v[194:197], v145 offset:21504
	ds_read_b128 v[198:201], v145 offset:22528
	ds_read_b128 v[202:205], v145 offset:23552
	global_load_lds_dwordx4 v[206:207], off
	s_add_i32 m0, s28, 0x2000
	s_add_u32 s28, s4, 0x80000
	v_lshl_add_u64 v[208:209], s[4:5], 0, v[130:131]
	s_addc_u32 s29, s5, 0
	s_add_i32 s31, s31, s51
	global_load_lds_dwordx4 v[208:209], off
	v_lshl_add_u64 v[210:211], s[28:29], 0, v[0:1]
	s_mov_b32 m0, s31
	v_lshl_add_u64 v[212:213], s[36:37], 0, v[130:131]
	global_load_lds_dwordx4 v[210:211], off
	v_lshl_add_u64 v[210:211], s[28:29], 0, v[130:131]
	s_add_i32 m0, s31, 0x2000
	s_nop 0
	global_load_lds_dwordx4 v[210:211], off
	v_lshl_add_u64 v[210:211], s[36:37], 0, v[0:1]
	s_mov_b32 m0, s52
	s_nop 0
	global_load_lds_dwordx4 v[210:211], off
	s_mov_b32 m0, s53
	s_nop 0
	global_load_lds_dwordx4 v[212:213], off
	s_waitcnt vmcnt(8)
	s_waitcnt lgkmcnt(0)
	s_setprio 1
	s_barrier
; #define PG8_STAGE(bufoff, gbase, voff) do { _Pragma("unroll") for (int _i = 0; _i < 2; ++_i) \
;         __builtin_amdgcn_global_load_lds((const unsigned*)((const char*)(gbase) + (voff)[_i]), (LAS unsigned*)(lds + (bufoff) + ldsw + _i * 8192), 16, 0, 0); } while (0)
; #define PG8_LDA(dst, b, h) do { _Pragma("unroll") for (int m = 0; m < 4; ++m) _Pragma("unroll") for (int k = 0; k < 2; ++k) dst[m][k] = *(const LAS bf16x8*)(lds + PG8_SA(b, h) + aoff + m * 2048 + k * 1024); } while (0)
; #define PG8_LDB(dst, b, h) do { _Pragma("unroll") for (int n = 0; n < 2; ++n) _Pragma("unroll") for (int k = 0; k < 2; ++k) dst[n][k] = *(const LAS bf16x8*)(lds + PG8_SB(b, h) + boff + n * 2048 + k * 1024); } while (0)
; #define PG8_MMA(ai, bj, At, Bt) do { __builtin_amdgcn_s_setprio(1); _Pragma("unroll") for (int m = 0; m < 4; ++m) _Pragma("unroll") for (int n = 0; n < 2; ++n) _Pragma("unroll") for (int k = 0; k < 2; ++k) \
;         acc[ai][bj][m][n] = __builtin_amdgcn_mfma_f32_16x16x32_bf16(Bt[n][k], At[m][k], acc[ai][bj][m][n], 0, 0, 0); __builtin_amdgcn_s_setprio(0); } while (0)
; #define PG8_WAIT_V(n) asm volatile("s_waitcnt vmcnt(" #n ")" ::: "memory")
; #define PG8_WAIT_L(n) asm volatile("s_waitcnt lgkmcnt(" #n ")" ::: "memory")
; #define PG8_BAR __builtin_amdgcn_s_barrier()
; #define PG8_SCHED __builtin_amdgcn_sched_barrier(0)
; template <class Epi, class Sched, bool ALIGN_EPI, bool LAST_FUSED = false, bool PERM = false, bool CARRY = false>
; __device__ __forceinline__ void gemm_phase(LAS unsigned char* lds, const int tid, const int K, const int lda, const int ldb, const Sched& S, const Epi& E) {
;     ...
;             PG8_WAIT_V(8); PG8_WAIT_L(0); PG8_BAR; PG8_MMA(1, 0, At, B0); PG8_MMA(1, 1, At, B1); PG8_BAR; PG8_SCHED;
;             PG8_LDB(B0, 1, 0); PG8_LDB(B1, 1, 1); PG8_SCHED; PG8_LDA(At, 1, 0); PG8_STAGE(PG8_SA(0, 1), a2 + hstepA, voffA);
;             PG8_WAIT_V(8); PG8_WAIT_L(0); PG8_BAR; PG8_MMA(0, 0, At, B0); PG8_MMA(0, 1, At, B1); PG8_BAR; PG8_SCHED;
;             PG8_LDA(At, 1, 1); PG8_STAGE(PG8_SB(1, 0), b3, voffB); PG8_STAGE(PG8_SB(1, 1), b3 + hstepB, voffB); PG8_STAGE(PG8_SA(1, 0), a3, voffA);
;             PG8_WAIT_V(8); PG8_WAIT_L(0); PG8_BAR; PG8_MMA(1, 0, At, B0); PG8_MMA(1, 1, At, B1); PG8_BAR; PG8_SCHED;
	v_mfma_f32_16x16x32_bf16 v[62:65], v[136:139], v[174:177], v[62:65]
	v_mfma_f32_16x16x32_bf16 v[58:61], v[150:153], v[174:177], v[58:61]
	v_mfma_f32_16x16x32_bf16 v[46:49], v[136:139], v[182:185], v[46:49]
	v_mfma_f32_16x16x32_bf16 v[42:45], v[150:153], v[182:185], v[42:45]
	v_mfma_f32_16x16x32_bf16 v[30:33], v[136:139], v[190:193], v[30:33]
	v_mfma_f32_16x16x32_bf16 v[26:29], v[150:153], v[190:193], v[26:29]
	v_mfma_f32_16x16x32_bf16 v[14:17], v[136:139], v[198:201], v[14:17]
	v_mfma_f32_16x16x32_bf16 v[10:13], v[150:153], v[198:201], v[10:13]
	v_mfma_f32_16x16x32_bf16 v[62:65], v[146:149], v[178:181], v[62:65]
	v_mfma_f32_16x16x32_bf16 v[58:61], v[154:157], v[178:181], v[58:61]
	v_mfma_f32_16x16x32_bf16 v[46:49], v[146:149], v[186:189], v[46:49]
	v_mfma_f32_16x16x32_bf16 v[42:45], v[154:157], v[186:189], v[42:45]
	v_mfma_f32_16x16x32_bf16 v[30:33], v[146:149], v[194:197], v[30:33]
	v_mfma_f32_16x16x32_bf16 v[26:29], v[154:157], v[194:197], v[26:29]
	v_mfma_f32_16x16x32_bf16 v[14:17], v[146:149], v[202:205], v[14:17]
	v_mfma_f32_16x16x32_bf16 v[10:13], v[154:157], v[202:205], v[10:13]
	s_setprio 0
	s_setprio 1
	v_mfma_f32_16x16x32_bf16 v[54:57], v[158:161], v[174:177], v[54:57]
	v_mfma_f32_16x16x32_bf16 v[50:53], v[166:169], v[174:177], v[50:53]
	v_mfma_f32_16x16x32_bf16 v[38:41], v[158:161], v[182:185], v[38:41]
	v_mfma_f32_16x16x32_bf16 v[34:37], v[166:169], v[182:185], v[34:37]
	v_mfma_f32_16x16x32_bf16 v[22:25], v[158:161], v[190:193], v[22:25]
	v_mfma_f32_16x16x32_bf16 v[18:21], v[166:169], v[190:193], v[18:21]
	v_mfma_f32_16x16x32_bf16 v[6:9], v[158:161], v[198:201], v[6:9]
	v_mfma_f32_16x16x32_bf16 v[2:5], v[166:169], v[198:201], v[2:5]
	v_mfma_f32_16x16x32_bf16 v[54:57], v[162:165], v[178:181], v[54:57]
	v_mfma_f32_16x16x32_bf16 v[50:53], v[170:173], v[178:181], v[50:53]
	v_mfma_f32_16x16x32_bf16 v[38:41], v[162:165], v[186:189], v[38:41]
	v_mfma_f32_16x16x32_bf16 v[34:37], v[170:173], v[186:189], v[34:37]
	v_mfma_f32_16x16x32_bf16 v[22:25], v[162:165], v[194:197], v[22:25]
	v_mfma_f32_16x16x32_bf16 v[18:21], v[170:173], v[194:197], v[18:21]
	v_mfma_f32_16x16x32_bf16 v[6:9], v[162:165], v[202:205], v[6:9]
	v_mfma_f32_16x16x32_bf16 v[2:5], v[170:173], v[202:205], v[2:5]
	s_barrier
	s_setprio 0
	s_add_i32 s31, 0, 0x18000
	s_add_i32 s35, 0, 0x1c000
	v_add_u32_e32 v154, s31, v144
	v_add_u32_e32 v170, s35, v144
	ds_read_b128 v[136:139], v154
	ds_read_b128 v[146:149], v154 offset:1024
	ds_read_b128 v[150:153], v154 offset:2048
	ds_read_b128 v[154:157], v154 offset:3072
	ds_read_b128 v[158:161], v170
	ds_read_b128 v[162:165], v170 offset:1024
	ds_read_b128 v[166:169], v170 offset:2048
	ds_read_b128 v[170:173], v170 offset:3072
	s_add_u32 s28, s36, 0x80000
	s_addc_u32 s29, s37, 0
	s_mov_b32 m0, s54
	v_lshl_add_u64 v[214:215], s[28:29], 0, v[0:1]
	ds_read_b128 v[174:177], v145 offset:32768
	ds_read_b128 v[178:181], v145 offset:33792
	ds_read_b128 v[182:185], v145 offset:34816
	ds_read_b128 v[186:189], v145 offset:35840
	ds_read_b128 v[190:193], v145 offset:36864
	ds_read_b128 v[194:197], v145 offset:37888
	ds_read_b128 v[198:201], v145 offset:38912
	ds_read_b128 v[202:205], v145 offset:39936
	global_load_lds_dwordx4 v[214:215], off
	v_lshl_add_u64 v[214:215], s[28:29], 0, v[130:131]
	s_mov_b32 m0, s55
	s_nop 0
	global_load_lds_dwordx4 v[214:215], off
	s_waitcnt vmcnt(8)
	s_waitcnt lgkmcnt(0)
	s_setprio 1
	s_barrier
	v_mfma_f32_16x16x32_bf16 v[126:129], v[136:139], v[174:177], v[126:129]
	v_mfma_f32_16x16x32_bf16 v[122:125], v[150:153], v[174:177], v[122:125]
	v_mfma_f32_16x16x32_bf16 v[110:113], v[136:139], v[182:185], v[110:113]
	v_mfma_f32_16x16x32_bf16 v[106:109], v[150:153], v[182:185], v[106:109]
	v_mfma_f32_16x16x32_bf16 v[94:97], v[136:139], v[190:193], v[94:97]
	v_mfma_f32_16x16x32_bf16 v[90:93], v[150:153], v[190:193], v[90:93]
	v_mfma_f32_16x16x32_bf16 v[78:81], v[136:139], v[198:201], v[78:81]
	v_mfma_f32_16x16x32_bf16 v[74:77], v[150:153], v[198:201], v[74:77]
	v_mfma_f32_16x16x32_bf16 v[126:129], v[146:149], v[178:181], v[126:129]
	v_mfma_f32_16x16x32_bf16 v[122:125], v[154:157], v[178:181], v[122:125]
	v_mfma_f32_16x16x32_bf16 v[110:113], v[146:149], v[186:189], v[110:113]
	v_mfma_f32_16x16x32_bf16 v[106:109], v[154:157], v[186:189], v[106:109]
	v_mfma_f32_16x16x32_bf16 v[94:97], v[146:149], v[194:197], v[94:97]
	v_mfma_f32_16x16x32_bf16 v[90:93], v[154:157], v[194:197], v[90:93]
	v_mfma_f32_16x16x32_bf16 v[78:81], v[146:149], v[202:205], v[78:81]
	v_mfma_f32_16x16x32_bf16 v[74:77], v[154:157], v[202:205], v[74:77]
	s_setprio 0
	s_setprio 1
	v_mfma_f32_16x16x32_bf16 v[118:121], v[158:161], v[174:177], v[118:121]
	v_mfma_f32_16x16x32_bf16 v[114:117], v[166:169], v[174:177], v[114:117]
	v_mfma_f32_16x16x32_bf16 v[102:105], v[158:161], v[182:185], v[102:105]
	v_mfma_f32_16x16x32_bf16 v[98:101], v[166:169], v[182:185], v[98:101]
	v_mfma_f32_16x16x32_bf16 v[86:89], v[158:161], v[190:193], v[86:89]
	v_mfma_f32_16x16x32_bf16 v[82:85], v[166:169], v[190:193], v[82:85]
	v_mfma_f32_16x16x32_bf16 v[70:73], v[158:161], v[198:201], v[70:73]
	v_mfma_f32_16x16x32_bf16 v[66:69], v[166:169], v[198:201], v[66:69]
	v_mfma_f32_16x16x32_bf16 v[118:121], v[162:165], v[178:181], v[118:121]
	v_mfma_f32_16x16x32_bf16 v[114:117], v[170:173], v[178:181], v[114:117]
	v_mfma_f32_16x16x32_bf16 v[102:105], v[162:165], v[186:189], v[102:105]
	v_mfma_f32_16x16x32_bf16 v[98:101], v[170:173], v[186:189], v[98:101]
	v_mfma_f32_16x16x32_bf16 v[86:89], v[162:165], v[194:197], v[86:89]
	v_mfma_f32_16x16x32_bf16 v[82:85], v[170:173], v[194:197], v[82:85]
	v_mfma_f32_16x16x32_bf16 v[70:73], v[162:165], v[202:205], v[70:73]
	v_mfma_f32_16x16x32_bf16 v[66:69], v[170:173], v[202:205], v[66:69]
	s_barrier
; #define PG8_STAGE(bufoff, gbase, voff) do { _Pragma("unroll") for (int _i = 0; _i < 2; ++_i) \
;         __builtin_amdgcn_global_load_lds((const unsigned*)((const char*)(gbase) + (voff)[_i]), (LAS unsigned*)(lds + (bufoff) + ldsw + _i * 8192), 16, 0, 0); } while (0)
; #define PG8_LDA(dst, b, h) do { _Pragma("unroll") for (int m = 0; m < 4; ++m) _Pragma("unroll") for (int k = 0; k < 2; ++k) dst[m][k] = *(const LAS bf16x8*)(lds + PG8_SA(b, h) + aoff + m * 2048 + k * 1024); } while (0)
; #define PG8_LDB(dst, b, h) do { _Pragma("unroll") for (int n = 0; n < 2; ++n) _Pragma("unroll") for (int k = 0; k < 2; ++k) dst[n][k] = *(const LAS bf16x8*)(lds + PG8_SB(b, h) + boff + n * 2048 + k * 1024); } while (0)
; #define PG8_MMA(ai, bj, At, Bt) do { __builtin_amdgcn_s_setprio(1); _Pragma("unroll") for (int m = 0; m < 4; ++m) _Pragma("unroll") for (int n = 0; n < 2; ++n) _Pragma("unroll") for (int k = 0; k < 2; ++k) \
;         acc[ai][bj][m][n] = __builtin_amdgcn_mfma_f32_16x16x32_bf16(Bt[n][k], At[m][k], acc[ai][bj][m][n], 0, 0, 0); __builtin_amdgcn_s_setprio(0); } while (0)
; #define PG8_WAIT_V(n) asm volatile("s_waitcnt vmcnt(" #n ")" ::: "memory")
; #define PG8_WAIT_L(n) asm volatile("s_waitcnt lgkmcnt(" #n ")" ::: "memory")
; #define PG8_BAR __builtin_amdgcn_s_barrier()
; #define PG8_SCHED __builtin_amdgcn_sched_barrier(0)
; template <class Epi, class Sched, bool ALIGN_EPI, bool LAST_FUSED = false, bool PERM = false, bool CARRY = false>
; __device__ __forceinline__ void gemm_phase(LAS unsigned char* lds, const int tid, const int K, const int lda, const int ldb, const Sched& S, const Epi& E) {
;     ...
;             PG8_LDB(B0, 1, 0); PG8_LDB(B1, 1, 1); PG8_SCHED; PG8_LDA(At, 1, 0); PG8_STAGE(PG8_SA(0, 1), a2 + hstepA, voffA);
;             PG8_WAIT_V(8); PG8_WAIT_L(0); PG8_BAR; PG8_MMA(0, 0, At, B0); PG8_MMA(0, 1, At, B1); PG8_BAR; PG8_SCHED;
;             PG8_LDA(At, 1, 1); PG8_STAGE(PG8_SB(1, 0), b3, voffB); PG8_STAGE(PG8_SB(1, 1), b3 + hstepB, voffB); PG8_STAGE(PG8_SA(1, 0), a3, voffA);
;             PG8_WAIT_V(8); PG8_WAIT_L(0); PG8_BAR; PG8_MMA(1, 0, At, B0); PG8_MMA(1, 1, At, B1); PG8_BAR; PG8_SCHED;
;         }
;         if constexpr (ALIGN_EPI) { if (wr == 0) PG8_BAR; }
	s_setprio 0
	s_add_i32 s28, s31, s51
	v_lshl_add_u64 v[206:207], v[206:207], 0, s[68:69]
	s_mov_b32 m0, s28
	ds_read_b128 v[174:177], v145 offset:49152
	ds_read_b128 v[178:181], v145 offset:50176
	ds_read_b128 v[182:185], v145 offset:51200
	ds_read_b128 v[186:189], v145 offset:52224
	ds_read_b128 v[190:193], v145 offset:53248
	ds_read_b128 v[194:197], v145 offset:54272
	ds_read_b128 v[198:201], v145 offset:55296
	ds_read_b128 v[202:205], v145 offset:56320
	global_load_lds_dwordx4 v[206:207], off
	s_add_i32 m0, s28, 0x2000
	s_add_u32 s4, s4, 0x80080
	v_lshl_add_u64 v[206:207], v[208:209], 0, s[68:69]
	s_addc_u32 s5, s5, 0
	s_add_i32 s28, s35, s51
	global_load_lds_dwordx4 v[206:207], off
	v_lshl_add_u64 v[206:207], s[4:5], 0, v[0:1]
	s_mov_b32 m0, s28
	s_nop 0
	global_load_lds_dwordx4 v[206:207], off
	v_lshl_add_u64 v[206:207], s[4:5], 0, v[130:131]
	s_add_i32 m0, s28, 0x2000
	s_nop 0
	global_load_lds_dwordx4 v[206:207], off
	v_lshl_add_u64 v[206:207], v[210:211], 0, s[68:69]
	s_mov_b32 m0, s57
	s_nop 0
	global_load_lds_dwordx4 v[206:207], off
	v_lshl_add_u64 v[206:207], v[212:213], 0, s[68:69]
	s_mov_b32 m0, s58
	s_nop 0
	global_load_lds_dwordx4 v[206:207], off
	s_waitcnt vmcnt(8)
	s_waitcnt lgkmcnt(0)
	s_setprio 1
	s_barrier
	v_mfma_f32_16x16x32_bf16 v[62:65], v[136:139], v[174:177], v[62:65]
	v_mfma_f32_16x16x32_bf16 v[58:61], v[150:153], v[174:177], v[58:61]
	v_mfma_f32_16x16x32_bf16 v[46:49], v[136:139], v[182:185], v[46:49]
	v_mfma_f32_16x16x32_bf16 v[42:45], v[150:153], v[182:185], v[42:45]
	v_mfma_f32_16x16x32_bf16 v[30:33], v[136:139], v[190:193], v[30:33]
	v_mfma_f32_16x16x32_bf16 v[26:29], v[150:153], v[190:193], v[26:29]
	v_mfma_f32_16x16x32_bf16 v[14:17], v[136:139], v[198:201], v[14:17]
	v_mfma_f32_16x16x32_bf16 v[10:13], v[150:153], v[198:201], v[10:13]
	v_mfma_f32_16x16x32_bf16 v[62:65], v[146:149], v[178:181], v[62:65]
	v_mfma_f32_16x16x32_bf16 v[58:61], v[154:157], v[178:181], v[58:61]
	v_mfma_f32_16x16x32_bf16 v[46:49], v[146:149], v[186:189], v[46:49]
	v_mfma_f32_16x16x32_bf16 v[42:45], v[154:157], v[186:189], v[42:45]
	v_mfma_f32_16x16x32_bf16 v[30:33], v[146:149], v[194:197], v[30:33]
	v_mfma_f32_16x16x32_bf16 v[26:29], v[154:157], v[194:197], v[26:29]
	v_mfma_f32_16x16x32_bf16 v[14:17], v[146:149], v[202:205], v[14:17]
	v_mfma_f32_16x16x32_bf16 v[10:13], v[154:157], v[202:205], v[10:13]
	s_setprio 0
	s_setprio 1
	v_mfma_f32_16x16x32_bf16 v[54:57], v[158:161], v[174:177], v[54:57]
	v_mfma_f32_16x16x32_bf16 v[50:53], v[166:169], v[174:177], v[50:53]
	v_mfma_f32_16x16x32_bf16 v[38:41], v[158:161], v[182:185], v[38:41]
	v_mfma_f32_16x16x32_bf16 v[34:37], v[166:169], v[182:185], v[34:37]
	v_mfma_f32_16x16x32_bf16 v[22:25], v[158:161], v[190:193], v[22:25]
	v_mfma_f32_16x16x32_bf16 v[18:21], v[166:169], v[190:193], v[18:21]
	v_mfma_f32_16x16x32_bf16 v[6:9], v[158:161], v[198:201], v[6:9]
	v_mfma_f32_16x16x32_bf16 v[2:5], v[166:169], v[198:201], v[2:5]
	v_mfma_f32_16x16x32_bf16 v[54:57], v[162:165], v[178:181], v[54:57]
	v_mfma_f32_16x16x32_bf16 v[50:53], v[170:173], v[178:181], v[50:53]
	v_mfma_f32_16x16x32_bf16 v[38:41], v[162:165], v[186:189], v[38:41]
	v_mfma_f32_16x16x32_bf16 v[34:37], v[170:173], v[186:189], v[34:37]
	v_mfma_f32_16x16x32_bf16 v[22:25], v[162:165], v[194:197], v[22:25]
	v_mfma_f32_16x16x32_bf16 v[18:21], v[170:173], v[194:197], v[18:21]
	v_mfma_f32_16x16x32_bf16 v[6:9], v[162:165], v[202:205], v[6:9]
	v_mfma_f32_16x16x32_bf16 v[2:5], v[170:173], v[202:205], v[2:5]
	s_barrier
	s_setprio 0
	s_add_i32 s27, s27, 2
	s_add_u32 s2, s2, 0x100
	s_addc_u32 s3, s3, 0
	s_add_u32 s22, s22, 0x100
	s_addc_u32 s23, s23, 0
	s_cmp_gt_u32 s27, 29
	s_cbranch_scc0 .LBB0_279
	s_and_b64 vcc, exec, s[18:19]
	s_cbranch_vccz .LBB0_282
	s_barrier

; #define PG8_STAGE(bufoff, gbase, voff) do { _Pragma("unroll") for (int _i = 0; _i < 2; ++_i) \
;         __builtin_amdgcn_global_load_lds((const unsigned*)((const char*)(gbase) + (voff)[_i]), (LAS unsigned*)(lds + (bufoff) + ldsw + _i * 8192), 16, 0, 0); } while (0)
; #define PG8_LDA(dst, b, h) do { _Pragma("unroll") for (int m = 0; m < 4; ++m) _Pragma("unroll") for (int k = 0; k < 2; ++k) dst[m][k] = *(const LAS bf16x8*)(lds + PG8_SA(b, h) + aoff + m * 2048 + k * 1024); } while (0)
; #define PG8_LDB(dst, b, h) do { _Pragma("unroll") for (int n = 0; n < 2; ++n) _Pragma("unroll") for (int k = 0; k < 2; ++k) dst[n][k] = *(const LAS bf16x8*)(lds + PG8_SB(b, h) + boff + n * 2048 + k * 1024); } while (0)
; template <class Epi, class Sched, bool ALIGN_EPI, bool LAST_FUSED = false, bool PERM = false, bool CARRY = false>
; __device__ __forceinline__ void gemm_phase(LAS unsigned char* lds, const int tid, const int K, const int lda, const int ldb, const Sched& S, const Epi& E) {
;     ...
;         for (int t = 0; t < nt; t += 2) {
;             const bool last = (t == nt - 2);
;             const char* a1 = cA + (size_t)(t + 1) * kstep;
;             const char* a2 = last ? nA : cA + (size_t)(t + 2) * kstep; const char* b2 = last ? nB : cB + (size_t)(t + 2) * kstep;
;             const char* a3 = a2 + kstep; const char* b3 = b2 + kstep;
;             PG8_LDB(B0, 0, 0); PG8_LDB(B1, 0, 1); PG8_SCHED; PG8_LDA(At, 0, 0); PG8_STAGE(PG8_SA(1, 1), a1 + hstepA, voffA);
;             PG8_WAIT_V(8); PG8_WAIT_L(0); PG8_BAR; PG8_MMA(0, 0, At, B0); PG8_MMA(0, 1, At, B1); PG8_BAR; PG8_SCHED;
;             PG8_LDA(At, 0, 1); PG8_STAGE(PG8_SB(0, 0), b2, voffB); PG8_STAGE(PG8_SB(0, 1), b2 + hstepB, voffB); PG8_STAGE(PG8_SA(0, 0), a2, voffA);
;             PG8_WAIT_V(8); PG8_WAIT_L(0); PG8_BAR; PG8_MMA(1, 0, At, B0); PG8_MMA(1, 1, At, B1); PG8_BAR; PG8_SCHED;
;             PG8_LDB(B0, 1, 0); PG8_LDB(B1, 1, 1); PG8_SCHED; PG8_LDA(At, 1, 0); PG8_STAGE(PG8_SA(0, 1), a2 + hstepA, voffA);
;             PG8_WAIT_V(8); PG8_WAIT_L(0); PG8_BAR; PG8_MMA(0, 0, At, B0); PG8_MMA(0, 1, At, B1); PG8_BAR; PG8_SCHED;
;             PG8_LDA(At, 1, 1); PG8_STAGE(PG8_SB(1, 0), b3, voffB); PG8_STAGE(PG8_SB(1, 1), b3 + hstepB, voffB); PG8_STAGE(PG8_SA(1, 0), a3, voffA);
;             PG8_WAIT_V(8); PG8_WAIT_L(0); PG8_BAR; PG8_MMA(1, 0, At, B0); PG8_MMA(1, 1, At, B1); PG8_BAR; PG8_SCHED;
.LBB0_512:
	s_add_u32 s28, s4, 0xfff80080
	s_addc_u32 s29, s5, -1
	s_add_i32 s31, 0, 0x10000
	s_cmp_eq_u32 s24, 28
	s_cselect_b32 s41, s87, s29
	s_cselect_b32 s40, s86, s28
	v_add_u32_e32 v148, s31, v160
	s_cselect_b32 s37, s39, s23
	s_cselect_b32 s36, s38, s22
	s_add_i32 s35, 0, 0x14000
	ds_read_b128 v[140:143], v148
	ds_read_b128 v[144:147], v148 offset:1024
	ds_read_b128 v[162:165], v148 offset:2048
	ds_read_b128 v[166:169], v148 offset:3072
	v_add_u32_e32 v148, s35, v160
	ds_read_b128 v[170:173], v148
	ds_read_b128 v[174:177], v148 offset:1024
	ds_read_b128 v[178:181], v148 offset:2048
	ds_read_b128 v[182:185], v148 offset:3072
	v_lshl_add_u64 v[148:149], s[4:5], 0, v[136:137]
	s_add_i32 m0, s54, 0xc000
	ds_read_b128 v[186:189], v161
	ds_read_b128 v[190:193], v161 offset:1024
	ds_read_b128 v[194:197], v161 offset:2048
	ds_read_b128 v[198:201], v161 offset:3072
	ds_read_b128 v[202:205], v161 offset:4096
	ds_read_b128 v[206:209], v161 offset:5120
	ds_read_b128 v[210:213], v161 offset:6144
	ds_read_b128 v[214:217], v161 offset:7168
	global_load_lds_dwordx4 v[148:149], off
	v_lshl_add_u64 v[148:149], s[4:5], 0, v[138:139]
	s_add_i32 m0, s54, 0xe000
	s_nop 0
	global_load_lds_dwordx4 v[148:149], off
	s_waitcnt vmcnt(8)
	s_waitcnt lgkmcnt(0)
	s_setprio 1
	s_barrier
	v_mfma_f32_16x16x32_bf16 v[126:129], v[140:143], v[186:189], v[126:129]
	v_mfma_f32_16x16x32_bf16 v[122:125], v[162:165], v[186:189], v[122:125]
	v_mfma_f32_16x16x32_bf16 v[110:113], v[140:143], v[194:197], v[110:113]
	v_mfma_f32_16x16x32_bf16 v[106:109], v[162:165], v[194:197], v[106:109]
	v_mfma_f32_16x16x32_bf16 v[94:97], v[140:143], v[202:205], v[94:97]
	v_mfma_f32_16x16x32_bf16 v[90:93], v[162:165], v[202:205], v[90:93]
	v_mfma_f32_16x16x32_bf16 v[78:81], v[140:143], v[210:213], v[78:81]
	v_mfma_f32_16x16x32_bf16 v[74:77], v[162:165], v[210:213], v[74:77]
	v_mfma_f32_16x16x32_bf16 v[126:129], v[144:147], v[190:193], v[126:129]
	v_mfma_f32_16x16x32_bf16 v[122:125], v[166:169], v[190:193], v[122:125]
	v_mfma_f32_16x16x32_bf16 v[110:113], v[144:147], v[198:201], v[110:113]
	v_mfma_f32_16x16x32_bf16 v[106:109], v[166:169], v[198:201], v[106:109]
	v_mfma_f32_16x16x32_bf16 v[94:97], v[144:147], v[206:209], v[94:97]
	v_mfma_f32_16x16x32_bf16 v[90:93], v[166:169], v[206:209], v[90:93]
	v_mfma_f32_16x16x32_bf16 v[78:81], v[144:147], v[214:217], v[78:81]
	v_mfma_f32_16x16x32_bf16 v[74:77], v[166:169], v[214:217], v[74:77]
	s_setprio 0
	s_setprio 1
	v_mfma_f32_16x16x32_bf16 v[118:121], v[170:173], v[186:189], v[118:121]
	v_mfma_f32_16x16x32_bf16 v[114:117], v[178:181], v[186:189], v[114:117]
	v_mfma_f32_16x16x32_bf16 v[102:105], v[170:173], v[194:197], v[102:105]
	v_mfma_f32_16x16x32_bf16 v[98:101], v[178:181], v[194:197], v[98:101]
	v_mfma_f32_16x16x32_bf16 v[86:89], v[170:173], v[202:205], v[86:89]
	v_mfma_f32_16x16x32_bf16 v[82:85], v[178:181], v[202:205], v[82:85]
	v_mfma_f32_16x16x32_bf16 v[70:73], v[170:173], v[210:213], v[70:73]
	v_mfma_f32_16x16x32_bf16 v[66:69], v[178:181], v[210:213], v[66:69]
	v_mfma_f32_16x16x32_bf16 v[118:121], v[174:177], v[190:193], v[118:121]
	v_mfma_f32_16x16x32_bf16 v[114:117], v[182:185], v[190:193], v[114:117]
	v_mfma_f32_16x16x32_bf16 v[102:105], v[174:177], v[198:201], v[102:105]
	v_mfma_f32_16x16x32_bf16 v[98:101], v[182:185], v[198:201], v[98:101]
	v_mfma_f32_16x16x32_bf16 v[86:89], v[174:177], v[206:209], v[86:89]
	v_mfma_f32_16x16x32_bf16 v[82:85], v[182:185], v[206:209], v[82:85]
	v_mfma_f32_16x16x32_bf16 v[70:73], v[174:177], v[214:217], v[70:73]
	v_mfma_f32_16x16x32_bf16 v[66:69], v[182:185], v[214:217], v[66:69]
	s_barrier
	s_setprio 0
	s_add_i32 s28, s31, s52
	v_lshl_add_u64 v[148:149], s[36:37], 0, v[0:1]
	s_mov_b32 m0, s28
	ds_read_b128 v[186:189], v161 offset:16384
	ds_read_b128 v[190:193], v161 offset:17408
	ds_read_b128 v[194:197], v161 offset:18432
	ds_read_b128 v[198:201], v161 offset:19456
	ds_read_b128 v[202:205], v161 offset:20480
	ds_read_b128 v[206:209], v161 offset:21504
	ds_read_b128 v[210:213], v161 offset:22528
	ds_read_b128 v[214:217], v161 offset:23552
	global_load_lds_dwordx4 v[148:149], off
	s_add_i32 m0, s28, 0x2000
	s_add_u32 s28, s36, 0x80000
	v_lshl_add_u64 v[152:153], s[36:37], 0, v[130:131]
	s_addc_u32 s29, s37, 0
	s_add_i32 s31, s35, s52
	global_load_lds_dwordx4 v[152:153], off
	v_lshl_add_u64 v[156:157], s[28:29], 0, v[0:1]
	s_mov_b32 m0, s31
	v_lshl_add_u64 v[218:219], s[40:41], 0, v[132:133]
	global_load_lds_dwordx4 v[156:157], off
	v_lshl_add_u64 v[156:157], s[28:29], 0, v[130:131]
	s_add_i32 m0, s31, 0x2000
	s_nop 0
	global_load_lds_dwordx4 v[156:157], off
	v_lshl_add_u64 v[156:157], s[40:41], 0, v[134:135]
	s_mov_b32 m0, s54
	s_nop 0
	global_load_lds_dwordx4 v[156:157], off
	s_mov_b32 m0, s55
	s_nop 0
	global_load_lds_dwordx4 v[218:219], off
	s_waitcnt vmcnt(8)
	s_waitcnt lgkmcnt(0)
	s_setprio 1
	s_barrier
; #define PG8_STAGE(bufoff, gbase, voff) do { _Pragma("unroll") for (int _i = 0; _i < 2; ++_i) \
;         __builtin_amdgcn_global_load_lds((const unsigned*)((const char*)(gbase) + (voff)[_i]), (LAS unsigned*)(lds + (bufoff) + ldsw + _i * 8192), 16, 0, 0); } while (0)
; #define PG8_LDA(dst, b, h) do { _Pragma("unroll") for (int m = 0; m < 4; ++m) _Pragma("unroll") for (int k = 0; k < 2; ++k) dst[m][k] = *(const LAS bf16x8*)(lds + PG8_SA(b, h) + aoff + m * 2048 + k * 1024); } while (0)
; #define PG8_LDB(dst, b, h) do { _Pragma("unroll") for (int n = 0; n < 2; ++n) _Pragma("unroll") for (int k = 0; k < 2; ++k) dst[n][k] = *(const LAS bf16x8*)(lds + PG8_SB(b, h) + boff + n * 2048 + k * 1024); } while (0)
; #define PG8_MMA(ai, bj, At, Bt) do { __builtin_amdgcn_s_setprio(1); _Pragma("unroll") for (int m = 0; m < 4; ++m) _Pragma("unroll") for (int n = 0; n < 2; ++n) _Pragma("unroll") for (int k = 0; k < 2; ++k) \
;         acc[ai][bj][m][n] = __builtin_amdgcn_mfma_f32_16x16x32_bf16(Bt[n][k], At[m][k], acc[ai][bj][m][n], 0, 0, 0); __builtin_amdgcn_s_setprio(0); } while (0)
; #define PG8_WAIT_V(n) asm volatile("s_waitcnt vmcnt(" #n ")" ::: "memory")
; #define PG8_WAIT_L(n) asm volatile("s_waitcnt lgkmcnt(" #n ")" ::: "memory")
; #define PG8_BAR __builtin_amdgcn_s_barrier()
; #define PG8_SCHED __builtin_amdgcn_sched_barrier(0)
; template <class Epi, class Sched, bool ALIGN_EPI, bool LAST_FUSED = false, bool PERM = false, bool CARRY = false>
; __device__ __forceinline__ void gemm_phase(LAS unsigned char* lds, const int tid, const int K, const int lda, const int ldb, const Sched& S, const Epi& E) {
;     ...
;             PG8_WAIT_V(8); PG8_WAIT_L(0); PG8_BAR; PG8_MMA(1, 0, At, B0); PG8_MMA(1, 1, At, B1); PG8_BAR; PG8_SCHED;
;             PG8_LDB(B0, 1, 0); PG8_LDB(B1, 1, 1); PG8_SCHED; PG8_LDA(At, 1, 0); PG8_STAGE(PG8_SA(0, 1), a2 + hstepA, voffA);
;             PG8_WAIT_V(8); PG8_WAIT_L(0); PG8_BAR; PG8_MMA(0, 0, At, B0); PG8_MMA(0, 1, At, B1); PG8_BAR; PG8_SCHED;
;             PG8_LDA(At, 1, 1); PG8_STAGE(PG8_SB(1, 0), b3, voffB); PG8_STAGE(PG8_SB(1, 1), b3 + hstepB, voffB); PG8_STAGE(PG8_SA(1, 0), a3, voffA);
;             PG8_WAIT_V(8); PG8_WAIT_L(0); PG8_BAR; PG8_MMA(1, 0, At, B0); PG8_MMA(1, 1, At, B1); PG8_BAR; PG8_SCHED;
	v_mfma_f32_16x16x32_bf16 v[62:65], v[140:143], v[186:189], v[62:65]
	v_mfma_f32_16x16x32_bf16 v[58:61], v[162:165], v[186:189], v[58:61]
	v_mfma_f32_16x16x32_bf16 v[46:49], v[140:143], v[194:197], v[46:49]
	v_mfma_f32_16x16x32_bf16 v[42:45], v[162:165], v[194:197], v[42:45]
	v_mfma_f32_16x16x32_bf16 v[30:33], v[140:143], v[202:205], v[30:33]
	v_mfma_f32_16x16x32_bf16 v[26:29], v[162:165], v[202:205], v[26:29]
	v_mfma_f32_16x16x32_bf16 v[14:17], v[140:143], v[210:213], v[14:17]
	v_mfma_f32_16x16x32_bf16 v[10:13], v[162:165], v[210:213], v[10:13]
	v_mfma_f32_16x16x32_bf16 v[62:65], v[144:147], v[190:193], v[62:65]
	v_mfma_f32_16x16x32_bf16 v[58:61], v[166:169], v[190:193], v[58:61]
	v_mfma_f32_16x16x32_bf16 v[46:49], v[144:147], v[198:201], v[46:49]
	v_mfma_f32_16x16x32_bf16 v[42:45], v[166:169], v[198:201], v[42:45]
	v_mfma_f32_16x16x32_bf16 v[30:33], v[144:147], v[206:209], v[30:33]
	v_mfma_f32_16x16x32_bf16 v[26:29], v[166:169], v[206:209], v[26:29]
	v_mfma_f32_16x16x32_bf16 v[14:17], v[144:147], v[214:217], v[14:17]
	v_mfma_f32_16x16x32_bf16 v[10:13], v[166:169], v[214:217], v[10:13]
	s_setprio 0
	s_setprio 1
	v_mfma_f32_16x16x32_bf16 v[54:57], v[170:173], v[186:189], v[54:57]
	v_mfma_f32_16x16x32_bf16 v[50:53], v[178:181], v[186:189], v[50:53]
	v_mfma_f32_16x16x32_bf16 v[38:41], v[170:173], v[194:197], v[38:41]
	v_mfma_f32_16x16x32_bf16 v[34:37], v[178:181], v[194:197], v[34:37]
	v_mfma_f32_16x16x32_bf16 v[22:25], v[170:173], v[202:205], v[22:25]
	v_mfma_f32_16x16x32_bf16 v[18:21], v[178:181], v[202:205], v[18:21]
	v_mfma_f32_16x16x32_bf16 v[6:9], v[170:173], v[210:213], v[6:9]
	v_mfma_f32_16x16x32_bf16 v[2:5], v[178:181], v[210:213], v[2:5]
	v_mfma_f32_16x16x32_bf16 v[54:57], v[174:177], v[190:193], v[54:57]
	v_mfma_f32_16x16x32_bf16 v[50:53], v[182:185], v[190:193], v[50:53]
	v_mfma_f32_16x16x32_bf16 v[38:41], v[174:177], v[198:201], v[38:41]
	v_mfma_f32_16x16x32_bf16 v[34:37], v[182:185], v[198:201], v[34:37]
	v_mfma_f32_16x16x32_bf16 v[22:25], v[174:177], v[206:209], v[22:25]
	v_mfma_f32_16x16x32_bf16 v[18:21], v[182:185], v[206:209], v[18:21]
	v_mfma_f32_16x16x32_bf16 v[6:9], v[174:177], v[214:217], v[6:9]
	v_mfma_f32_16x16x32_bf16 v[2:5], v[182:185], v[214:217], v[2:5]
	s_barrier
	s_setprio 0
	s_add_i32 s31, 0, 0x18000
	v_add_u32_e32 v150, s31, v160
	s_add_i32 s35, 0, 0x1c000
	ds_read_b128 v[140:143], v150
	ds_read_b128 v[144:147], v150 offset:1024
	ds_read_b128 v[162:165], v150 offset:2048
	ds_read_b128 v[166:169], v150 offset:3072
	v_add_u32_e32 v150, s35, v160
	ds_read_b128 v[170:173], v150
	ds_read_b128 v[174:177], v150 offset:1024
	ds_read_b128 v[178:181], v150 offset:2048
	ds_read_b128 v[182:185], v150 offset:3072
	s_add_u32 s28, s40, 0x80000
	s_addc_u32 s29, s41, 0
	s_mov_b32 m0, s56
	v_lshl_add_u64 v[220:221], s[28:29], 0, v[134:135]
	ds_read_b128 v[186:189], v161 offset:32768
	ds_read_b128 v[190:193], v161 offset:33792
	ds_read_b128 v[194:197], v161 offset:34816
	ds_read_b128 v[198:201], v161 offset:35840
	ds_read_b128 v[202:205], v161 offset:36864
	ds_read_b128 v[206:209], v161 offset:37888
	ds_read_b128 v[210:213], v161 offset:38912
	ds_read_b128 v[214:217], v161 offset:39936
	global_load_lds_dwordx4 v[220:221], off
	v_lshl_add_u64 v[220:221], s[28:29], 0, v[132:133]
	s_mov_b32 m0, s57
	s_nop 0
	global_load_lds_dwordx4 v[220:221], off
	s_waitcnt vmcnt(8)
	s_waitcnt lgkmcnt(0)
	s_setprio 1
	s_barrier
	v_mfma_f32_16x16x32_bf16 v[126:129], v[140:143], v[186:189], v[126:129]
	v_mfma_f32_16x16x32_bf16 v[122:125], v[162:165], v[186:189], v[122:125]
	v_mfma_f32_16x16x32_bf16 v[110:113], v[140:143], v[194:197], v[110:113]
	v_mfma_f32_16x16x32_bf16 v[106:109], v[162:165], v[194:197], v[106:109]
	v_mfma_f32_16x16x32_bf16 v[94:97], v[140:143], v[202:205], v[94:97]
	v_mfma_f32_16x16x32_bf16 v[90:93], v[162:165], v[202:205], v[90:93]
	v_mfma_f32_16x16x32_bf16 v[78:81], v[140:143], v[210:213], v[78:81]
	v_mfma_f32_16x16x32_bf16 v[74:77], v[162:165], v[210:213], v[74:77]
	v_mfma_f32_16x16x32_bf16 v[126:129], v[144:147], v[190:193], v[126:129]
	v_mfma_f32_16x16x32_bf16 v[122:125], v[166:169], v[190:193], v[122:125]
	v_mfma_f32_16x16x32_bf16 v[110:113], v[144:147], v[198:201], v[110:113]
	v_mfma_f32_16x16x32_bf16 v[106:109], v[166:169], v[198:201], v[106:109]
	v_mfma_f32_16x16x32_bf16 v[94:97], v[144:147], v[206:209], v[94:97]
	v_mfma_f32_16x16x32_bf16 v[90:93], v[166:169], v[206:209], v[90:93]
	v_mfma_f32_16x16x32_bf16 v[78:81], v[144:147], v[214:217], v[78:81]
	v_mfma_f32_16x16x32_bf16 v[74:77], v[166:169], v[214:217], v[74:77]
	s_setprio 0
	s_setprio 1
	v_mfma_f32_16x16x32_bf16 v[118:121], v[170:173], v[186:189], v[118:121]
	v_mfma_f32_16x16x32_bf16 v[114:117], v[178:181], v[186:189], v[114:117]
	v_mfma_f32_16x16x32_bf16 v[102:105], v[170:173], v[194:197], v[102:105]
	v_mfma_f32_16x16x32_bf16 v[98:101], v[178:181], v[194:197], v[98:101]
	v_mfma_f32_16x16x32_bf16 v[86:89], v[170:173], v[202:205], v[86:89]
	v_mfma_f32_16x16x32_bf16 v[82:85], v[178:181], v[202:205], v[82:85]
	v_mfma_f32_16x16x32_bf16 v[70:73], v[170:173], v[210:213], v[70:73]
	v_mfma_f32_16x16x32_bf16 v[66:69], v[178:181], v[210:213], v[66:69]
	v_mfma_f32_16x16x32_bf16 v[118:121], v[174:177], v[190:193], v[118:121]
	v_mfma_f32_16x16x32_bf16 v[114:117], v[182:185], v[190:193], v[114:117]
	v_mfma_f32_16x16x32_bf16 v[102:105], v[174:177], v[198:201], v[102:105]
	v_mfma_f32_16x16x32_bf16 v[98:101], v[182:185], v[198:201], v[98:101]
	v_mfma_f32_16x16x32_bf16 v[86:89], v[174:177], v[206:209], v[86:89]
	v_mfma_f32_16x16x32_bf16 v[82:85], v[182:185], v[206:209], v[82:85]
	v_mfma_f32_16x16x32_bf16 v[70:73], v[174:177], v[214:217], v[70:73]
	v_mfma_f32_16x16x32_bf16 v[66:69], v[182:185], v[214:217], v[66:69]
	s_barrier
; #define PG8_STAGE(bufoff, gbase, voff) do { _Pragma("unroll") for (int _i = 0; _i < 2; ++_i) \
;         __builtin_amdgcn_global_load_lds((const unsigned*)((const char*)(gbase) + (voff)[_i]), (LAS unsigned*)(lds + (bufoff) + ldsw + _i * 8192), 16, 0, 0); } while (0)
; #define PG8_LDA(dst, b, h) do { _Pragma("unroll") for (int m = 0; m < 4; ++m) _Pragma("unroll") for (int k = 0; k < 2; ++k) dst[m][k] = *(const LAS bf16x8*)(lds + PG8_SA(b, h) + aoff + m * 2048 + k * 1024); } while (0)
; #define PG8_LDB(dst, b, h) do { _Pragma("unroll") for (int n = 0; n < 2; ++n) _Pragma("unroll") for (int k = 0; k < 2; ++k) dst[n][k] = *(const LAS bf16x8*)(lds + PG8_SB(b, h) + boff + n * 2048 + k * 1024); } while (0)
; #define PG8_MMA(ai, bj, At, Bt) do { __builtin_amdgcn_s_setprio(1); _Pragma("unroll") for (int m = 0; m < 4; ++m) _Pragma("unroll") for (int n = 0; n < 2; ++n) _Pragma("unroll") for (int k = 0; k < 2; ++k) \
;         acc[ai][bj][m][n] = __builtin_amdgcn_mfma_f32_16x16x32_bf16(Bt[n][k], At[m][k], acc[ai][bj][m][n], 0, 0, 0); __builtin_amdgcn_s_setprio(0); } while (0)
; #define PG8_WAIT_V(n) asm volatile("s_waitcnt vmcnt(" #n ")" ::: "memory")
; #define PG8_WAIT_L(n) asm volatile("s_waitcnt lgkmcnt(" #n ")" ::: "memory")
; #define PG8_BAR __builtin_amdgcn_s_barrier()
; #define PG8_SCHED __builtin_amdgcn_sched_barrier(0)
; template <class Epi, class Sched, bool ALIGN_EPI, bool LAST_FUSED = false, bool PERM = false, bool CARRY = false>
; __device__ __forceinline__ void gemm_phase(LAS unsigned char* lds, const int tid, const int K, const int lda, const int ldb, const Sched& S, const Epi& E) {
;     ...
;             PG8_LDB(B0, 1, 0); PG8_LDB(B1, 1, 1); PG8_SCHED; PG8_LDA(At, 1, 0); PG8_STAGE(PG8_SA(0, 1), a2 + hstepA, voffA);
;             PG8_WAIT_V(8); PG8_WAIT_L(0); PG8_BAR; PG8_MMA(0, 0, At, B0); PG8_MMA(0, 1, At, B1); PG8_BAR; PG8_SCHED;
;             PG8_LDA(At, 1, 1); PG8_STAGE(PG8_SB(1, 0), b3, voffB); PG8_STAGE(PG8_SB(1, 1), b3 + hstepB, voffB); PG8_STAGE(PG8_SA(1, 0), a3, voffA);
;             PG8_WAIT_V(8); PG8_WAIT_L(0); PG8_BAR; PG8_MMA(1, 0, At, B0); PG8_MMA(1, 1, At, B1); PG8_BAR; PG8_SCHED;
;         }
;         if constexpr (ALIGN_EPI) { if (wr == 0) PG8_BAR; }
	s_setprio 0
	s_add_i32 s28, s31, s52
	v_lshl_add_u64 v[148:149], v[148:149], 0, s[68:69]
	s_mov_b32 m0, s28
	ds_read_b128 v[186:189], v161 offset:49152
	ds_read_b128 v[190:193], v161 offset:50176
	ds_read_b128 v[194:197], v161 offset:51200
	ds_read_b128 v[198:201], v161 offset:52224
	ds_read_b128 v[202:205], v161 offset:53248
	ds_read_b128 v[206:209], v161 offset:54272
	ds_read_b128 v[210:213], v161 offset:55296
	ds_read_b128 v[214:217], v161 offset:56320
	global_load_lds_dwordx4 v[148:149], off
	s_add_i32 m0, s28, 0x2000
	s_add_u32 s28, s36, 0x80080
	v_lshl_add_u64 v[148:149], v[152:153], 0, s[68:69]
	s_addc_u32 s29, s37, 0
	s_add_i32 s31, s35, s52
	global_load_lds_dwordx4 v[148:149], off
	v_lshl_add_u64 v[148:149], s[28:29], 0, v[0:1]
	s_mov_b32 m0, s31
	s_nop 0
	global_load_lds_dwordx4 v[148:149], off
	v_lshl_add_u64 v[148:149], s[28:29], 0, v[130:131]
	s_add_i32 m0, s31, 0x2000
	s_nop 0
	global_load_lds_dwordx4 v[148:149], off
	v_lshl_add_u64 v[148:149], v[156:157], 0, s[68:69]
	s_mov_b32 m0, s59
	s_nop 0
	global_load_lds_dwordx4 v[148:149], off
	v_lshl_add_u64 v[148:149], v[218:219], 0, s[68:69]
	s_mov_b32 m0, s60
	s_nop 0
	global_load_lds_dwordx4 v[148:149], off
	s_waitcnt vmcnt(8)
	s_waitcnt lgkmcnt(0)
	s_setprio 1
	s_barrier
	v_mfma_f32_16x16x32_bf16 v[62:65], v[140:143], v[186:189], v[62:65]
	v_mfma_f32_16x16x32_bf16 v[58:61], v[162:165], v[186:189], v[58:61]
	v_mfma_f32_16x16x32_bf16 v[46:49], v[140:143], v[194:197], v[46:49]
	v_mfma_f32_16x16x32_bf16 v[42:45], v[162:165], v[194:197], v[42:45]
	v_mfma_f32_16x16x32_bf16 v[30:33], v[140:143], v[202:205], v[30:33]
	v_mfma_f32_16x16x32_bf16 v[26:29], v[162:165], v[202:205], v[26:29]
	v_mfma_f32_16x16x32_bf16 v[14:17], v[140:143], v[210:213], v[14:17]
	v_mfma_f32_16x16x32_bf16 v[10:13], v[162:165], v[210:213], v[10:13]
	v_mfma_f32_16x16x32_bf16 v[62:65], v[144:147], v[190:193], v[62:65]
	v_mfma_f32_16x16x32_bf16 v[58:61], v[166:169], v[190:193], v[58:61]
	v_mfma_f32_16x16x32_bf16 v[46:49], v[144:147], v[198:201], v[46:49]
	v_mfma_f32_16x16x32_bf16 v[42:45], v[166:169], v[198:201], v[42:45]
	v_mfma_f32_16x16x32_bf16 v[30:33], v[144:147], v[206:209], v[30:33]
	v_mfma_f32_16x16x32_bf16 v[26:29], v[166:169], v[206:209], v[26:29]
	v_mfma_f32_16x16x32_bf16 v[14:17], v[144:147], v[214:217], v[14:17]
	v_mfma_f32_16x16x32_bf16 v[10:13], v[166:169], v[214:217], v[10:13]
	s_setprio 0
	s_setprio 1
	v_mfma_f32_16x16x32_bf16 v[54:57], v[170:173], v[186:189], v[54:57]
	v_mfma_f32_16x16x32_bf16 v[50:53], v[178:181], v[186:189], v[50:53]
	v_mfma_f32_16x16x32_bf16 v[38:41], v[170:173], v[194:197], v[38:41]
	v_mfma_f32_16x16x32_bf16 v[34:37], v[178:181], v[194:197], v[34:37]
	v_mfma_f32_16x16x32_bf16 v[22:25], v[170:173], v[202:205], v[22:25]
	v_mfma_f32_16x16x32_bf16 v[18:21], v[178:181], v[202:205], v[18:21]
	v_mfma_f32_16x16x32_bf16 v[6:9], v[170:173], v[210:213], v[6:9]
	v_mfma_f32_16x16x32_bf16 v[2:5], v[178:181], v[210:213], v[2:5]
	v_mfma_f32_16x16x32_bf16 v[54:57], v[174:177], v[190:193], v[54:57]
	v_mfma_f32_16x16x32_bf16 v[50:53], v[182:185], v[190:193], v[50:53]
	v_mfma_f32_16x16x32_bf16 v[38:41], v[174:177], v[198:201], v[38:41]
	v_mfma_f32_16x16x32_bf16 v[34:37], v[182:185], v[198:201], v[34:37]
	v_mfma_f32_16x16x32_bf16 v[22:25], v[174:177], v[206:209], v[22:25]
	v_mfma_f32_16x16x32_bf16 v[18:21], v[182:185], v[206:209], v[18:21]
	v_mfma_f32_16x16x32_bf16 v[6:9], v[174:177], v[214:217], v[6:9]
	v_mfma_f32_16x16x32_bf16 v[2:5], v[182:185], v[214:217], v[2:5]
	s_barrier
	s_setprio 0
	s_add_i32 s24, s24, 2
	s_add_u32 s4, s4, 0x100
	s_addc_u32 s5, s5, 0
	s_add_u32 s22, s22, 0x100
	s_addc_u32 s23, s23, 0
	s_cmp_gt_u32 s24, 29
	s_cbranch_scc0 .LBB0_512
	s_and_b64 vcc, exec, s[78:79]
	s_cbranch_vccz .LBB0_515
	s_barrier

; #define PG8_STAGE(bufoff, gbase, voff) do { _Pragma("unroll") for (int _i = 0; _i < 2; ++_i) \
;         __builtin_amdgcn_global_load_lds((const unsigned*)((const char*)(gbase) + (voff)[_i]), (LAS unsigned*)(lds + (bufoff) + ldsw + _i * 8192), 16, 0, 0); } while (0)
; #define PG8_LDA(dst, b, h) do { _Pragma("unroll") for (int m = 0; m < 4; ++m) _Pragma("unroll") for (int k = 0; k < 2; ++k) dst[m][k] = *(const LAS bf16x8*)(lds + PG8_SA(b, h) + aoff + m * 2048 + k * 1024); } while (0)
; #define PG8_BAR __builtin_amdgcn_s_barrier()
; template <class Epi, class Sched, bool ALIGN_EPI, bool LAST_FUSED = false, bool PERM = false, bool CARRY = false>
; __device__ __forceinline__ void gemm_phase(LAS unsigned char* lds, const int tid, const int K, const int lda, const int ldb, const Sched& S, const Epi& E) {
;     ...
;         const bool has_next = S.next(KD_IDX(ui + 1), nxt);
;         const char* nA = has_next ? nxt.a : cA; const char* nB = has_next ? nxt.b : cB; const int nt = cur.nt;
; #pragma unroll 1
;         for (int t = 0; t < nt; t += 2) {
;             const bool last = (t == nt - 2);
;             const char* a1 = cA + (size_t)(t + 1) * kstep;
;             const char* a2 = last ? nA : cA + (size_t)(t + 2) * kstep; const char* b2 = last ? nB : cB + (size_t)(t + 2) * kstep;
;             const char* a3 = a2 + kstep; const char* b3 = b2 + kstep;
;             PG8_LDB(B0, 0, 0); PG8_LDB(B1, 0, 1); PG8_SCHED; PG8_LDA(At, 0, 0); PG8_STAGE(PG8_SA(1, 1), a1 + hstepA, voffA);
;             PG8_WAIT_V(8); PG8_WAIT_L(0); PG8_BAR; PG8_MMA(0, 0, At, B0); PG8_MMA(0, 1, At, B1); PG8_BAR; PG8_SCHED;
;             PG8_LDA(At, 0, 1); PG8_STAGE(PG8_SB(0, 0), b2, voffB); PG8_STAGE(PG8_SB(0, 1), b2 + hstepB, voffB); PG8_STAGE(PG8_SA(0, 0), a2, voffA);
;             PG8_WAIT_V(8); PG8_WAIT_L(0); PG8_BAR; PG8_MMA(1, 0, At, B0); PG8_MMA(1, 1, At, B1); PG8_BAR; PG8_SCHED;
;             PG8_LDB(B0, 1, 0); PG8_LDB(B1, 1, 1); PG8_SCHED; PG8_LDA(At, 1, 0); PG8_STAGE(PG8_SA(0, 1), a2 + hstepA, voffA);
;             PG8_WAIT_V(8); PG8_WAIT_L(0); PG8_BAR; PG8_MMA(0, 0, At, B0); PG8_MMA(0, 1, At, B1); PG8_BAR; PG8_SCHED;
;             PG8_LDA(At, 1, 1); PG8_STAGE(PG8_SB(1, 0), b3, voffB); PG8_STAGE(PG8_SB(1, 1), b3 + hstepB, voffB); PG8_STAGE(PG8_SA(1, 0), a3, voffA);
;             PG8_WAIT_V(8); PG8_WAIT_L(0); PG8_BAR; PG8_MMA(1, 0, At, B0); PG8_MMA(1, 1, At, B1); PG8_BAR; PG8_SCHED;
.LBB0_601:
	s_add_u32 s23, s30, s15
	s_addc_u32 s27, s31, 0
	s_add_u32 s35, s23, 0x100
	s_addc_u32 s42, s27, 0
	s_and_b64 s[28:29], s[40:41], exec
	s_cselect_b32 s47, s17, s42
	s_cselect_b32 s46, s16, s35
	s_add_u32 s15, s36, s15
	s_addc_u32 s28, s37, 0
	s_add_u32 s15, s15, 0x100
	s_addc_u32 s35, s28, 0
	s_add_i32 s75, 0, 0x10000
	s_and_b64 s[28:29], s[40:41], exec
	s_cselect_b32 s49, s19, s35
	s_cselect_b32 s48, s18, s15
	s_add_i32 s41, 0, 0x14000
	s_add_u32 s52, s23, 0x80080
	s_addc_u32 s53, s27, 0
	s_add_i32 s45, s75, s59
	s_add_i32 m0, s60, 0xc000
	s_add_i32 s77, s60, 0xe000
	s_add_i32 s29, s45, 0x2000
	s_add_u32 s50, s48, 0x80000
	v_add_u32_e32 v154, s75, v144
	v_add_u32_e32 v170, s41, v144
	s_addc_u32 s51, s49, 0
	s_add_i32 s44, s41, s59
	ds_read_b128 v[136:139], v154
	ds_read_b128 v[146:149], v154 offset:1024
	ds_read_b128 v[150:153], v154 offset:2048
	ds_read_b128 v[154:157], v154 offset:3072
	ds_read_b128 v[158:161], v170
	ds_read_b128 v[162:165], v170 offset:1024
	ds_read_b128 v[166:169], v170 offset:2048
	ds_read_b128 v[170:173], v170 offset:3072
	s_add_i32 s35, s44, 0x2000
	s_add_i32 s28, 0, 0x18000
	s_add_i32 s27, 0, 0x1c000
	s_add_u32 s42, s46, 0x80000
	s_addc_u32 s43, s47, 0
	s_add_i32 s23, s28, s59
	s_add_i32 s15, s23, 0x2000
	s_add_u32 s40, s48, 0x80080
	s_addc_u32 s41, s49, 0
	s_add_i32 s76, s27, s59
	s_add_i32 s75, s76, 0x2000
	v_lshl_add_u64 v[206:207], s[52:53], 0, v[134:135]
	ds_read_b128 v[174:177], v145
	ds_read_b128 v[178:181], v145 offset:1024
	ds_read_b128 v[182:185], v145 offset:2048
	ds_read_b128 v[186:189], v145 offset:3072
	ds_read_b128 v[190:193], v145 offset:4096
	ds_read_b128 v[194:197], v145 offset:5120
	ds_read_b128 v[198:201], v145 offset:6144
	ds_read_b128 v[202:205], v145 offset:7168
	global_load_lds_dwordx4 v[206:207], off
	v_lshl_add_u64 v[206:207], s[52:53], 0, v[132:133]
	s_mov_b32 m0, s77
	s_nop 0
	global_load_lds_dwordx4 v[206:207], off
	s_waitcnt vmcnt(8)
	s_waitcnt lgkmcnt(0)
	s_setprio 1
	s_barrier
	v_mfma_f32_16x16x32_bf16 v[126:129], v[136:139], v[174:177], v[126:129]
	v_mfma_f32_16x16x32_bf16 v[122:125], v[150:153], v[174:177], v[122:125]
	v_mfma_f32_16x16x32_bf16 v[110:113], v[136:139], v[182:185], v[110:113]
	v_mfma_f32_16x16x32_bf16 v[106:109], v[150:153], v[182:185], v[106:109]
	v_mfma_f32_16x16x32_bf16 v[94:97], v[136:139], v[190:193], v[94:97]
	v_mfma_f32_16x16x32_bf16 v[90:93], v[150:153], v[190:193], v[90:93]
	v_mfma_f32_16x16x32_bf16 v[78:81], v[136:139], v[198:201], v[78:81]
	v_mfma_f32_16x16x32_bf16 v[74:77], v[150:153], v[198:201], v[74:77]
	v_mfma_f32_16x16x32_bf16 v[126:129], v[146:149], v[178:181], v[126:129]
	v_mfma_f32_16x16x32_bf16 v[122:125], v[154:157], v[178:181], v[122:125]
	v_mfma_f32_16x16x32_bf16 v[110:113], v[146:149], v[186:189], v[110:113]
	v_mfma_f32_16x16x32_bf16 v[106:109], v[154:157], v[186:189], v[106:109]
	v_mfma_f32_16x16x32_bf16 v[94:97], v[146:149], v[194:197], v[94:97]
	v_mfma_f32_16x16x32_bf16 v[90:93], v[154:157], v[194:197], v[90:93]
	v_mfma_f32_16x16x32_bf16 v[78:81], v[146:149], v[202:205], v[78:81]
	v_mfma_f32_16x16x32_bf16 v[74:77], v[154:157], v[202:205], v[74:77]
	s_setprio 0
	s_setprio 1
	v_mfma_f32_16x16x32_bf16 v[118:121], v[158:161], v[174:177], v[118:121]
	v_mfma_f32_16x16x32_bf16 v[114:117], v[166:169], v[174:177], v[114:117]
	v_mfma_f32_16x16x32_bf16 v[102:105], v[158:161], v[182:185], v[102:105]
	v_mfma_f32_16x16x32_bf16 v[98:101], v[166:169], v[182:185], v[98:101]
	v_mfma_f32_16x16x32_bf16 v[86:89], v[158:161], v[190:193], v[86:89]
	v_mfma_f32_16x16x32_bf16 v[82:85], v[166:169], v[190:193], v[82:85]
	v_mfma_f32_16x16x32_bf16 v[70:73], v[158:161], v[198:201], v[70:73]
	v_mfma_f32_16x16x32_bf16 v[66:69], v[166:169], v[198:201], v[66:69]
	v_mfma_f32_16x16x32_bf16 v[118:121], v[162:165], v[178:181], v[118:121]
	v_mfma_f32_16x16x32_bf16 v[114:117], v[170:173], v[178:181], v[114:117]
	v_mfma_f32_16x16x32_bf16 v[102:105], v[162:165], v[186:189], v[102:105]
	v_mfma_f32_16x16x32_bf16 v[98:101], v[170:173], v[186:189], v[98:101]
	v_mfma_f32_16x16x32_bf16 v[86:89], v[162:165], v[194:197], v[86:89]
	v_mfma_f32_16x16x32_bf16 v[82:85], v[170:173], v[194:197], v[82:85]
	v_mfma_f32_16x16x32_bf16 v[70:73], v[162:165], v[202:205], v[70:73]
	v_mfma_f32_16x16x32_bf16 v[66:69], v[170:173], v[202:205], v[66:69]
	s_barrier
	s_setprio 0
	s_mov_b32 m0, s45
	v_lshl_add_u64 v[206:207], s[48:49], 0, v[0:1]
	ds_read_b128 v[174:177], v145 offset:16384
	ds_read_b128 v[178:181], v145 offset:17408
	ds_read_b128 v[182:185], v145 offset:18432
	ds_read_b128 v[186:189], v145 offset:19456
	ds_read_b128 v[190:193], v145 offset:20480
	ds_read_b128 v[194:197], v145 offset:21504
	ds_read_b128 v[198:201], v145 offset:22528
	ds_read_b128 v[202:205], v145 offset:23552
	global_load_lds_dwordx4 v[206:207], off
	v_lshl_add_u64 v[208:209], s[48:49], 0, v[130:131]
	s_mov_b32 m0, s29
	v_lshl_add_u64 v[210:211], s[50:51], 0, v[0:1]
	global_load_lds_dwordx4 v[208:209], off
	s_mov_b32 m0, s44
	v_lshl_add_u64 v[212:213], s[46:47], 0, v[132:133]
	global_load_lds_dwordx4 v[210:211], off
	v_lshl_add_u64 v[210:211], s[50:51], 0, v[130:131]
	s_mov_b32 m0, s35
	s_nop 0
	global_load_lds_dwordx4 v[210:211], off
	v_lshl_add_u64 v[210:211], s[46:47], 0, v[134:135]
	s_mov_b32 m0, s60
	s_nop 0
	global_load_lds_dwordx4 v[210:211], off
	s_mov_b32 m0, s61
	s_nop 0
	global_load_lds_dwordx4 v[212:213], off
	s_waitcnt vmcnt(8)
	s_waitcnt lgkmcnt(0)
	s_setprio 1
	s_barrier
; #define PG8_STAGE(bufoff, gbase, voff) do { _Pragma("unroll") for (int _i = 0; _i < 2; ++_i) \
;         __builtin_amdgcn_global_load_lds((const unsigned*)((const char*)(gbase) + (voff)[_i]), (LAS unsigned*)(lds + (bufoff) + ldsw + _i * 8192), 16, 0, 0); } while (0)
; #define PG8_LDA(dst, b, h) do { _Pragma("unroll") for (int m = 0; m < 4; ++m) _Pragma("unroll") for (int k = 0; k < 2; ++k) dst[m][k] = *(const LAS bf16x8*)(lds + PG8_SA(b, h) + aoff + m * 2048 + k * 1024); } while (0)
; #define PG8_LDB(dst, b, h) do { _Pragma("unroll") for (int n = 0; n < 2; ++n) _Pragma("unroll") for (int k = 0; k < 2; ++k) dst[n][k] = *(const LAS bf16x8*)(lds + PG8_SB(b, h) + boff + n * 2048 + k * 1024); } while (0)
; #define PG8_MMA(ai, bj, At, Bt) do { __builtin_amdgcn_s_setprio(1); _Pragma("unroll") for (int m = 0; m < 4; ++m) _Pragma("unroll") for (int n = 0; n < 2; ++n) _Pragma("unroll") for (int k = 0; k < 2; ++k) \
;         acc[ai][bj][m][n] = __builtin_amdgcn_mfma_f32_16x16x32_bf16(Bt[n][k], At[m][k], acc[ai][bj][m][n], 0, 0, 0); __builtin_amdgcn_s_setprio(0); } while (0)
; #define PG8_WAIT_V(n) asm volatile("s_waitcnt vmcnt(" #n ")" ::: "memory")
; #define PG8_WAIT_L(n) asm volatile("s_waitcnt lgkmcnt(" #n ")" ::: "memory")
; #define PG8_BAR __builtin_amdgcn_s_barrier()
; #define PG8_SCHED __builtin_amdgcn_sched_barrier(0)
; template <class Epi, class Sched, bool ALIGN_EPI, bool LAST_FUSED = false, bool PERM = false, bool CARRY = false>
; __device__ __forceinline__ void gemm_phase(LAS unsigned char* lds, const int tid, const int K, const int lda, const int ldb, const Sched& S, const Epi& E) {
;     ...
;             PG8_WAIT_V(8); PG8_WAIT_L(0); PG8_BAR; PG8_MMA(1, 0, At, B0); PG8_MMA(1, 1, At, B1); PG8_BAR; PG8_SCHED;
;             PG8_LDB(B0, 1, 0); PG8_LDB(B1, 1, 1); PG8_SCHED; PG8_LDA(At, 1, 0); PG8_STAGE(PG8_SA(0, 1), a2 + hstepA, voffA);
;             PG8_WAIT_V(8); PG8_WAIT_L(0); PG8_BAR; PG8_MMA(0, 0, At, B0); PG8_MMA(0, 1, At, B1); PG8_BAR; PG8_SCHED;
;             PG8_LDA(At, 1, 1); PG8_STAGE(PG8_SB(1, 0), b3, voffB); PG8_STAGE(PG8_SB(1, 1), b3 + hstepB, voffB); PG8_STAGE(PG8_SA(1, 0), a3, voffA);
;             PG8_WAIT_V(8); PG8_WAIT_L(0); PG8_BAR; PG8_MMA(1, 0, At, B0); PG8_MMA(1, 1, At, B1); PG8_BAR; PG8_SCHED;
	v_mfma_f32_16x16x32_bf16 v[62:65], v[136:139], v[174:177], v[62:65]
	v_mfma_f32_16x16x32_bf16 v[58:61], v[150:153], v[174:177], v[58:61]
	v_mfma_f32_16x16x32_bf16 v[46:49], v[136:139], v[182:185], v[46:49]
	v_mfma_f32_16x16x32_bf16 v[42:45], v[150:153], v[182:185], v[42:45]
	v_mfma_f32_16x16x32_bf16 v[30:33], v[136:139], v[190:193], v[30:33]
	v_mfma_f32_16x16x32_bf16 v[26:29], v[150:153], v[190:193], v[26:29]
	v_mfma_f32_16x16x32_bf16 v[14:17], v[136:139], v[198:201], v[14:17]
	v_mfma_f32_16x16x32_bf16 v[10:13], v[150:153], v[198:201], v[10:13]
	v_mfma_f32_16x16x32_bf16 v[62:65], v[146:149], v[178:181], v[62:65]
	v_mfma_f32_16x16x32_bf16 v[58:61], v[154:157], v[178:181], v[58:61]
	v_mfma_f32_16x16x32_bf16 v[46:49], v[146:149], v[186:189], v[46:49]
	v_mfma_f32_16x16x32_bf16 v[42:45], v[154:157], v[186:189], v[42:45]
	v_mfma_f32_16x16x32_bf16 v[30:33], v[146:149], v[194:197], v[30:33]
	v_mfma_f32_16x16x32_bf16 v[26:29], v[154:157], v[194:197], v[26:29]
	v_mfma_f32_16x16x32_bf16 v[14:17], v[146:149], v[202:205], v[14:17]
	v_mfma_f32_16x16x32_bf16 v[10:13], v[154:157], v[202:205], v[10:13]
	s_setprio 0
	s_setprio 1
	v_mfma_f32_16x16x32_bf16 v[54:57], v[158:161], v[174:177], v[54:57]
	v_mfma_f32_16x16x32_bf16 v[50:53], v[166:169], v[174:177], v[50:53]
	v_mfma_f32_16x16x32_bf16 v[38:41], v[158:161], v[182:185], v[38:41]
	v_mfma_f32_16x16x32_bf16 v[34:37], v[166:169], v[182:185], v[34:37]
	v_mfma_f32_16x16x32_bf16 v[22:25], v[158:161], v[190:193], v[22:25]
	v_mfma_f32_16x16x32_bf16 v[18:21], v[166:169], v[190:193], v[18:21]
	v_mfma_f32_16x16x32_bf16 v[6:9], v[158:161], v[198:201], v[6:9]
	v_mfma_f32_16x16x32_bf16 v[2:5], v[166:169], v[198:201], v[2:5]
	v_mfma_f32_16x16x32_bf16 v[54:57], v[162:165], v[178:181], v[54:57]
	v_mfma_f32_16x16x32_bf16 v[50:53], v[170:173], v[178:181], v[50:53]
	v_mfma_f32_16x16x32_bf16 v[38:41], v[162:165], v[186:189], v[38:41]
	v_mfma_f32_16x16x32_bf16 v[34:37], v[170:173], v[186:189], v[34:37]
	v_mfma_f32_16x16x32_bf16 v[22:25], v[162:165], v[194:197], v[22:25]
	v_mfma_f32_16x16x32_bf16 v[18:21], v[170:173], v[194:197], v[18:21]
	v_mfma_f32_16x16x32_bf16 v[6:9], v[162:165], v[202:205], v[6:9]
	v_mfma_f32_16x16x32_bf16 v[2:5], v[170:173], v[202:205], v[2:5]
	s_barrier
	s_setprio 0
	v_add_u32_e32 v154, s28, v144
	v_add_u32_e32 v170, s27, v144
	ds_read_b128 v[136:139], v154
	ds_read_b128 v[146:149], v154 offset:1024
	ds_read_b128 v[150:153], v154 offset:2048
	ds_read_b128 v[154:157], v154 offset:3072
	ds_read_b128 v[158:161], v170
	ds_read_b128 v[162:165], v170 offset:1024
	ds_read_b128 v[166:169], v170 offset:2048
	ds_read_b128 v[170:173], v170 offset:3072
	s_mov_b32 m0, s62
	v_lshl_add_u64 v[214:215], s[42:43], 0, v[134:135]
	ds_read_b128 v[174:177], v145 offset:32768
	ds_read_b128 v[178:181], v145 offset:33792
	ds_read_b128 v[182:185], v145 offset:34816
	ds_read_b128 v[186:189], v145 offset:35840
	ds_read_b128 v[190:193], v145 offset:36864
	ds_read_b128 v[194:197], v145 offset:37888
	ds_read_b128 v[198:201], v145 offset:38912
	ds_read_b128 v[202:205], v145 offset:39936
	global_load_lds_dwordx4 v[214:215], off
	v_lshl_add_u64 v[214:215], s[42:43], 0, v[132:133]
	s_mov_b32 m0, s63
	s_nop 0
	global_load_lds_dwordx4 v[214:215], off
	s_waitcnt vmcnt(8)
	s_waitcnt lgkmcnt(0)
	s_setprio 1
	s_barrier
	v_mfma_f32_16x16x32_bf16 v[126:129], v[136:139], v[174:177], v[126:129]
	v_mfma_f32_16x16x32_bf16 v[122:125], v[150:153], v[174:177], v[122:125]
	v_mfma_f32_16x16x32_bf16 v[110:113], v[136:139], v[182:185], v[110:113]
	v_mfma_f32_16x16x32_bf16 v[106:109], v[150:153], v[182:185], v[106:109]
	v_mfma_f32_16x16x32_bf16 v[94:97], v[136:139], v[190:193], v[94:97]
	v_mfma_f32_16x16x32_bf16 v[90:93], v[150:153], v[190:193], v[90:93]
	v_mfma_f32_16x16x32_bf16 v[78:81], v[136:139], v[198:201], v[78:81]
	v_mfma_f32_16x16x32_bf16 v[74:77], v[150:153], v[198:201], v[74:77]
	v_mfma_f32_16x16x32_bf16 v[126:129], v[146:149], v[178:181], v[126:129]
	v_mfma_f32_16x16x32_bf16 v[122:125], v[154:157], v[178:181], v[122:125]
	v_mfma_f32_16x16x32_bf16 v[110:113], v[146:149], v[186:189], v[110:113]
	v_mfma_f32_16x16x32_bf16 v[106:109], v[154:157], v[186:189], v[106:109]
	v_mfma_f32_16x16x32_bf16 v[94:97], v[146:149], v[194:197], v[94:97]
	v_mfma_f32_16x16x32_bf16 v[90:93], v[154:157], v[194:197], v[90:93]
	v_mfma_f32_16x16x32_bf16 v[78:81], v[146:149], v[202:205], v[78:81]
	v_mfma_f32_16x16x32_bf16 v[74:77], v[154:157], v[202:205], v[74:77]
	s_setprio 0
	s_setprio 1
	v_mfma_f32_16x16x32_bf16 v[118:121], v[158:161], v[174:177], v[118:121]
	v_mfma_f32_16x16x32_bf16 v[114:117], v[166:169], v[174:177], v[114:117]
	v_mfma_f32_16x16x32_bf16 v[102:105], v[158:161], v[182:185], v[102:105]
	v_mfma_f32_16x16x32_bf16 v[98:101], v[166:169], v[182:185], v[98:101]
	v_mfma_f32_16x16x32_bf16 v[86:89], v[158:161], v[190:193], v[86:89]
	v_mfma_f32_16x16x32_bf16 v[82:85], v[166:169], v[190:193], v[82:85]
	v_mfma_f32_16x16x32_bf16 v[70:73], v[158:161], v[198:201], v[70:73]
	v_mfma_f32_16x16x32_bf16 v[66:69], v[166:169], v[198:201], v[66:69]
	v_mfma_f32_16x16x32_bf16 v[118:121], v[162:165], v[178:181], v[118:121]
	v_mfma_f32_16x16x32_bf16 v[114:117], v[170:173], v[178:181], v[114:117]
	v_mfma_f32_16x16x32_bf16 v[102:105], v[162:165], v[186:189], v[102:105]
	v_mfma_f32_16x16x32_bf16 v[98:101], v[170:173], v[186:189], v[98:101]
	v_mfma_f32_16x16x32_bf16 v[86:89], v[162:165], v[194:197], v[86:89]
	v_mfma_f32_16x16x32_bf16 v[82:85], v[170:173], v[194:197], v[82:85]
	v_mfma_f32_16x16x32_bf16 v[70:73], v[162:165], v[202:205], v[70:73]
	v_mfma_f32_16x16x32_bf16 v[66:69], v[170:173], v[202:205], v[66:69]
	s_barrier
; #define PG8_STAGE(bufoff, gbase, voff) do { _Pragma("unroll") for (int _i = 0; _i < 2; ++_i) \
;         __builtin_amdgcn_global_load_lds((const unsigned*)((const char*)(gbase) + (voff)[_i]), (LAS unsigned*)(lds + (bufoff) + ldsw + _i * 8192), 16, 0, 0); } while (0)
; #define PG8_LDA(dst, b, h) do { _Pragma("unroll") for (int m = 0; m < 4; ++m) _Pragma("unroll") for (int k = 0; k < 2; ++k) dst[m][k] = *(const LAS bf16x8*)(lds + PG8_SA(b, h) + aoff + m * 2048 + k * 1024); } while (0)
; #define PG8_LDB(dst, b, h) do { _Pragma("unroll") for (int n = 0; n < 2; ++n) _Pragma("unroll") for (int k = 0; k < 2; ++k) dst[n][k] = *(const LAS bf16x8*)(lds + PG8_SB(b, h) + boff + n * 2048 + k * 1024); } while (0)
; #define PG8_MMA(ai, bj, At, Bt) do { __builtin_amdgcn_s_setprio(1); _Pragma("unroll") for (int m = 0; m < 4; ++m) _Pragma("unroll") for (int n = 0; n < 2; ++n) _Pragma("unroll") for (int k = 0; k < 2; ++k) \
;         acc[ai][bj][m][n] = __builtin_amdgcn_mfma_f32_16x16x32_bf16(Bt[n][k], At[m][k], acc[ai][bj][m][n], 0, 0, 0); __builtin_amdgcn_s_setprio(0); } while (0)
; #define PG8_WAIT_V(n) asm volatile("s_waitcnt vmcnt(" #n ")" ::: "memory")
; #define PG8_WAIT_L(n) asm volatile("s_waitcnt lgkmcnt(" #n ")" ::: "memory")
; #define PG8_BAR __builtin_amdgcn_s_barrier()
; #define PG8_SCHED __builtin_amdgcn_sched_barrier(0)
; template <class Epi, class Sched, bool ALIGN_EPI, bool LAST_FUSED = false, bool PERM = false, bool CARRY = false>
; __device__ __forceinline__ void gemm_phase(LAS unsigned char* lds, const int tid, const int K, const int lda, const int ldb, const Sched& S, const Epi& E) {
;     ...
;             PG8_LDB(B0, 1, 0); PG8_LDB(B1, 1, 1); PG8_SCHED; PG8_LDA(At, 1, 0); PG8_STAGE(PG8_SA(0, 1), a2 + hstepA, voffA);
;             PG8_WAIT_V(8); PG8_WAIT_L(0); PG8_BAR; PG8_MMA(0, 0, At, B0); PG8_MMA(0, 1, At, B1); PG8_BAR; PG8_SCHED;
;             PG8_LDA(At, 1, 1); PG8_STAGE(PG8_SB(1, 0), b3, voffB); PG8_STAGE(PG8_SB(1, 1), b3 + hstepB, voffB); PG8_STAGE(PG8_SA(1, 0), a3, voffA);
;             PG8_WAIT_V(8); PG8_WAIT_L(0); PG8_BAR; PG8_MMA(1, 0, At, B0); PG8_MMA(1, 1, At, B1); PG8_BAR; PG8_SCHED;
;         }
;         if constexpr (ALIGN_EPI) { if (wr == 0) PG8_BAR; }
	s_setprio 0
	s_mov_b32 m0, s23
	v_lshl_add_u64 v[206:207], v[206:207], 0, s[68:69]
	ds_read_b128 v[174:177], v145 offset:49152
	ds_read_b128 v[178:181], v145 offset:50176
	ds_read_b128 v[182:185], v145 offset:51200
	ds_read_b128 v[186:189], v145 offset:52224
	ds_read_b128 v[190:193], v145 offset:53248
	ds_read_b128 v[194:197], v145 offset:54272
	ds_read_b128 v[198:201], v145 offset:55296
	ds_read_b128 v[202:205], v145 offset:56320
	global_load_lds_dwordx4 v[206:207], off
	v_lshl_add_u64 v[206:207], v[208:209], 0, s[68:69]
	s_mov_b32 m0, s15
	s_nop 0
	global_load_lds_dwordx4 v[206:207], off
	v_lshl_add_u64 v[206:207], s[40:41], 0, v[0:1]
	s_mov_b32 m0, s76
	s_nop 0
	global_load_lds_dwordx4 v[206:207], off
	v_lshl_add_u64 v[206:207], s[40:41], 0, v[130:131]
	s_mov_b32 m0, s75
	s_nop 0
	global_load_lds_dwordx4 v[206:207], off
	v_lshl_add_u64 v[206:207], v[210:211], 0, s[68:69]
	s_mov_b32 m0, s66
	s_nop 0
	global_load_lds_dwordx4 v[206:207], off
	v_lshl_add_u64 v[206:207], v[212:213], 0, s[68:69]
	s_mov_b32 m0, s67
	s_nop 0
	global_load_lds_dwordx4 v[206:207], off
	s_waitcnt vmcnt(8)
	s_waitcnt lgkmcnt(0)
	s_setprio 1
	s_barrier
	v_mfma_f32_16x16x32_bf16 v[62:65], v[136:139], v[174:177], v[62:65]
	v_mfma_f32_16x16x32_bf16 v[58:61], v[150:153], v[174:177], v[58:61]
	v_mfma_f32_16x16x32_bf16 v[46:49], v[136:139], v[182:185], v[46:49]
	v_mfma_f32_16x16x32_bf16 v[42:45], v[150:153], v[182:185], v[42:45]
	v_mfma_f32_16x16x32_bf16 v[30:33], v[136:139], v[190:193], v[30:33]
	v_mfma_f32_16x16x32_bf16 v[26:29], v[150:153], v[190:193], v[26:29]
	v_mfma_f32_16x16x32_bf16 v[14:17], v[136:139], v[198:201], v[14:17]
	v_mfma_f32_16x16x32_bf16 v[10:13], v[150:153], v[198:201], v[10:13]
	v_mfma_f32_16x16x32_bf16 v[62:65], v[146:149], v[178:181], v[62:65]
	v_mfma_f32_16x16x32_bf16 v[58:61], v[154:157], v[178:181], v[58:61]
	v_mfma_f32_16x16x32_bf16 v[46:49], v[146:149], v[186:189], v[46:49]
	v_mfma_f32_16x16x32_bf16 v[42:45], v[154:157], v[186:189], v[42:45]
	v_mfma_f32_16x16x32_bf16 v[30:33], v[146:149], v[194:197], v[30:33]
	v_mfma_f32_16x16x32_bf16 v[26:29], v[154:157], v[194:197], v[26:29]
	v_mfma_f32_16x16x32_bf16 v[14:17], v[146:149], v[202:205], v[14:17]
	v_mfma_f32_16x16x32_bf16 v[10:13], v[154:157], v[202:205], v[10:13]
	s_setprio 0
	s_setprio 1
	v_mfma_f32_16x16x32_bf16 v[54:57], v[158:161], v[174:177], v[54:57]
	v_mfma_f32_16x16x32_bf16 v[50:53], v[166:169], v[174:177], v[50:53]
	v_mfma_f32_16x16x32_bf16 v[38:41], v[158:161], v[182:185], v[38:41]
	v_mfma_f32_16x16x32_bf16 v[34:37], v[166:169], v[182:185], v[34:37]
	v_mfma_f32_16x16x32_bf16 v[22:25], v[158:161], v[190:193], v[22:25]
	v_mfma_f32_16x16x32_bf16 v[18:21], v[166:169], v[190:193], v[18:21]
	v_mfma_f32_16x16x32_bf16 v[6:9], v[158:161], v[198:201], v[6:9]
	v_mfma_f32_16x16x32_bf16 v[2:5], v[166:169], v[198:201], v[2:5]
	v_mfma_f32_16x16x32_bf16 v[54:57], v[162:165], v[178:181], v[54:57]
	v_mfma_f32_16x16x32_bf16 v[50:53], v[170:173], v[178:181], v[50:53]
	v_mfma_f32_16x16x32_bf16 v[38:41], v[162:165], v[186:189], v[38:41]
	v_mfma_f32_16x16x32_bf16 v[34:37], v[170:173], v[186:189], v[34:37]
	v_mfma_f32_16x16x32_bf16 v[22:25], v[162:165], v[194:197], v[22:25]
	v_mfma_f32_16x16x32_bf16 v[18:21], v[170:173], v[194:197], v[18:21]
	v_mfma_f32_16x16x32_bf16 v[6:9], v[162:165], v[202:205], v[6:9]
	v_mfma_f32_16x16x32_bf16 v[2:5], v[170:173], v[202:205], v[2:5]
	s_barrier
	s_setprio 0
	s_movk_i32 s15, 0x100
	s_andn2_b64 vcc, exec, s[38:39]
	s_mov_b64 s[40:41], -1
	s_mov_b64 s[38:39], 0
	s_cbranch_vccz .LBB0_601
	s_and_b64 vcc, exec, s[12:13]
	s_cbranch_vccz .LBB0_604
	s_barrier

; #define PG8_STAGE(bufoff, gbase, voff) do { _Pragma("unroll") for (int _i = 0; _i < 2; ++_i) \
;         __builtin_amdgcn_global_load_lds((const unsigned*)((const char*)(gbase) + (voff)[_i]), (LAS unsigned*)(lds + (bufoff) + ldsw + _i * 8192), 16, 0, 0); } while (0)
; #define PG8_LDA(dst, b, h) do { _Pragma("unroll") for (int m = 0; m < 4; ++m) _Pragma("unroll") for (int k = 0; k < 2; ++k) dst[m][k] = *(const LAS bf16x8*)(lds + PG8_SA(b, h) + aoff + m * 2048 + k * 1024); } while (0)
; #define PG8_BAR __builtin_amdgcn_s_barrier()
; template <class Epi, class Sched, bool ALIGN_EPI, bool LAST_FUSED = false, bool PERM = false, bool CARRY = false>
; __device__ __forceinline__ void gemm_phase(LAS unsigned char* lds, const int tid, const int K, const int lda, const int ldb, const Sched& S, const Epi& E) {
;     ...
;         const bool has_next = S.next(KD_IDX(ui + 1), nxt);
;         const char* nA = has_next ? nxt.a : cA; const char* nB = has_next ? nxt.b : cB; const int nt = cur.nt;
; #pragma unroll 1
;         for (int t = 0; t < nt; t += 2) {
;             const bool last = (t == nt - 2);
;             const char* a1 = cA + (size_t)(t + 1) * kstep;
;             const char* a2 = last ? nA : cA + (size_t)(t + 2) * kstep; const char* b2 = last ? nB : cB + (size_t)(t + 2) * kstep;
;             const char* a3 = a2 + kstep; const char* b3 = b2 + kstep;
;             PG8_LDB(B0, 0, 0); PG8_LDB(B1, 0, 1); PG8_SCHED; PG8_LDA(At, 0, 0); PG8_STAGE(PG8_SA(1, 1), a1 + hstepA, voffA);
;             PG8_WAIT_V(8); PG8_WAIT_L(0); PG8_BAR; PG8_MMA(0, 0, At, B0); PG8_MMA(0, 1, At, B1); PG8_BAR; PG8_SCHED;
;             PG8_LDA(At, 0, 1); PG8_STAGE(PG8_SB(0, 0), b2, voffB); PG8_STAGE(PG8_SB(0, 1), b2 + hstepB, voffB); PG8_STAGE(PG8_SA(0, 0), a2, voffA);
;             PG8_WAIT_V(8); PG8_WAIT_L(0); PG8_BAR; PG8_MMA(1, 0, At, B0); PG8_MMA(1, 1, At, B1); PG8_BAR; PG8_SCHED;
;             PG8_LDB(B0, 1, 0); PG8_LDB(B1, 1, 1); PG8_SCHED; PG8_LDA(At, 1, 0); PG8_STAGE(PG8_SA(0, 1), a2 + hstepA, voffA);
;             PG8_WAIT_V(8); PG8_WAIT_L(0); PG8_BAR; PG8_MMA(0, 0, At, B0); PG8_MMA(0, 1, At, B1); PG8_BAR; PG8_SCHED;
;             PG8_LDA(At, 1, 1); PG8_STAGE(PG8_SB(1, 0), b3, voffB); PG8_STAGE(PG8_SB(1, 1), b3 + hstepB, voffB); PG8_STAGE(PG8_SA(1, 0), a3, voffA);
;             PG8_WAIT_V(8); PG8_WAIT_L(0); PG8_BAR; PG8_MMA(1, 0, At, B0); PG8_MMA(1, 1, At, B1); PG8_BAR; PG8_SCHED;
.LBB0_622:
	s_add_u32 s48, s30, s24
	s_addc_u32 s49, s31, 0
	s_add_u32 s42, s48, 0x100
	s_addc_u32 s43, s49, 0
	s_and_b64 s[40:41], s[38:39], exec
	s_cselect_b32 s43, s15, s43
	s_cselect_b32 s42, s14, s42
	s_add_u32 s24, s26, s24
	s_addc_u32 s40, s27, 0
	s_add_u32 s24, s24, 0x100
	s_addc_u32 s40, s40, 0
	s_add_i32 s62, 0, 0x10000
	s_and_b64 s[38:39], s[38:39], exec
	s_cselect_b32 s47, s17, s40
	s_cselect_b32 s46, s16, s24
	s_add_i32 s39, 0, 0x14000
	s_add_u32 s64, s48, 0x30080
	s_addc_u32 s65, s49, 0
	s_add_i32 s67, s62, s29
	s_add_i32 m0, s45, 0xc000
	s_add_i32 s66, s45, 0xe000
	s_add_i32 s70, s67, 0x2000
	s_add_u32 s48, s46, 0x10000
	v_add_u32_e32 v152, s62, v140
	v_add_u32_e32 v168, s39, v140
	s_addc_u32 s49, s47, 0
	s_add_i32 s71, s39, s29
	ds_read_b128 v[136:139], v152
	ds_read_b128 v[144:147], v152 offset:1024
	ds_read_b128 v[148:151], v152 offset:2048
	ds_read_b128 v[152:155], v152 offset:3072
	ds_read_b128 v[156:159], v168
	ds_read_b128 v[160:163], v168 offset:1024
	ds_read_b128 v[164:167], v168 offset:2048
	ds_read_b128 v[168:171], v168 offset:3072
	s_add_i32 s74, s71, 0x2000
	s_add_i32 s75, 0, 0x18000
	s_add_i32 s76, 0, 0x1c000
	s_add_u32 s40, s42, 0x30000
	s_addc_u32 s41, s43, 0
	s_add_i32 s61, s75, s29
	s_add_i32 s24, s61, 0x2000
	s_add_u32 s38, s46, 0x10080
	s_addc_u32 s39, s47, 0
	s_add_i32 s63, s76, s29
	s_add_i32 s62, s63, 0x2000
	v_lshl_add_u64 v[204:205], s[64:65], 0, v[130:131]
	ds_read_b128 v[172:175], v143
	ds_read_b128 v[176:179], v143 offset:1024
	ds_read_b128 v[180:183], v143 offset:2048
	ds_read_b128 v[184:187], v143 offset:3072
	ds_read_b128 v[188:191], v143 offset:4096
	ds_read_b128 v[192:195], v143 offset:5120
	ds_read_b128 v[196:199], v143 offset:6144
	ds_read_b128 v[200:203], v143 offset:7168
	global_load_lds_dwordx4 v[204:205], off
	v_lshl_add_u64 v[204:205], s[64:65], 0, v[132:133]
	s_mov_b32 m0, s66
	s_nop 0
	global_load_lds_dwordx4 v[204:205], off
	s_waitcnt vmcnt(8)
	s_waitcnt lgkmcnt(0)
	s_setprio 1
	s_barrier
	v_mfma_f32_16x16x32_bf16 v[126:129], v[136:139], v[172:175], v[126:129]
	v_mfma_f32_16x16x32_bf16 v[122:125], v[148:151], v[172:175], v[122:125]
	v_mfma_f32_16x16x32_bf16 v[118:121], v[136:139], v[180:183], v[118:121]
	v_mfma_f32_16x16x32_bf16 v[114:117], v[148:151], v[180:183], v[114:117]
	v_mfma_f32_16x16x32_bf16 v[110:113], v[136:139], v[188:191], v[110:113]
	v_mfma_f32_16x16x32_bf16 v[106:109], v[148:151], v[188:191], v[106:109]
	v_mfma_f32_16x16x32_bf16 v[102:105], v[136:139], v[196:199], v[102:105]
	v_mfma_f32_16x16x32_bf16 v[98:101], v[148:151], v[196:199], v[98:101]
	v_mfma_f32_16x16x32_bf16 v[126:129], v[144:147], v[176:179], v[126:129]
	v_mfma_f32_16x16x32_bf16 v[122:125], v[152:155], v[176:179], v[122:125]
	v_mfma_f32_16x16x32_bf16 v[118:121], v[144:147], v[184:187], v[118:121]
	v_mfma_f32_16x16x32_bf16 v[114:117], v[152:155], v[184:187], v[114:117]
	v_mfma_f32_16x16x32_bf16 v[110:113], v[144:147], v[192:195], v[110:113]
	v_mfma_f32_16x16x32_bf16 v[106:109], v[152:155], v[192:195], v[106:109]
	v_mfma_f32_16x16x32_bf16 v[102:105], v[144:147], v[200:203], v[102:105]
	v_mfma_f32_16x16x32_bf16 v[98:101], v[152:155], v[200:203], v[98:101]
	s_setprio 0
	s_setprio 1
	v_mfma_f32_16x16x32_bf16 v[94:97], v[156:159], v[172:175], v[94:97]
	v_mfma_f32_16x16x32_bf16 v[90:93], v[164:167], v[172:175], v[90:93]
	v_mfma_f32_16x16x32_bf16 v[86:89], v[156:159], v[180:183], v[86:89]
	v_mfma_f32_16x16x32_bf16 v[82:85], v[164:167], v[180:183], v[82:85]
	v_mfma_f32_16x16x32_bf16 v[78:81], v[156:159], v[188:191], v[78:81]
	v_mfma_f32_16x16x32_bf16 v[74:77], v[164:167], v[188:191], v[74:77]
	v_mfma_f32_16x16x32_bf16 v[70:73], v[156:159], v[196:199], v[70:73]
	v_mfma_f32_16x16x32_bf16 v[66:69], v[164:167], v[196:199], v[66:69]
	v_mfma_f32_16x16x32_bf16 v[94:97], v[160:163], v[176:179], v[94:97]
	v_mfma_f32_16x16x32_bf16 v[90:93], v[168:171], v[176:179], v[90:93]
	v_mfma_f32_16x16x32_bf16 v[86:89], v[160:163], v[184:187], v[86:89]
	v_mfma_f32_16x16x32_bf16 v[82:85], v[168:171], v[184:187], v[82:85]
	v_mfma_f32_16x16x32_bf16 v[78:81], v[160:163], v[192:195], v[78:81]
	v_mfma_f32_16x16x32_bf16 v[74:77], v[168:171], v[192:195], v[74:77]
	v_mfma_f32_16x16x32_bf16 v[70:73], v[160:163], v[200:203], v[70:73]
	v_mfma_f32_16x16x32_bf16 v[66:69], v[168:171], v[200:203], v[66:69]
	s_barrier
	s_setprio 0
	s_mov_b32 m0, s67
	v_lshl_add_u64 v[204:205], s[46:47], 0, v[0:1]
	ds_read_b128 v[172:175], v143 offset:16384
	ds_read_b128 v[176:179], v143 offset:17408
	ds_read_b128 v[180:183], v143 offset:18432
	ds_read_b128 v[184:187], v143 offset:19456
	ds_read_b128 v[188:191], v143 offset:20480
	ds_read_b128 v[192:195], v143 offset:21504
	ds_read_b128 v[196:199], v143 offset:22528
	ds_read_b128 v[200:203], v143 offset:23552
	global_load_lds_dwordx4 v[204:205], off
	v_lshl_add_u64 v[206:207], s[46:47], 0, v[134:135]
	s_mov_b32 m0, s70
	v_lshl_add_u64 v[208:209], s[48:49], 0, v[0:1]
	global_load_lds_dwordx4 v[206:207], off
	s_mov_b32 m0, s71
	v_lshl_add_u64 v[210:211], s[42:43], 0, v[132:133]
	global_load_lds_dwordx4 v[208:209], off
	v_lshl_add_u64 v[208:209], s[48:49], 0, v[134:135]
	s_mov_b32 m0, s74
	s_nop 0
	global_load_lds_dwordx4 v[208:209], off
	v_lshl_add_u64 v[208:209], s[42:43], 0, v[130:131]
	s_mov_b32 m0, s45
	s_nop 0
	global_load_lds_dwordx4 v[208:209], off
	s_mov_b32 m0, s50
	s_nop 0
	global_load_lds_dwordx4 v[210:211], off
	s_waitcnt vmcnt(8)
	s_waitcnt lgkmcnt(0)
	s_setprio 1
	s_barrier
; #define PG8_STAGE(bufoff, gbase, voff) do { _Pragma("unroll") for (int _i = 0; _i < 2; ++_i) \
;         __builtin_amdgcn_global_load_lds((const unsigned*)((const char*)(gbase) + (voff)[_i]), (LAS unsigned*)(lds + (bufoff) + ldsw + _i * 8192), 16, 0, 0); } while (0)
; #define PG8_LDA(dst, b, h) do { _Pragma("unroll") for (int m = 0; m < 4; ++m) _Pragma("unroll") for (int k = 0; k < 2; ++k) dst[m][k] = *(const LAS bf16x8*)(lds + PG8_SA(b, h) + aoff + m * 2048 + k * 1024); } while (0)
; #define PG8_LDB(dst, b, h) do { _Pragma("unroll") for (int n = 0; n < 2; ++n) _Pragma("unroll") for (int k = 0; k < 2; ++k) dst[n][k] = *(const LAS bf16x8*)(lds + PG8_SB(b, h) + boff + n * 2048 + k * 1024); } while (0)
; #define PG8_MMA(ai, bj, At, Bt) do { __builtin_amdgcn_s_setprio(1); _Pragma("unroll") for (int m = 0; m < 4; ++m) _Pragma("unroll") for (int n = 0; n < 2; ++n) _Pragma("unroll") for (int k = 0; k < 2; ++k) \
;         acc[ai][bj][m][n] = __builtin_amdgcn_mfma_f32_16x16x32_bf16(Bt[n][k], At[m][k], acc[ai][bj][m][n], 0, 0, 0); __builtin_amdgcn_s_setprio(0); } while (0)
; #define PG8_WAIT_V(n) asm volatile("s_waitcnt vmcnt(" #n ")" ::: "memory")
; #define PG8_WAIT_L(n) asm volatile("s_waitcnt lgkmcnt(" #n ")" ::: "memory")
; #define PG8_BAR __builtin_amdgcn_s_barrier()
; #define PG8_SCHED __builtin_amdgcn_sched_barrier(0)
; template <class Epi, class Sched, bool ALIGN_EPI, bool LAST_FUSED = false, bool PERM = false, bool CARRY = false>
; __device__ __forceinline__ void gemm_phase(LAS unsigned char* lds, const int tid, const int K, const int lda, const int ldb, const Sched& S, const Epi& E) {
;     ...
;             PG8_WAIT_V(8); PG8_WAIT_L(0); PG8_BAR; PG8_MMA(1, 0, At, B0); PG8_MMA(1, 1, At, B1); PG8_BAR; PG8_SCHED;
;             PG8_LDB(B0, 1, 0); PG8_LDB(B1, 1, 1); PG8_SCHED; PG8_LDA(At, 1, 0); PG8_STAGE(PG8_SA(0, 1), a2 + hstepA, voffA);
;             PG8_WAIT_V(8); PG8_WAIT_L(0); PG8_BAR; PG8_MMA(0, 0, At, B0); PG8_MMA(0, 1, At, B1); PG8_BAR; PG8_SCHED;
;             PG8_LDA(At, 1, 1); PG8_STAGE(PG8_SB(1, 0), b3, voffB); PG8_STAGE(PG8_SB(1, 1), b3 + hstepB, voffB); PG8_STAGE(PG8_SA(1, 0), a3, voffA);
;             PG8_WAIT_V(8); PG8_WAIT_L(0); PG8_BAR; PG8_MMA(1, 0, At, B0); PG8_MMA(1, 1, At, B1); PG8_BAR; PG8_SCHED;
	v_mfma_f32_16x16x32_bf16 v[62:65], v[136:139], v[172:175], v[62:65]
	v_mfma_f32_16x16x32_bf16 v[58:61], v[148:151], v[172:175], v[58:61]
	v_mfma_f32_16x16x32_bf16 v[54:57], v[136:139], v[180:183], v[54:57]
	v_mfma_f32_16x16x32_bf16 v[50:53], v[148:151], v[180:183], v[50:53]
	v_mfma_f32_16x16x32_bf16 v[46:49], v[136:139], v[188:191], v[46:49]
	v_mfma_f32_16x16x32_bf16 v[42:45], v[148:151], v[188:191], v[42:45]
	v_mfma_f32_16x16x32_bf16 v[38:41], v[136:139], v[196:199], v[38:41]
	v_mfma_f32_16x16x32_bf16 v[34:37], v[148:151], v[196:199], v[34:37]
	v_mfma_f32_16x16x32_bf16 v[62:65], v[144:147], v[176:179], v[62:65]
	v_mfma_f32_16x16x32_bf16 v[58:61], v[152:155], v[176:179], v[58:61]
	v_mfma_f32_16x16x32_bf16 v[54:57], v[144:147], v[184:187], v[54:57]
	v_mfma_f32_16x16x32_bf16 v[50:53], v[152:155], v[184:187], v[50:53]
	v_mfma_f32_16x16x32_bf16 v[46:49], v[144:147], v[192:195], v[46:49]
	v_mfma_f32_16x16x32_bf16 v[42:45], v[152:155], v[192:195], v[42:45]
	v_mfma_f32_16x16x32_bf16 v[38:41], v[144:147], v[200:203], v[38:41]
	v_mfma_f32_16x16x32_bf16 v[34:37], v[152:155], v[200:203], v[34:37]
	s_setprio 0
	s_setprio 1
	v_mfma_f32_16x16x32_bf16 v[30:33], v[156:159], v[172:175], v[30:33]
	v_mfma_f32_16x16x32_bf16 v[26:29], v[164:167], v[172:175], v[26:29]
	v_mfma_f32_16x16x32_bf16 v[22:25], v[156:159], v[180:183], v[22:25]
	v_mfma_f32_16x16x32_bf16 v[18:21], v[164:167], v[180:183], v[18:21]
	v_mfma_f32_16x16x32_bf16 v[14:17], v[156:159], v[188:191], v[14:17]
	v_mfma_f32_16x16x32_bf16 v[10:13], v[164:167], v[188:191], v[10:13]
	v_mfma_f32_16x16x32_bf16 v[6:9], v[156:159], v[196:199], v[6:9]
	v_mfma_f32_16x16x32_bf16 v[2:5], v[164:167], v[196:199], v[2:5]
	v_mfma_f32_16x16x32_bf16 v[30:33], v[160:163], v[176:179], v[30:33]
	v_mfma_f32_16x16x32_bf16 v[26:29], v[168:171], v[176:179], v[26:29]
	v_mfma_f32_16x16x32_bf16 v[22:25], v[160:163], v[184:187], v[22:25]
	v_mfma_f32_16x16x32_bf16 v[18:21], v[168:171], v[184:187], v[18:21]
	v_mfma_f32_16x16x32_bf16 v[14:17], v[160:163], v[192:195], v[14:17]
	v_mfma_f32_16x16x32_bf16 v[10:13], v[168:171], v[192:195], v[10:13]
	v_mfma_f32_16x16x32_bf16 v[6:9], v[160:163], v[200:203], v[6:9]
	v_mfma_f32_16x16x32_bf16 v[2:5], v[168:171], v[200:203], v[2:5]
	s_barrier
	s_setprio 0
	v_add_u32_e32 v152, s75, v140
	v_add_u32_e32 v168, s76, v140
	ds_read_b128 v[136:139], v152
	ds_read_b128 v[144:147], v152 offset:1024
	ds_read_b128 v[148:151], v152 offset:2048
	ds_read_b128 v[152:155], v152 offset:3072
	ds_read_b128 v[156:159], v168
	ds_read_b128 v[160:163], v168 offset:1024
	ds_read_b128 v[164:167], v168 offset:2048
	ds_read_b128 v[168:171], v168 offset:3072
	s_mov_b32 m0, s51
	v_lshl_add_u64 v[212:213], s[40:41], 0, v[130:131]
	ds_read_b128 v[172:175], v143 offset:32768
	ds_read_b128 v[176:179], v143 offset:33792
	ds_read_b128 v[180:183], v143 offset:34816
	ds_read_b128 v[184:187], v143 offset:35840
	ds_read_b128 v[188:191], v143 offset:36864
	ds_read_b128 v[192:195], v143 offset:37888
	ds_read_b128 v[196:199], v143 offset:38912
	ds_read_b128 v[200:203], v143 offset:39936
	global_load_lds_dwordx4 v[212:213], off
	v_lshl_add_u64 v[212:213], s[40:41], 0, v[132:133]
	s_mov_b32 m0, s52
	s_nop 0
	global_load_lds_dwordx4 v[212:213], off
	s_waitcnt vmcnt(8)
	s_waitcnt lgkmcnt(0)
	s_setprio 1
	s_barrier
	v_mfma_f32_16x16x32_bf16 v[126:129], v[136:139], v[172:175], v[126:129]
	v_mfma_f32_16x16x32_bf16 v[122:125], v[148:151], v[172:175], v[122:125]
	v_mfma_f32_16x16x32_bf16 v[118:121], v[136:139], v[180:183], v[118:121]
	v_mfma_f32_16x16x32_bf16 v[114:117], v[148:151], v[180:183], v[114:117]
	v_mfma_f32_16x16x32_bf16 v[110:113], v[136:139], v[188:191], v[110:113]
	v_mfma_f32_16x16x32_bf16 v[106:109], v[148:151], v[188:191], v[106:109]
	v_mfma_f32_16x16x32_bf16 v[102:105], v[136:139], v[196:199], v[102:105]
	v_mfma_f32_16x16x32_bf16 v[98:101], v[148:151], v[196:199], v[98:101]
	v_mfma_f32_16x16x32_bf16 v[126:129], v[144:147], v[176:179], v[126:129]
	v_mfma_f32_16x16x32_bf16 v[122:125], v[152:155], v[176:179], v[122:125]
	v_mfma_f32_16x16x32_bf16 v[118:121], v[144:147], v[184:187], v[118:121]
	v_mfma_f32_16x16x32_bf16 v[114:117], v[152:155], v[184:187], v[114:117]
	v_mfma_f32_16x16x32_bf16 v[110:113], v[144:147], v[192:195], v[110:113]
	v_mfma_f32_16x16x32_bf16 v[106:109], v[152:155], v[192:195], v[106:109]
	v_mfma_f32_16x16x32_bf16 v[102:105], v[144:147], v[200:203], v[102:105]
	v_mfma_f32_16x16x32_bf16 v[98:101], v[152:155], v[200:203], v[98:101]
	s_setprio 0
	s_setprio 1
	v_mfma_f32_16x16x32_bf16 v[94:97], v[156:159], v[172:175], v[94:97]
	v_mfma_f32_16x16x32_bf16 v[90:93], v[164:167], v[172:175], v[90:93]
	v_mfma_f32_16x16x32_bf16 v[86:89], v[156:159], v[180:183], v[86:89]
	v_mfma_f32_16x16x32_bf16 v[82:85], v[164:167], v[180:183], v[82:85]
	v_mfma_f32_16x16x32_bf16 v[78:81], v[156:159], v[188:191], v[78:81]
	v_mfma_f32_16x16x32_bf16 v[74:77], v[164:167], v[188:191], v[74:77]
	v_mfma_f32_16x16x32_bf16 v[70:73], v[156:159], v[196:199], v[70:73]
	v_mfma_f32_16x16x32_bf16 v[66:69], v[164:167], v[196:199], v[66:69]
	v_mfma_f32_16x16x32_bf16 v[94:97], v[160:163], v[176:179], v[94:97]
	v_mfma_f32_16x16x32_bf16 v[90:93], v[168:171], v[176:179], v[90:93]
	v_mfma_f32_16x16x32_bf16 v[86:89], v[160:163], v[184:187], v[86:89]
	v_mfma_f32_16x16x32_bf16 v[82:85], v[168:171], v[184:187], v[82:85]
	v_mfma_f32_16x16x32_bf16 v[78:81], v[160:163], v[192:195], v[78:81]
	v_mfma_f32_16x16x32_bf16 v[74:77], v[168:171], v[192:195], v[74:77]
	v_mfma_f32_16x16x32_bf16 v[70:73], v[160:163], v[200:203], v[70:73]
	v_mfma_f32_16x16x32_bf16 v[66:69], v[168:171], v[200:203], v[66:69]
	s_barrier
; #define PG8_STAGE(bufoff, gbase, voff) do { _Pragma("unroll") for (int _i = 0; _i < 2; ++_i) \
;         __builtin_amdgcn_global_load_lds((const unsigned*)((const char*)(gbase) + (voff)[_i]), (LAS unsigned*)(lds + (bufoff) + ldsw + _i * 8192), 16, 0, 0); } while (0)
; #define PG8_LDA(dst, b, h) do { _Pragma("unroll") for (int m = 0; m < 4; ++m) _Pragma("unroll") for (int k = 0; k < 2; ++k) dst[m][k] = *(const LAS bf16x8*)(lds + PG8_SA(b, h) + aoff + m * 2048 + k * 1024); } while (0)
; #define PG8_LDB(dst, b, h) do { _Pragma("unroll") for (int n = 0; n < 2; ++n) _Pragma("unroll") for (int k = 0; k < 2; ++k) dst[n][k] = *(const LAS bf16x8*)(lds + PG8_SB(b, h) + boff + n * 2048 + k * 1024); } while (0)
; #define PG8_MMA(ai, bj, At, Bt) do { __builtin_amdgcn_s_setprio(1); _Pragma("unroll") for (int m = 0; m < 4; ++m) _Pragma("unroll") for (int n = 0; n < 2; ++n) _Pragma("unroll") for (int k = 0; k < 2; ++k) \
;         acc[ai][bj][m][n] = __builtin_amdgcn_mfma_f32_16x16x32_bf16(Bt[n][k], At[m][k], acc[ai][bj][m][n], 0, 0, 0); __builtin_amdgcn_s_setprio(0); } while (0)
; #define PG8_WAIT_V(n) asm volatile("s_waitcnt vmcnt(" #n ")" ::: "memory")
; #define PG8_WAIT_L(n) asm volatile("s_waitcnt lgkmcnt(" #n ")" ::: "memory")
; #define PG8_BAR __builtin_amdgcn_s_barrier()
; #define PG8_SCHED __builtin_amdgcn_sched_barrier(0)
; template <class Epi, class Sched, bool ALIGN_EPI, bool LAST_FUSED = false, bool PERM = false, bool CARRY = false>
; __device__ __forceinline__ void gemm_phase(LAS unsigned char* lds, const int tid, const int K, const int lda, const int ldb, const Sched& S, const Epi& E) {
;     ...
;             PG8_LDB(B0, 1, 0); PG8_LDB(B1, 1, 1); PG8_SCHED; PG8_LDA(At, 1, 0); PG8_STAGE(PG8_SA(0, 1), a2 + hstepA, voffA);
;             PG8_WAIT_V(8); PG8_WAIT_L(0); PG8_BAR; PG8_MMA(0, 0, At, B0); PG8_MMA(0, 1, At, B1); PG8_BAR; PG8_SCHED;
;             PG8_LDA(At, 1, 1); PG8_STAGE(PG8_SB(1, 0), b3, voffB); PG8_STAGE(PG8_SB(1, 1), b3 + hstepB, voffB); PG8_STAGE(PG8_SA(1, 0), a3, voffA);
;             PG8_WAIT_V(8); PG8_WAIT_L(0); PG8_BAR; PG8_MMA(1, 0, At, B0); PG8_MMA(1, 1, At, B1); PG8_BAR; PG8_SCHED;
;         }
;         if constexpr (ALIGN_EPI) { if (wr == 0) PG8_BAR; }
	s_setprio 0
	s_mov_b32 m0, s61
	v_lshl_add_u64 v[204:205], v[204:205], 0, s[68:69]
	ds_read_b128 v[172:175], v143 offset:49152
	ds_read_b128 v[176:179], v143 offset:50176
	ds_read_b128 v[180:183], v143 offset:51200
	ds_read_b128 v[184:187], v143 offset:52224
	ds_read_b128 v[188:191], v143 offset:53248
	ds_read_b128 v[192:195], v143 offset:54272
	ds_read_b128 v[196:199], v143 offset:55296
	ds_read_b128 v[200:203], v143 offset:56320
	global_load_lds_dwordx4 v[204:205], off
	v_lshl_add_u64 v[204:205], v[206:207], 0, s[68:69]
	s_mov_b32 m0, s24
	s_nop 0
	global_load_lds_dwordx4 v[204:205], off
	v_lshl_add_u64 v[204:205], s[38:39], 0, v[0:1]
	s_mov_b32 m0, s63
	s_nop 0
	global_load_lds_dwordx4 v[204:205], off
	v_lshl_add_u64 v[204:205], s[38:39], 0, v[134:135]
	s_mov_b32 m0, s62
	s_nop 0
	global_load_lds_dwordx4 v[204:205], off
	v_lshl_add_u64 v[204:205], v[208:209], 0, s[68:69]
	s_mov_b32 m0, s55
	s_nop 0
	global_load_lds_dwordx4 v[204:205], off
	v_lshl_add_u64 v[204:205], v[210:211], 0, s[68:69]
	s_mov_b32 m0, s56
	s_nop 0
	global_load_lds_dwordx4 v[204:205], off
	s_waitcnt vmcnt(8)
	s_waitcnt lgkmcnt(0)
	s_setprio 1
	s_barrier
	v_mfma_f32_16x16x32_bf16 v[62:65], v[136:139], v[172:175], v[62:65]
	v_mfma_f32_16x16x32_bf16 v[58:61], v[148:151], v[172:175], v[58:61]
	v_mfma_f32_16x16x32_bf16 v[54:57], v[136:139], v[180:183], v[54:57]
	v_mfma_f32_16x16x32_bf16 v[50:53], v[148:151], v[180:183], v[50:53]
	v_mfma_f32_16x16x32_bf16 v[46:49], v[136:139], v[188:191], v[46:49]
	v_mfma_f32_16x16x32_bf16 v[42:45], v[148:151], v[188:191], v[42:45]
	v_mfma_f32_16x16x32_bf16 v[38:41], v[136:139], v[196:199], v[38:41]
	v_mfma_f32_16x16x32_bf16 v[34:37], v[148:151], v[196:199], v[34:37]
	v_mfma_f32_16x16x32_bf16 v[62:65], v[144:147], v[176:179], v[62:65]
	v_mfma_f32_16x16x32_bf16 v[58:61], v[152:155], v[176:179], v[58:61]
	v_mfma_f32_16x16x32_bf16 v[54:57], v[144:147], v[184:187], v[54:57]
	v_mfma_f32_16x16x32_bf16 v[50:53], v[152:155], v[184:187], v[50:53]
	v_mfma_f32_16x16x32_bf16 v[46:49], v[144:147], v[192:195], v[46:49]
	v_mfma_f32_16x16x32_bf16 v[42:45], v[152:155], v[192:195], v[42:45]
	v_mfma_f32_16x16x32_bf16 v[38:41], v[144:147], v[200:203], v[38:41]
	v_mfma_f32_16x16x32_bf16 v[34:37], v[152:155], v[200:203], v[34:37]
	s_setprio 0
	s_setprio 1
	v_mfma_f32_16x16x32_bf16 v[30:33], v[156:159], v[172:175], v[30:33]
	v_mfma_f32_16x16x32_bf16 v[26:29], v[164:167], v[172:175], v[26:29]
	v_mfma_f32_16x16x32_bf16 v[22:25], v[156:159], v[180:183], v[22:25]
	v_mfma_f32_16x16x32_bf16 v[18:21], v[164:167], v[180:183], v[18:21]
	v_mfma_f32_16x16x32_bf16 v[14:17], v[156:159], v[188:191], v[14:17]
	v_mfma_f32_16x16x32_bf16 v[10:13], v[164:167], v[188:191], v[10:13]
	v_mfma_f32_16x16x32_bf16 v[6:9], v[156:159], v[196:199], v[6:9]
	v_mfma_f32_16x16x32_bf16 v[2:5], v[164:167], v[196:199], v[2:5]
	v_mfma_f32_16x16x32_bf16 v[30:33], v[160:163], v[176:179], v[30:33]
	v_mfma_f32_16x16x32_bf16 v[26:29], v[168:171], v[176:179], v[26:29]
	v_mfma_f32_16x16x32_bf16 v[22:25], v[160:163], v[184:187], v[22:25]
	v_mfma_f32_16x16x32_bf16 v[18:21], v[168:171], v[184:187], v[18:21]
	v_mfma_f32_16x16x32_bf16 v[14:17], v[160:163], v[192:195], v[14:17]
	v_mfma_f32_16x16x32_bf16 v[10:13], v[168:171], v[192:195], v[10:13]
	v_mfma_f32_16x16x32_bf16 v[6:9], v[160:163], v[200:203], v[6:9]
	v_mfma_f32_16x16x32_bf16 v[2:5], v[168:171], v[200:203], v[2:5]
	s_barrier
	s_setprio 0
	s_movk_i32 s24, 0x100
	s_andn2_b64 vcc, exec, s[36:37]
	s_mov_b64 s[38:39], -1
	s_mov_b64 s[36:37], 0
	s_cbranch_vccz .LBB0_622
	s_and_b64 vcc, exec, s[10:11]
	s_cbranch_vccz .LBB0_625
	s_barrier

; #define PG8_STAGE(bufoff, gbase, voff) do { _Pragma("unroll") for (int _i = 0; _i < 2; ++_i) \
;         __builtin_amdgcn_global_load_lds((const unsigned*)((const char*)(gbase) + (voff)[_i]), (LAS unsigned*)(lds + (bufoff) + ldsw + _i * 8192), 16, 0, 0); } while (0)
; #define PG8_LDA(dst, b, h) do { _Pragma("unroll") for (int m = 0; m < 4; ++m) _Pragma("unroll") for (int k = 0; k < 2; ++k) dst[m][k] = *(const LAS bf16x8*)(lds + PG8_SA(b, h) + aoff + m * 2048 + k * 1024); } while (0)
; #define PG8_LDB(dst, b, h) do { _Pragma("unroll") for (int n = 0; n < 2; ++n) _Pragma("unroll") for (int k = 0; k < 2; ++k) dst[n][k] = *(const LAS bf16x8*)(lds + PG8_SB(b, h) + boff + n * 2048 + k * 1024); } while (0)
; template <class Epi, class Sched, bool ALIGN_EPI, bool LAST_FUSED = false, bool PERM = false, bool CARRY = false>
; __device__ __forceinline__ void gemm_phase(LAS unsigned char* lds, const int tid, const int K, const int lda, const int ldb, const Sched& S, const Epi& E) {
;     ...
;         for (int t = 0; t < nt; t += 2) {
;             const bool last = (t == nt - 2);
;             const char* a1 = cA + (size_t)(t + 1) * kstep;
;             const char* a2 = last ? nA : cA + (size_t)(t + 2) * kstep; const char* b2 = last ? nB : cB + (size_t)(t + 2) * kstep;
;             const char* a3 = a2 + kstep; const char* b3 = b2 + kstep;
;             PG8_LDB(B0, 0, 0); PG8_LDB(B1, 0, 1); PG8_SCHED; PG8_LDA(At, 0, 0); PG8_STAGE(PG8_SA(1, 1), a1 + hstepA, voffA);
;             PG8_WAIT_V(8); PG8_WAIT_L(0); PG8_BAR; PG8_MMA(0, 0, At, B0); PG8_MMA(0, 1, At, B1); PG8_BAR; PG8_SCHED;
;             PG8_LDA(At, 0, 1); PG8_STAGE(PG8_SB(0, 0), b2, voffB); PG8_STAGE(PG8_SB(0, 1), b2 + hstepB, voffB); PG8_STAGE(PG8_SA(0, 0), a2, voffA);
;             PG8_WAIT_V(8); PG8_WAIT_L(0); PG8_BAR; PG8_MMA(1, 0, At, B0); PG8_MMA(1, 1, At, B1); PG8_BAR; PG8_SCHED;
;             PG8_LDB(B0, 1, 0); PG8_LDB(B1, 1, 1); PG8_SCHED; PG8_LDA(At, 1, 0); PG8_STAGE(PG8_SA(0, 1), a2 + hstepA, voffA);
;             PG8_WAIT_V(8); PG8_WAIT_L(0); PG8_BAR; PG8_MMA(0, 0, At, B0); PG8_MMA(0, 1, At, B1); PG8_BAR; PG8_SCHED;
;             PG8_LDA(At, 1, 1); PG8_STAGE(PG8_SB(1, 0), b3, voffB); PG8_STAGE(PG8_SB(1, 1), b3 + hstepB, voffB); PG8_STAGE(PG8_SA(1, 0), a3, voffA);
;             PG8_WAIT_V(8); PG8_WAIT_L(0); PG8_BAR; PG8_MMA(1, 0, At, B0); PG8_MMA(1, 1, At, B1); PG8_BAR; PG8_SCHED;
.LBB0_705:
	s_add_u32 s30, s26, 0x100
	s_addc_u32 s31, s27, 0
	s_add_i32 s54, 0, 0x10000
	s_cmp_eq_u32 s53, 8
	s_cselect_b32 s39, s15, s31
	s_cselect_b32 s38, s14, s30
	v_add_u32_e32 v140, s54, v144
	s_cselect_b32 s37, s17, s52
	s_cselect_b32 s36, s16, s13
	s_add_i32 s55, 0, 0x14000
	ds_read_b128 v[146:149], v140
	ds_read_b128 v[150:153], v140 offset:1024
	ds_read_b128 v[154:157], v140 offset:2048
	ds_read_b128 v[158:161], v140 offset:3072
	v_add_u32_e32 v140, s55, v144
	ds_read_b128 v[162:165], v140
	ds_read_b128 v[166:169], v140 offset:1024
	ds_read_b128 v[170:173], v140 offset:2048
	ds_read_b128 v[174:177], v140 offset:3072
	v_lshl_add_u64 v[140:141], s[26:27], 0, v[136:137]
	s_add_i32 m0, s19, 0xc000
	ds_read_b128 v[178:181], v145
	ds_read_b128 v[182:185], v145 offset:1024
	ds_read_b128 v[186:189], v145 offset:2048
	ds_read_b128 v[190:193], v145 offset:3072
	ds_read_b128 v[194:197], v145 offset:4096
	ds_read_b128 v[198:201], v145 offset:5120
	ds_read_b128 v[202:205], v145 offset:6144
	ds_read_b128 v[206:209], v145 offset:7168
	global_load_lds_dwordx4 v[140:141], off
	v_lshl_add_u64 v[140:141], s[26:27], 0, v[138:139]
	s_add_i32 m0, s19, 0xe000
	s_nop 0
	global_load_lds_dwordx4 v[140:141], off
	s_waitcnt vmcnt(8)
	s_waitcnt lgkmcnt(0)
	s_setprio 1
	s_barrier
	v_mfma_f32_16x16x32_bf16 v[126:129], v[146:149], v[178:181], v[126:129]
	v_mfma_f32_16x16x32_bf16 v[122:125], v[154:157], v[178:181], v[122:125]
	v_mfma_f32_16x16x32_bf16 v[118:121], v[146:149], v[186:189], v[118:121]
	v_mfma_f32_16x16x32_bf16 v[110:113], v[154:157], v[186:189], v[110:113]
	v_mfma_f32_16x16x32_bf16 v[102:105], v[146:149], v[194:197], v[102:105]
	v_mfma_f32_16x16x32_bf16 v[94:97], v[154:157], v[194:197], v[94:97]
	v_mfma_f32_16x16x32_bf16 v[86:89], v[146:149], v[202:205], v[86:89]
	v_mfma_f32_16x16x32_bf16 v[78:81], v[154:157], v[202:205], v[78:81]
	v_mfma_f32_16x16x32_bf16 v[126:129], v[150:153], v[182:185], v[126:129]
	v_mfma_f32_16x16x32_bf16 v[122:125], v[158:161], v[182:185], v[122:125]
	v_mfma_f32_16x16x32_bf16 v[118:121], v[150:153], v[190:193], v[118:121]
	v_mfma_f32_16x16x32_bf16 v[110:113], v[158:161], v[190:193], v[110:113]
	v_mfma_f32_16x16x32_bf16 v[102:105], v[150:153], v[198:201], v[102:105]
	v_mfma_f32_16x16x32_bf16 v[94:97], v[158:161], v[198:201], v[94:97]
	v_mfma_f32_16x16x32_bf16 v[86:89], v[150:153], v[206:209], v[86:89]
	v_mfma_f32_16x16x32_bf16 v[78:81], v[158:161], v[206:209], v[78:81]
	s_setprio 0
	s_setprio 1
	v_mfma_f32_16x16x32_bf16 v[114:117], v[162:165], v[178:181], v[114:117]
	v_mfma_f32_16x16x32_bf16 v[106:109], v[170:173], v[178:181], v[106:109]
	v_mfma_f32_16x16x32_bf16 v[98:101], v[162:165], v[186:189], v[98:101]
	v_mfma_f32_16x16x32_bf16 v[90:93], v[170:173], v[186:189], v[90:93]
	v_mfma_f32_16x16x32_bf16 v[82:85], v[162:165], v[194:197], v[82:85]
	v_mfma_f32_16x16x32_bf16 v[74:77], v[170:173], v[194:197], v[74:77]
	v_mfma_f32_16x16x32_bf16 v[70:73], v[162:165], v[202:205], v[70:73]
	v_mfma_f32_16x16x32_bf16 v[66:69], v[170:173], v[202:205], v[66:69]
	v_mfma_f32_16x16x32_bf16 v[114:117], v[166:169], v[182:185], v[114:117]
	v_mfma_f32_16x16x32_bf16 v[106:109], v[174:177], v[182:185], v[106:109]
	v_mfma_f32_16x16x32_bf16 v[98:101], v[166:169], v[190:193], v[98:101]
	v_mfma_f32_16x16x32_bf16 v[90:93], v[174:177], v[190:193], v[90:93]
	v_mfma_f32_16x16x32_bf16 v[82:85], v[166:169], v[198:201], v[82:85]
	v_mfma_f32_16x16x32_bf16 v[74:77], v[174:177], v[198:201], v[74:77]
	v_mfma_f32_16x16x32_bf16 v[70:73], v[166:169], v[206:209], v[70:73]
	v_mfma_f32_16x16x32_bf16 v[66:69], v[174:177], v[206:209], v[66:69]
	s_barrier
	s_setprio 0
	s_add_i32 s26, s54, s40
	v_lshl_add_u64 v[140:141], s[36:37], 0, v[0:1]
	s_mov_b32 m0, s26
	ds_read_b128 v[178:181], v145 offset:16384
	ds_read_b128 v[182:185], v145 offset:17408
	ds_read_b128 v[186:189], v145 offset:18432
	ds_read_b128 v[190:193], v145 offset:19456
	ds_read_b128 v[194:197], v145 offset:20480
	ds_read_b128 v[198:201], v145 offset:21504
	ds_read_b128 v[202:205], v145 offset:22528
	ds_read_b128 v[206:209], v145 offset:23552
	global_load_lds_dwordx4 v[140:141], off
	s_add_i32 m0, s26, 0x2000
	s_add_u32 s26, s36, 0x30000
	v_lshl_add_u64 v[210:211], s[36:37], 0, v[130:131]
	s_addc_u32 s27, s37, 0
	s_add_i32 s54, s55, s40
	global_load_lds_dwordx4 v[210:211], off
	v_lshl_add_u64 v[212:213], s[26:27], 0, v[0:1]
	s_mov_b32 m0, s54
	v_lshl_add_u64 v[214:215], s[38:39], 0, v[132:133]
	global_load_lds_dwordx4 v[212:213], off
	v_lshl_add_u64 v[212:213], s[26:27], 0, v[130:131]
	s_add_i32 m0, s54, 0x2000
	s_nop 0
	global_load_lds_dwordx4 v[212:213], off
	v_lshl_add_u64 v[212:213], s[38:39], 0, v[134:135]
	s_mov_b32 m0, s19
	s_nop 0
	global_load_lds_dwordx4 v[212:213], off
	s_mov_b32 m0, s42
	s_nop 0
	global_load_lds_dwordx4 v[214:215], off
	s_waitcnt vmcnt(8)
	s_waitcnt lgkmcnt(0)
	s_setprio 1
	s_barrier
; #define PG8_STAGE(bufoff, gbase, voff) do { _Pragma("unroll") for (int _i = 0; _i < 2; ++_i) \
;         __builtin_amdgcn_global_load_lds((const unsigned*)((const char*)(gbase) + (voff)[_i]), (LAS unsigned*)(lds + (bufoff) + ldsw + _i * 8192), 16, 0, 0); } while (0)
; #define PG8_LDA(dst, b, h) do { _Pragma("unroll") for (int m = 0; m < 4; ++m) _Pragma("unroll") for (int k = 0; k < 2; ++k) dst[m][k] = *(const LAS bf16x8*)(lds + PG8_SA(b, h) + aoff + m * 2048 + k * 1024); } while (0)
; #define PG8_LDB(dst, b, h) do { _Pragma("unroll") for (int n = 0; n < 2; ++n) _Pragma("unroll") for (int k = 0; k < 2; ++k) dst[n][k] = *(const LAS bf16x8*)(lds + PG8_SB(b, h) + boff + n * 2048 + k * 1024); } while (0)
; #define PG8_MMA(ai, bj, At, Bt) do { __builtin_amdgcn_s_setprio(1); _Pragma("unroll") for (int m = 0; m < 4; ++m) _Pragma("unroll") for (int n = 0; n < 2; ++n) _Pragma("unroll") for (int k = 0; k < 2; ++k) \
;         acc[ai][bj][m][n] = __builtin_amdgcn_mfma_f32_16x16x32_bf16(Bt[n][k], At[m][k], acc[ai][bj][m][n], 0, 0, 0); __builtin_amdgcn_s_setprio(0); } while (0)
; #define PG8_WAIT_V(n) asm volatile("s_waitcnt vmcnt(" #n ")" ::: "memory")
; #define PG8_WAIT_L(n) asm volatile("s_waitcnt lgkmcnt(" #n ")" ::: "memory")
; #define PG8_BAR __builtin_amdgcn_s_barrier()
; #define PG8_SCHED __builtin_amdgcn_sched_barrier(0)
; template <class Epi, class Sched, bool ALIGN_EPI, bool LAST_FUSED = false, bool PERM = false, bool CARRY = false>
; __device__ __forceinline__ void gemm_phase(LAS unsigned char* lds, const int tid, const int K, const int lda, const int ldb, const Sched& S, const Epi& E) {
;     ...
;             PG8_WAIT_V(8); PG8_WAIT_L(0); PG8_BAR; PG8_MMA(1, 0, At, B0); PG8_MMA(1, 1, At, B1); PG8_BAR; PG8_SCHED;
;             PG8_LDB(B0, 1, 0); PG8_LDB(B1, 1, 1); PG8_SCHED; PG8_LDA(At, 1, 0); PG8_STAGE(PG8_SA(0, 1), a2 + hstepA, voffA);
;             PG8_WAIT_V(8); PG8_WAIT_L(0); PG8_BAR; PG8_MMA(0, 0, At, B0); PG8_MMA(0, 1, At, B1); PG8_BAR; PG8_SCHED;
;             PG8_LDA(At, 1, 1); PG8_STAGE(PG8_SB(1, 0), b3, voffB); PG8_STAGE(PG8_SB(1, 1), b3 + hstepB, voffB); PG8_STAGE(PG8_SA(1, 0), a3, voffA);
;             PG8_WAIT_V(8); PG8_WAIT_L(0); PG8_BAR; PG8_MMA(1, 0, At, B0); PG8_MMA(1, 1, At, B1); PG8_BAR; PG8_SCHED;
	v_mfma_f32_16x16x32_bf16 v[62:65], v[146:149], v[178:181], v[62:65]
	v_mfma_f32_16x16x32_bf16 v[58:61], v[154:157], v[178:181], v[58:61]
	v_mfma_f32_16x16x32_bf16 v[54:57], v[146:149], v[186:189], v[54:57]
	v_mfma_f32_16x16x32_bf16 v[46:49], v[154:157], v[186:189], v[46:49]
	v_mfma_f32_16x16x32_bf16 v[38:41], v[146:149], v[194:197], v[38:41]
	v_mfma_f32_16x16x32_bf16 v[30:33], v[154:157], v[194:197], v[30:33]
	v_mfma_f32_16x16x32_bf16 v[22:25], v[146:149], v[202:205], v[22:25]
	v_mfma_f32_16x16x32_bf16 v[14:17], v[154:157], v[202:205], v[14:17]
	v_mfma_f32_16x16x32_bf16 v[62:65], v[150:153], v[182:185], v[62:65]
	v_mfma_f32_16x16x32_bf16 v[58:61], v[158:161], v[182:185], v[58:61]
	v_mfma_f32_16x16x32_bf16 v[54:57], v[150:153], v[190:193], v[54:57]
	v_mfma_f32_16x16x32_bf16 v[46:49], v[158:161], v[190:193], v[46:49]
	v_mfma_f32_16x16x32_bf16 v[38:41], v[150:153], v[198:201], v[38:41]
	v_mfma_f32_16x16x32_bf16 v[30:33], v[158:161], v[198:201], v[30:33]
	v_mfma_f32_16x16x32_bf16 v[22:25], v[150:153], v[206:209], v[22:25]
	v_mfma_f32_16x16x32_bf16 v[14:17], v[158:161], v[206:209], v[14:17]
	s_setprio 0
	s_setprio 1
	v_mfma_f32_16x16x32_bf16 v[50:53], v[162:165], v[178:181], v[50:53]
	v_mfma_f32_16x16x32_bf16 v[42:45], v[170:173], v[178:181], v[42:45]
	v_mfma_f32_16x16x32_bf16 v[34:37], v[162:165], v[186:189], v[34:37]
	v_mfma_f32_16x16x32_bf16 v[26:29], v[170:173], v[186:189], v[26:29]
	v_mfma_f32_16x16x32_bf16 v[18:21], v[162:165], v[194:197], v[18:21]
	v_mfma_f32_16x16x32_bf16 v[10:13], v[170:173], v[194:197], v[10:13]
	v_mfma_f32_16x16x32_bf16 v[6:9], v[162:165], v[202:205], v[6:9]
	v_mfma_f32_16x16x32_bf16 v[2:5], v[170:173], v[202:205], v[2:5]
	v_mfma_f32_16x16x32_bf16 v[50:53], v[166:169], v[182:185], v[50:53]
	v_mfma_f32_16x16x32_bf16 v[42:45], v[174:177], v[182:185], v[42:45]
	v_mfma_f32_16x16x32_bf16 v[34:37], v[166:169], v[190:193], v[34:37]
	v_mfma_f32_16x16x32_bf16 v[26:29], v[174:177], v[190:193], v[26:29]
	v_mfma_f32_16x16x32_bf16 v[18:21], v[166:169], v[198:201], v[18:21]
	v_mfma_f32_16x16x32_bf16 v[10:13], v[174:177], v[198:201], v[10:13]
	v_mfma_f32_16x16x32_bf16 v[6:9], v[166:169], v[206:209], v[6:9]
	v_mfma_f32_16x16x32_bf16 v[2:5], v[174:177], v[206:209], v[2:5]
	s_barrier
	s_setprio 0
	s_add_i32 s54, 0, 0x18000
	s_add_i32 s55, 0, 0x1c000
	v_add_u32_e32 v158, s54, v144
	v_add_u32_e32 v174, s55, v144
	ds_read_b128 v[146:149], v158
	ds_read_b128 v[150:153], v158 offset:1024
	ds_read_b128 v[154:157], v158 offset:2048
	ds_read_b128 v[158:161], v158 offset:3072
	ds_read_b128 v[162:165], v174
	ds_read_b128 v[166:169], v174 offset:1024
	ds_read_b128 v[170:173], v174 offset:2048
	ds_read_b128 v[174:177], v174 offset:3072
	s_add_u32 s26, s38, 0x180000
	s_addc_u32 s27, s39, 0
	s_mov_b32 m0, s43
	v_lshl_add_u64 v[216:217], s[26:27], 0, v[134:135]
	ds_read_b128 v[178:181], v145 offset:32768
	ds_read_b128 v[182:185], v145 offset:33792
	ds_read_b128 v[186:189], v145 offset:34816
	ds_read_b128 v[190:193], v145 offset:35840
	ds_read_b128 v[194:197], v145 offset:36864
	ds_read_b128 v[198:201], v145 offset:37888
	ds_read_b128 v[202:205], v145 offset:38912
	ds_read_b128 v[206:209], v145 offset:39936
	global_load_lds_dwordx4 v[216:217], off
	v_lshl_add_u64 v[216:217], s[26:27], 0, v[132:133]
	s_mov_b32 m0, s44
	s_nop 0
	global_load_lds_dwordx4 v[216:217], off
	s_waitcnt vmcnt(8)
	s_waitcnt lgkmcnt(0)
	s_setprio 1
	s_barrier
	v_mfma_f32_16x16x32_bf16 v[126:129], v[146:149], v[178:181], v[126:129]
	v_mfma_f32_16x16x32_bf16 v[122:125], v[154:157], v[178:181], v[122:125]
	v_mfma_f32_16x16x32_bf16 v[118:121], v[146:149], v[186:189], v[118:121]
	v_mfma_f32_16x16x32_bf16 v[110:113], v[154:157], v[186:189], v[110:113]
	v_mfma_f32_16x16x32_bf16 v[102:105], v[146:149], v[194:197], v[102:105]
	v_mfma_f32_16x16x32_bf16 v[94:97], v[154:157], v[194:197], v[94:97]
	v_mfma_f32_16x16x32_bf16 v[86:89], v[146:149], v[202:205], v[86:89]
	v_mfma_f32_16x16x32_bf16 v[78:81], v[154:157], v[202:205], v[78:81]
	v_mfma_f32_16x16x32_bf16 v[126:129], v[150:153], v[182:185], v[126:129]
	v_mfma_f32_16x16x32_bf16 v[122:125], v[158:161], v[182:185], v[122:125]
	v_mfma_f32_16x16x32_bf16 v[118:121], v[150:153], v[190:193], v[118:121]
	v_mfma_f32_16x16x32_bf16 v[110:113], v[158:161], v[190:193], v[110:113]
	v_mfma_f32_16x16x32_bf16 v[102:105], v[150:153], v[198:201], v[102:105]
	v_mfma_f32_16x16x32_bf16 v[94:97], v[158:161], v[198:201], v[94:97]
	v_mfma_f32_16x16x32_bf16 v[86:89], v[150:153], v[206:209], v[86:89]
	v_mfma_f32_16x16x32_bf16 v[78:81], v[158:161], v[206:209], v[78:81]
	s_setprio 0
	s_setprio 1
	v_mfma_f32_16x16x32_bf16 v[114:117], v[162:165], v[178:181], v[114:117]
	v_mfma_f32_16x16x32_bf16 v[106:109], v[170:173], v[178:181], v[106:109]
	v_mfma_f32_16x16x32_bf16 v[98:101], v[162:165], v[186:189], v[98:101]
	v_mfma_f32_16x16x32_bf16 v[90:93], v[170:173], v[186:189], v[90:93]
	v_mfma_f32_16x16x32_bf16 v[82:85], v[162:165], v[194:197], v[82:85]
	v_mfma_f32_16x16x32_bf16 v[74:77], v[170:173], v[194:197], v[74:77]
	v_mfma_f32_16x16x32_bf16 v[70:73], v[162:165], v[202:205], v[70:73]
	v_mfma_f32_16x16x32_bf16 v[66:69], v[170:173], v[202:205], v[66:69]
	v_mfma_f32_16x16x32_bf16 v[114:117], v[166:169], v[182:185], v[114:117]
	v_mfma_f32_16x16x32_bf16 v[106:109], v[174:177], v[182:185], v[106:109]
	v_mfma_f32_16x16x32_bf16 v[98:101], v[166:169], v[190:193], v[98:101]
	v_mfma_f32_16x16x32_bf16 v[90:93], v[174:177], v[190:193], v[90:93]
	v_mfma_f32_16x16x32_bf16 v[82:85], v[166:169], v[198:201], v[82:85]
	v_mfma_f32_16x16x32_bf16 v[74:77], v[174:177], v[198:201], v[74:77]
	v_mfma_f32_16x16x32_bf16 v[70:73], v[166:169], v[206:209], v[70:73]
	v_mfma_f32_16x16x32_bf16 v[66:69], v[174:177], v[206:209], v[66:69]
	s_barrier
; #define PG8_STAGE(bufoff, gbase, voff) do { _Pragma("unroll") for (int _i = 0; _i < 2; ++_i) \
;         __builtin_amdgcn_global_load_lds((const unsigned*)((const char*)(gbase) + (voff)[_i]), (LAS unsigned*)(lds + (bufoff) + ldsw + _i * 8192), 16, 0, 0); } while (0)
; #define PG8_LDA(dst, b, h) do { _Pragma("unroll") for (int m = 0; m < 4; ++m) _Pragma("unroll") for (int k = 0; k < 2; ++k) dst[m][k] = *(const LAS bf16x8*)(lds + PG8_SA(b, h) + aoff + m * 2048 + k * 1024); } while (0)
; #define PG8_LDB(dst, b, h) do { _Pragma("unroll") for (int n = 0; n < 2; ++n) _Pragma("unroll") for (int k = 0; k < 2; ++k) dst[n][k] = *(const LAS bf16x8*)(lds + PG8_SB(b, h) + boff + n * 2048 + k * 1024); } while (0)
; #define PG8_MMA(ai, bj, At, Bt) do { __builtin_amdgcn_s_setprio(1); _Pragma("unroll") for (int m = 0; m < 4; ++m) _Pragma("unroll") for (int n = 0; n < 2; ++n) _Pragma("unroll") for (int k = 0; k < 2; ++k) \
;         acc[ai][bj][m][n] = __builtin_amdgcn_mfma_f32_16x16x32_bf16(Bt[n][k], At[m][k], acc[ai][bj][m][n], 0, 0, 0); __builtin_amdgcn_s_setprio(0); } while (0)
; #define PG8_WAIT_V(n) asm volatile("s_waitcnt vmcnt(" #n ")" ::: "memory")
; #define PG8_WAIT_L(n) asm volatile("s_waitcnt lgkmcnt(" #n ")" ::: "memory")
; #define PG8_BAR __builtin_amdgcn_s_barrier()
; #define PG8_SCHED __builtin_amdgcn_sched_barrier(0)
; template <class Epi, class Sched, bool ALIGN_EPI, bool LAST_FUSED = false, bool PERM = false, bool CARRY = false>
; __device__ __forceinline__ void gemm_phase(LAS unsigned char* lds, const int tid, const int K, const int lda, const int ldb, const Sched& S, const Epi& E) {
;     ...
;             PG8_LDB(B0, 1, 0); PG8_LDB(B1, 1, 1); PG8_SCHED; PG8_LDA(At, 1, 0); PG8_STAGE(PG8_SA(0, 1), a2 + hstepA, voffA);
;             PG8_WAIT_V(8); PG8_WAIT_L(0); PG8_BAR; PG8_MMA(0, 0, At, B0); PG8_MMA(0, 1, At, B1); PG8_BAR; PG8_SCHED;
;             PG8_LDA(At, 1, 1); PG8_STAGE(PG8_SB(1, 0), b3, voffB); PG8_STAGE(PG8_SB(1, 1), b3 + hstepB, voffB); PG8_STAGE(PG8_SA(1, 0), a3, voffA);
;             PG8_WAIT_V(8); PG8_WAIT_L(0); PG8_BAR; PG8_MMA(1, 0, At, B0); PG8_MMA(1, 1, At, B1); PG8_BAR; PG8_SCHED;
;         }
;         if constexpr (ALIGN_EPI) { if (wr == 0) PG8_BAR; }
	s_setprio 0
	s_add_i32 s26, s54, s40
	v_lshl_add_u64 v[140:141], v[140:141], 0, s[68:69]
	s_mov_b32 m0, s26
	ds_read_b128 v[178:181], v145 offset:49152
	ds_read_b128 v[182:185], v145 offset:50176
	ds_read_b128 v[186:189], v145 offset:51200
	ds_read_b128 v[190:193], v145 offset:52224
	ds_read_b128 v[194:197], v145 offset:53248
	ds_read_b128 v[198:201], v145 offset:54272
	ds_read_b128 v[202:205], v145 offset:55296
	ds_read_b128 v[206:209], v145 offset:56320
	global_load_lds_dwordx4 v[140:141], off
	s_add_i32 m0, s26, 0x2000
	s_add_u32 s26, s36, 0x30080
	v_lshl_add_u64 v[140:141], v[210:211], 0, s[68:69]
	s_addc_u32 s27, s37, 0
	s_add_i32 s36, s55, s40
	global_load_lds_dwordx4 v[140:141], off
	v_lshl_add_u64 v[140:141], s[26:27], 0, v[0:1]
	s_mov_b32 m0, s36
	s_nop 0
	global_load_lds_dwordx4 v[140:141], off
	v_lshl_add_u64 v[140:141], s[26:27], 0, v[130:131]
	s_add_i32 m0, s36, 0x2000
	s_nop 0
	global_load_lds_dwordx4 v[140:141], off
	v_lshl_add_u64 v[140:141], v[212:213], 0, s[68:69]
	s_mov_b32 m0, s46
	s_nop 0
	global_load_lds_dwordx4 v[140:141], off
	v_lshl_add_u64 v[140:141], v[214:215], 0, s[68:69]
	s_mov_b32 m0, s47
	s_nop 0
	global_load_lds_dwordx4 v[140:141], off
	s_waitcnt vmcnt(8)
	s_waitcnt lgkmcnt(0)
	s_setprio 1
	s_barrier
	v_mfma_f32_16x16x32_bf16 v[62:65], v[146:149], v[178:181], v[62:65]
	v_mfma_f32_16x16x32_bf16 v[58:61], v[154:157], v[178:181], v[58:61]
	v_mfma_f32_16x16x32_bf16 v[54:57], v[146:149], v[186:189], v[54:57]
	v_mfma_f32_16x16x32_bf16 v[46:49], v[154:157], v[186:189], v[46:49]
	v_mfma_f32_16x16x32_bf16 v[38:41], v[146:149], v[194:197], v[38:41]
	v_mfma_f32_16x16x32_bf16 v[30:33], v[154:157], v[194:197], v[30:33]
	v_mfma_f32_16x16x32_bf16 v[22:25], v[146:149], v[202:205], v[22:25]
	v_mfma_f32_16x16x32_bf16 v[14:17], v[154:157], v[202:205], v[14:17]
	v_mfma_f32_16x16x32_bf16 v[62:65], v[150:153], v[182:185], v[62:65]
	v_mfma_f32_16x16x32_bf16 v[58:61], v[158:161], v[182:185], v[58:61]
	v_mfma_f32_16x16x32_bf16 v[54:57], v[150:153], v[190:193], v[54:57]
	v_mfma_f32_16x16x32_bf16 v[46:49], v[158:161], v[190:193], v[46:49]
	v_mfma_f32_16x16x32_bf16 v[38:41], v[150:153], v[198:201], v[38:41]
	v_mfma_f32_16x16x32_bf16 v[30:33], v[158:161], v[198:201], v[30:33]
	v_mfma_f32_16x16x32_bf16 v[22:25], v[150:153], v[206:209], v[22:25]
	v_mfma_f32_16x16x32_bf16 v[14:17], v[158:161], v[206:209], v[14:17]
	s_setprio 0
	s_setprio 1
	v_mfma_f32_16x16x32_bf16 v[50:53], v[162:165], v[178:181], v[50:53]
	v_mfma_f32_16x16x32_bf16 v[42:45], v[170:173], v[178:181], v[42:45]
	v_mfma_f32_16x16x32_bf16 v[34:37], v[162:165], v[186:189], v[34:37]
	v_mfma_f32_16x16x32_bf16 v[26:29], v[170:173], v[186:189], v[26:29]
	v_mfma_f32_16x16x32_bf16 v[18:21], v[162:165], v[194:197], v[18:21]
	v_mfma_f32_16x16x32_bf16 v[10:13], v[170:173], v[194:197], v[10:13]
	v_mfma_f32_16x16x32_bf16 v[6:9], v[162:165], v[202:205], v[6:9]
	v_mfma_f32_16x16x32_bf16 v[2:5], v[170:173], v[202:205], v[2:5]
	v_mfma_f32_16x16x32_bf16 v[50:53], v[166:169], v[182:185], v[50:53]
	v_mfma_f32_16x16x32_bf16 v[42:45], v[174:177], v[182:185], v[42:45]
	v_mfma_f32_16x16x32_bf16 v[34:37], v[166:169], v[190:193], v[34:37]
	v_mfma_f32_16x16x32_bf16 v[26:29], v[174:177], v[190:193], v[26:29]
	v_mfma_f32_16x16x32_bf16 v[18:21], v[166:169], v[198:201], v[18:21]
	v_mfma_f32_16x16x32_bf16 v[10:13], v[174:177], v[198:201], v[10:13]
	v_mfma_f32_16x16x32_bf16 v[6:9], v[166:169], v[206:209], v[6:9]
	v_mfma_f32_16x16x32_bf16 v[2:5], v[174:177], v[206:209], v[2:5]
	s_barrier
	s_setprio 0
	s_add_i32 s53, s53, 2
	s_add_u32 s13, s13, 0x100
	s_addc_u32 s52, s52, 0
	s_cmp_gt_u32 s53, 9
	s_mov_b64 s[26:27], s[30:31]
	s_cbranch_scc0 .LBB0_705
	s_and_b64 vcc, exec, s[10:11]
	s_cbranch_vccz .LBB0_708
	s_barrier

; #define PG8_STAGE(bufoff, gbase, voff) do { _Pragma("unroll") for (int _i = 0; _i < 2; ++_i) \
;         __builtin_amdgcn_global_load_lds((const unsigned*)((const char*)(gbase) + (voff)[_i]), (LAS unsigned*)(lds + (bufoff) + ldsw + _i * 8192), 16, 0, 0); } while (0)
; #define PG8_LDA(dst, b, h) do { _Pragma("unroll") for (int m = 0; m < 4; ++m) _Pragma("unroll") for (int k = 0; k < 2; ++k) dst[m][k] = *(const LAS bf16x8*)(lds + PG8_SA(b, h) + aoff + m * 2048 + k * 1024); } while (0)
; #define PG8_LDB(dst, b, h) do { _Pragma("unroll") for (int n = 0; n < 2; ++n) _Pragma("unroll") for (int k = 0; k < 2; ++k) dst[n][k] = *(const LAS bf16x8*)(lds + PG8_SB(b, h) + boff + n * 2048 + k * 1024); } while (0)
; template <class Epi, class Sched, bool ALIGN_EPI, bool LAST_FUSED = false, bool PERM = false, bool CARRY = false>
; __device__ __forceinline__ void gemm_phase(LAS unsigned char* lds, const int tid, const int K, const int lda, const int ldb, const Sched& S, const Epi& E) {
;     ...
;         for (int t = 0; t < nt; t += 2) {
;             const bool last = (t == nt - 2);
;             const char* a1 = cA + (size_t)(t + 1) * kstep;
;             const char* a2 = last ? nA : cA + (size_t)(t + 2) * kstep; const char* b2 = last ? nB : cB + (size_t)(t + 2) * kstep;
;             const char* a3 = a2 + kstep; const char* b3 = b2 + kstep;
;             PG8_LDB(B0, 0, 0); PG8_LDB(B1, 0, 1); PG8_SCHED; PG8_LDA(At, 0, 0); PG8_STAGE(PG8_SA(1, 1), a1 + hstepA, voffA);
;             PG8_WAIT_V(8); PG8_WAIT_L(0); PG8_BAR; PG8_MMA(0, 0, At, B0); PG8_MMA(0, 1, At, B1); PG8_BAR; PG8_SCHED;
;             PG8_LDA(At, 0, 1); PG8_STAGE(PG8_SB(0, 0), b2, voffB); PG8_STAGE(PG8_SB(0, 1), b2 + hstepB, voffB); PG8_STAGE(PG8_SA(0, 0), a2, voffA);
;             PG8_WAIT_V(8); PG8_WAIT_L(0); PG8_BAR; PG8_MMA(1, 0, At, B0); PG8_MMA(1, 1, At, B1); PG8_BAR; PG8_SCHED;
;             PG8_LDB(B0, 1, 0); PG8_LDB(B1, 1, 1); PG8_SCHED; PG8_LDA(At, 1, 0); PG8_STAGE(PG8_SA(0, 1), a2 + hstepA, voffA);
;             PG8_WAIT_V(8); PG8_WAIT_L(0); PG8_BAR; PG8_MMA(0, 0, At, B0); PG8_MMA(0, 1, At, B1); PG8_BAR; PG8_SCHED;
;             PG8_LDA(At, 1, 1); PG8_STAGE(PG8_SB(1, 0), b3, voffB); PG8_STAGE(PG8_SB(1, 1), b3 + hstepB, voffB); PG8_STAGE(PG8_SA(1, 0), a3, voffA);
;             PG8_WAIT_V(8); PG8_WAIT_L(0); PG8_BAR; PG8_MMA(1, 0, At, B0); PG8_MMA(1, 1, At, B1); PG8_BAR; PG8_SCHED;
.LBB0_838:
	s_add_u32 s6, s4, 0xfff80080
	s_addc_u32 s7, s5, -1
	s_add_i32 s29, 0, 0x10000
	s_cmp_eq_u32 s28, 28
	s_cselect_b32 s37, s43, s7
	s_cselect_b32 s36, s42, s6
	v_add_u32_e32 v140, s29, v146
	s_cselect_b32 s7, s71, s23
	s_cselect_b32 s6, s70, s22
	s_add_i32 s31, 0, 0x14000
	ds_read_b128 v[136:139], v140
	ds_read_b128 v[148:151], v140 offset:1024
	ds_read_b128 v[152:155], v140 offset:2048
	ds_read_b128 v[156:159], v140 offset:3072
	v_add_u32_e32 v140, s31, v146
	ds_read_b128 v[160:163], v140
	ds_read_b128 v[164:167], v140 offset:1024
	ds_read_b128 v[168:171], v140 offset:2048
	ds_read_b128 v[172:175], v140 offset:3072
	v_lshl_add_u64 v[140:141], s[4:5], 0, v[132:133]
	s_add_i32 m0, s50, 0xc000
	ds_read_b128 v[176:179], v147
	ds_read_b128 v[180:183], v147 offset:1024
	ds_read_b128 v[184:187], v147 offset:2048
	ds_read_b128 v[188:191], v147 offset:3072
	ds_read_b128 v[192:195], v147 offset:4096
	ds_read_b128 v[196:199], v147 offset:5120
	ds_read_b128 v[200:203], v147 offset:6144
	ds_read_b128 v[204:207], v147 offset:7168
	global_load_lds_dwordx4 v[140:141], off
	v_lshl_add_u64 v[140:141], s[4:5], 0, v[134:135]
	s_add_i32 m0, s50, 0xe000
	s_nop 0
	global_load_lds_dwordx4 v[140:141], off
	s_waitcnt vmcnt(8)
	s_waitcnt lgkmcnt(0)
	s_setprio 1
	s_barrier
	v_mfma_f32_16x16x32_bf16 v[126:129], v[136:139], v[176:179], v[126:129]
	v_mfma_f32_16x16x32_bf16 v[122:125], v[152:155], v[176:179], v[122:125]
	v_mfma_f32_16x16x32_bf16 v[110:113], v[136:139], v[184:187], v[110:113]
	v_mfma_f32_16x16x32_bf16 v[106:109], v[152:155], v[184:187], v[106:109]
	v_mfma_f32_16x16x32_bf16 v[94:97], v[136:139], v[192:195], v[94:97]
	v_mfma_f32_16x16x32_bf16 v[90:93], v[152:155], v[192:195], v[90:93]
	v_mfma_f32_16x16x32_bf16 v[78:81], v[136:139], v[200:203], v[78:81]
	v_mfma_f32_16x16x32_bf16 v[74:77], v[152:155], v[200:203], v[74:77]
	v_mfma_f32_16x16x32_bf16 v[126:129], v[148:151], v[180:183], v[126:129]
	v_mfma_f32_16x16x32_bf16 v[122:125], v[156:159], v[180:183], v[122:125]
	v_mfma_f32_16x16x32_bf16 v[110:113], v[148:151], v[188:191], v[110:113]
	v_mfma_f32_16x16x32_bf16 v[106:109], v[156:159], v[188:191], v[106:109]
	v_mfma_f32_16x16x32_bf16 v[94:97], v[148:151], v[196:199], v[94:97]
	v_mfma_f32_16x16x32_bf16 v[90:93], v[156:159], v[196:199], v[90:93]
	v_mfma_f32_16x16x32_bf16 v[78:81], v[148:151], v[204:207], v[78:81]
	v_mfma_f32_16x16x32_bf16 v[74:77], v[156:159], v[204:207], v[74:77]
	s_setprio 0
	s_setprio 1
	v_mfma_f32_16x16x32_bf16 v[118:121], v[160:163], v[176:179], v[118:121]
	v_mfma_f32_16x16x32_bf16 v[114:117], v[168:171], v[176:179], v[114:117]
	v_mfma_f32_16x16x32_bf16 v[102:105], v[160:163], v[184:187], v[102:105]
	v_mfma_f32_16x16x32_bf16 v[98:101], v[168:171], v[184:187], v[98:101]
	v_mfma_f32_16x16x32_bf16 v[86:89], v[160:163], v[192:195], v[86:89]
	v_mfma_f32_16x16x32_bf16 v[82:85], v[168:171], v[192:195], v[82:85]
	v_mfma_f32_16x16x32_bf16 v[70:73], v[160:163], v[200:203], v[70:73]
	v_mfma_f32_16x16x32_bf16 v[66:69], v[168:171], v[200:203], v[66:69]
	v_mfma_f32_16x16x32_bf16 v[118:121], v[164:167], v[180:183], v[118:121]
	v_mfma_f32_16x16x32_bf16 v[114:117], v[172:175], v[180:183], v[114:117]
	v_mfma_f32_16x16x32_bf16 v[102:105], v[164:167], v[188:191], v[102:105]
	v_mfma_f32_16x16x32_bf16 v[98:101], v[172:175], v[188:191], v[98:101]
	v_mfma_f32_16x16x32_bf16 v[86:89], v[164:167], v[196:199], v[86:89]
	v_mfma_f32_16x16x32_bf16 v[82:85], v[172:175], v[196:199], v[82:85]
	v_mfma_f32_16x16x32_bf16 v[70:73], v[164:167], v[204:207], v[70:73]
	v_mfma_f32_16x16x32_bf16 v[66:69], v[172:175], v[204:207], v[66:69]
	s_barrier
	s_setprio 0
	s_add_i32 s29, s29, s49
	v_lshl_add_u64 v[140:141], s[6:7], 0, v[0:1]
	s_mov_b32 m0, s29
	ds_read_b128 v[176:179], v147 offset:16384
	ds_read_b128 v[180:183], v147 offset:17408
	ds_read_b128 v[184:187], v147 offset:18432
	ds_read_b128 v[188:191], v147 offset:19456
	ds_read_b128 v[192:195], v147 offset:20480
	ds_read_b128 v[196:199], v147 offset:21504
	ds_read_b128 v[200:203], v147 offset:22528
	ds_read_b128 v[204:207], v147 offset:23552
	global_load_lds_dwordx4 v[140:141], off
	s_add_i32 m0, s29, 0x2000
	s_add_u32 s44, s6, 0x80000
	v_lshl_add_u64 v[208:209], s[6:7], 0, v[130:131]
	s_addc_u32 s45, s7, 0
	s_add_i32 s29, s31, s49
	global_load_lds_dwordx4 v[208:209], off
	v_lshl_add_u64 v[210:211], s[44:45], 0, v[0:1]
	s_mov_b32 m0, s29
	v_lshl_add_u64 v[212:213], s[36:37], 0, v[130:131]
	global_load_lds_dwordx4 v[210:211], off
	v_lshl_add_u64 v[210:211], s[44:45], 0, v[130:131]
	s_add_i32 m0, s29, 0x2000
	s_nop 0
	global_load_lds_dwordx4 v[210:211], off
	v_lshl_add_u64 v[210:211], s[36:37], 0, v[0:1]
	s_mov_b32 m0, s50
	s_nop 0
	global_load_lds_dwordx4 v[210:211], off
	s_mov_b32 m0, s51
	s_nop 0
	global_load_lds_dwordx4 v[212:213], off
	s_waitcnt vmcnt(8)
	s_waitcnt lgkmcnt(0)
	s_setprio 1
	s_barrier
; #define PG8_STAGE(bufoff, gbase, voff) do { _Pragma("unroll") for (int _i = 0; _i < 2; ++_i) \
;         __builtin_amdgcn_global_load_lds((const unsigned*)((const char*)(gbase) + (voff)[_i]), (LAS unsigned*)(lds + (bufoff) + ldsw + _i * 8192), 16, 0, 0); } while (0)
; #define PG8_LDA(dst, b, h) do { _Pragma("unroll") for (int m = 0; m < 4; ++m) _Pragma("unroll") for (int k = 0; k < 2; ++k) dst[m][k] = *(const LAS bf16x8*)(lds + PG8_SA(b, h) + aoff + m * 2048 + k * 1024); } while (0)
; #define PG8_LDB(dst, b, h) do { _Pragma("unroll") for (int n = 0; n < 2; ++n) _Pragma("unroll") for (int k = 0; k < 2; ++k) dst[n][k] = *(const LAS bf16x8*)(lds + PG8_SB(b, h) + boff + n * 2048 + k * 1024); } while (0)
; #define PG8_MMA(ai, bj, At, Bt) do { __builtin_amdgcn_s_setprio(1); _Pragma("unroll") for (int m = 0; m < 4; ++m) _Pragma("unroll") for (int n = 0; n < 2; ++n) _Pragma("unroll") for (int k = 0; k < 2; ++k) \
;         acc[ai][bj][m][n] = __builtin_amdgcn_mfma_f32_16x16x32_bf16(Bt[n][k], At[m][k], acc[ai][bj][m][n], 0, 0, 0); __builtin_amdgcn_s_setprio(0); } while (0)
; #define PG8_WAIT_V(n) asm volatile("s_waitcnt vmcnt(" #n ")" ::: "memory")
; #define PG8_WAIT_L(n) asm volatile("s_waitcnt lgkmcnt(" #n ")" ::: "memory")
; #define PG8_BAR __builtin_amdgcn_s_barrier()
; #define PG8_SCHED __builtin_amdgcn_sched_barrier(0)
; template <class Epi, class Sched, bool ALIGN_EPI, bool LAST_FUSED = false, bool PERM = false, bool CARRY = false>
; __device__ __forceinline__ void gemm_phase(LAS unsigned char* lds, const int tid, const int K, const int lda, const int ldb, const Sched& S, const Epi& E) {
;     ...
;             PG8_WAIT_V(8); PG8_WAIT_L(0); PG8_BAR; PG8_MMA(1, 0, At, B0); PG8_MMA(1, 1, At, B1); PG8_BAR; PG8_SCHED;
;             PG8_LDB(B0, 1, 0); PG8_LDB(B1, 1, 1); PG8_SCHED; PG8_LDA(At, 1, 0); PG8_STAGE(PG8_SA(0, 1), a2 + hstepA, voffA);
;             PG8_WAIT_V(8); PG8_WAIT_L(0); PG8_BAR; PG8_MMA(0, 0, At, B0); PG8_MMA(0, 1, At, B1); PG8_BAR; PG8_SCHED;
	v_mfma_f32_16x16x32_bf16 v[62:65], v[136:139], v[176:179], v[62:65]
	v_mfma_f32_16x16x32_bf16 v[58:61], v[152:155], v[176:179], v[58:61]
	v_mfma_f32_16x16x32_bf16 v[46:49], v[136:139], v[184:187], v[46:49]
	v_mfma_f32_16x16x32_bf16 v[42:45], v[152:155], v[184:187], v[42:45]
	v_mfma_f32_16x16x32_bf16 v[30:33], v[136:139], v[192:195], v[30:33]
	v_mfma_f32_16x16x32_bf16 v[26:29], v[152:155], v[192:195], v[26:29]
	v_mfma_f32_16x16x32_bf16 v[14:17], v[136:139], v[200:203], v[14:17]
	v_mfma_f32_16x16x32_bf16 v[10:13], v[152:155], v[200:203], v[10:13]
	v_mfma_f32_16x16x32_bf16 v[62:65], v[148:151], v[180:183], v[62:65]
	v_mfma_f32_16x16x32_bf16 v[58:61], v[156:159], v[180:183], v[58:61]
	v_mfma_f32_16x16x32_bf16 v[46:49], v[148:151], v[188:191], v[46:49]
	v_mfma_f32_16x16x32_bf16 v[42:45], v[156:159], v[188:191], v[42:45]
	v_mfma_f32_16x16x32_bf16 v[30:33], v[148:151], v[196:199], v[30:33]
	v_mfma_f32_16x16x32_bf16 v[26:29], v[156:159], v[196:199], v[26:29]
	v_mfma_f32_16x16x32_bf16 v[14:17], v[148:151], v[204:207], v[14:17]
	v_mfma_f32_16x16x32_bf16 v[10:13], v[156:159], v[204:207], v[10:13]
	s_setprio 0
	s_setprio 1
	v_mfma_f32_16x16x32_bf16 v[54:57], v[160:163], v[176:179], v[54:57]
	v_mfma_f32_16x16x32_bf16 v[50:53], v[168:171], v[176:179], v[50:53]
	v_mfma_f32_16x16x32_bf16 v[38:41], v[160:163], v[184:187], v[38:41]
	v_mfma_f32_16x16x32_bf16 v[34:37], v[168:171], v[184:187], v[34:37]
	v_mfma_f32_16x16x32_bf16 v[22:25], v[160:163], v[192:195], v[22:25]
	v_mfma_f32_16x16x32_bf16 v[18:21], v[168:171], v[192:195], v[18:21]
	v_mfma_f32_16x16x32_bf16 v[6:9], v[160:163], v[200:203], v[6:9]
	v_mfma_f32_16x16x32_bf16 v[2:5], v[168:171], v[200:203], v[2:5]
	v_mfma_f32_16x16x32_bf16 v[54:57], v[164:167], v[180:183], v[54:57]
	v_mfma_f32_16x16x32_bf16 v[50:53], v[172:175], v[180:183], v[50:53]
	v_mfma_f32_16x16x32_bf16 v[38:41], v[164:167], v[188:191], v[38:41]
	v_mfma_f32_16x16x32_bf16 v[34:37], v[172:175], v[188:191], v[34:37]
	v_mfma_f32_16x16x32_bf16 v[22:25], v[164:167], v[196:199], v[22:25]
	v_mfma_f32_16x16x32_bf16 v[18:21], v[172:175], v[196:199], v[18:21]
	v_mfma_f32_16x16x32_bf16 v[6:9], v[164:167], v[204:207], v[6:9]
	v_mfma_f32_16x16x32_bf16 v[2:5], v[172:175], v[204:207], v[2:5]
	s_barrier
	s_setprio 0
	s_add_i32 s29, 0, 0x18000
	s_add_i32 s31, 0, 0x1c000
	v_add_u32_e32 v156, s29, v146
	v_add_u32_e32 v172, s31, v146
	ds_read_b128 v[136:139], v156
	ds_read_b128 v[148:151], v156 offset:1024
	ds_read_b128 v[152:155], v156 offset:2048
	ds_read_b128 v[156:159], v156 offset:3072
	ds_read_b128 v[160:163], v172
	ds_read_b128 v[164:167], v172 offset:1024
	ds_read_b128 v[168:171], v172 offset:2048
	ds_read_b128 v[172:175], v172 offset:3072
	s_add_u32 s36, s36, 0x80000
	s_addc_u32 s37, s37, 0
	s_mov_b32 m0, s52
	v_lshl_add_u64 v[214:215], s[36:37], 0, v[0:1]
	ds_read_b128 v[176:179], v147 offset:32768
	ds_read_b128 v[180:183], v147 offset:33792
	ds_read_b128 v[184:187], v147 offset:34816
	ds_read_b128 v[188:191], v147 offset:35840
	ds_read_b128 v[192:195], v147 offset:36864
	ds_read_b128 v[196:199], v147 offset:37888
	ds_read_b128 v[200:203], v147 offset:38912
	ds_read_b128 v[204:207], v147 offset:39936
	global_load_lds_dwordx4 v[214:215], off
	v_lshl_add_u64 v[214:215], s[36:37], 0, v[130:131]
	s_mov_b32 m0, s53
	s_nop 0
	global_load_lds_dwordx4 v[214:215], off
	s_waitcnt vmcnt(8)
	s_waitcnt lgkmcnt(0)
	s_setprio 1
	s_barrier
	v_mfma_f32_16x16x32_bf16 v[126:129], v[136:139], v[176:179], v[126:129]
	v_mfma_f32_16x16x32_bf16 v[122:125], v[152:155], v[176:179], v[122:125]
	v_mfma_f32_16x16x32_bf16 v[110:113], v[136:139], v[184:187], v[110:113]
	v_mfma_f32_16x16x32_bf16 v[106:109], v[152:155], v[184:187], v[106:109]
	v_mfma_f32_16x16x32_bf16 v[94:97], v[136:139], v[192:195], v[94:97]
	v_mfma_f32_16x16x32_bf16 v[90:93], v[152:155], v[192:195], v[90:93]
	v_mfma_f32_16x16x32_bf16 v[78:81], v[136:139], v[200:203], v[78:81]
	v_mfma_f32_16x16x32_bf16 v[74:77], v[152:155], v[200:203], v[74:77]
	v_mfma_f32_16x16x32_bf16 v[126:129], v[148:151], v[180:183], v[126:129]
	v_mfma_f32_16x16x32_bf16 v[122:125], v[156:159], v[180:183], v[122:125]
	v_mfma_f32_16x16x32_bf16 v[110:113], v[148:151], v[188:191], v[110:113]
	v_mfma_f32_16x16x32_bf16 v[106:109], v[156:159], v[188:191], v[106:109]
	v_mfma_f32_16x16x32_bf16 v[94:97], v[148:151], v[196:199], v[94:97]
	v_mfma_f32_16x16x32_bf16 v[90:93], v[156:159], v[196:199], v[90:93]
	v_mfma_f32_16x16x32_bf16 v[78:81], v[148:151], v[204:207], v[78:81]
	v_mfma_f32_16x16x32_bf16 v[74:77], v[156:159], v[204:207], v[74:77]
	s_setprio 0
	s_setprio 1
	v_mfma_f32_16x16x32_bf16 v[118:121], v[160:163], v[176:179], v[118:121]
	v_mfma_f32_16x16x32_bf16 v[114:117], v[168:171], v[176:179], v[114:117]
	v_mfma_f32_16x16x32_bf16 v[102:105], v[160:163], v[184:187], v[102:105]
	v_mfma_f32_16x16x32_bf16 v[98:101], v[168:171], v[184:187], v[98:101]
	v_mfma_f32_16x16x32_bf16 v[86:89], v[160:163], v[192:195], v[86:89]
	v_mfma_f32_16x16x32_bf16 v[82:85], v[168:171], v[192:195], v[82:85]
	v_mfma_f32_16x16x32_bf16 v[70:73], v[160:163], v[200:203], v[70:73]
	v_mfma_f32_16x16x32_bf16 v[66:69], v[168:171], v[200:203], v[66:69]
	v_mfma_f32_16x16x32_bf16 v[118:121], v[164:167], v[180:183], v[118:121]
	v_mfma_f32_16x16x32_bf16 v[114:117], v[172:175], v[180:183], v[114:117]
	v_mfma_f32_16x16x32_bf16 v[102:105], v[164:167], v[188:191], v[102:105]
	v_mfma_f32_16x16x32_bf16 v[98:101], v[172:175], v[188:191], v[98:101]
	v_mfma_f32_16x16x32_bf16 v[86:89], v[164:167], v[196:199], v[86:89]
	v_mfma_f32_16x16x32_bf16 v[82:85], v[172:175], v[196:199], v[82:85]
	v_mfma_f32_16x16x32_bf16 v[70:73], v[164:167], v[204:207], v[70:73]
	v_mfma_f32_16x16x32_bf16 v[66:69], v[172:175], v[204:207], v[66:69]
	s_barrier
; #define PG8_STAGE(bufoff, gbase, voff) do { _Pragma("unroll") for (int _i = 0; _i < 2; ++_i) \
;         __builtin_amdgcn_global_load_lds((const unsigned*)((const char*)(gbase) + (voff)[_i]), (LAS unsigned*)(lds + (bufoff) + ldsw + _i * 8192), 16, 0, 0); } while (0)
; #define PG8_LDA(dst, b, h) do { _Pragma("unroll") for (int m = 0; m < 4; ++m) _Pragma("unroll") for (int k = 0; k < 2; ++k) dst[m][k] = *(const LAS bf16x8*)(lds + PG8_SA(b, h) + aoff + m * 2048 + k * 1024); } while (0)
; #define PG8_MMA(ai, bj, At, Bt) do { __builtin_amdgcn_s_setprio(1); _Pragma("unroll") for (int m = 0; m < 4; ++m) _Pragma("unroll") for (int n = 0; n < 2; ++n) _Pragma("unroll") for (int k = 0; k < 2; ++k) \
;         acc[ai][bj][m][n] = __builtin_amdgcn_mfma_f32_16x16x32_bf16(Bt[n][k], At[m][k], acc[ai][bj][m][n], 0, 0, 0); __builtin_amdgcn_s_setprio(0); } while (0)
; #define PG8_WAIT_V(n) asm volatile("s_waitcnt vmcnt(" #n ")" ::: "memory")
; #define PG8_WAIT_L(n) asm volatile("s_waitcnt lgkmcnt(" #n ")" ::: "memory")
; #define PG8_BAR __builtin_amdgcn_s_barrier()
; #define PG8_SCHED __builtin_amdgcn_sched_barrier(0)
; template <class Epi, class Sched, bool ALIGN_EPI, bool LAST_FUSED = false, bool PERM = false, bool CARRY = false>
; __device__ __forceinline__ void gemm_phase(LAS unsigned char* lds, const int tid, const int K, const int lda, const int ldb, const Sched& S, const Epi& E) {
;     ...
;             PG8_LDA(At, 1, 1); PG8_STAGE(PG8_SB(1, 0), b3, voffB); PG8_STAGE(PG8_SB(1, 1), b3 + hstepB, voffB); PG8_STAGE(PG8_SA(1, 0), a3, voffA);
;             PG8_WAIT_V(8); PG8_WAIT_L(0); PG8_BAR; PG8_MMA(1, 0, At, B0); PG8_MMA(1, 1, At, B1); PG8_BAR; PG8_SCHED;
;         }
;         if constexpr (ALIGN_EPI) { if (wr == 0) PG8_BAR; }
	s_setprio 0
	s_add_i32 s29, s29, s49
	v_lshl_add_u64 v[140:141], v[140:141], 0, s[68:69]
	s_mov_b32 m0, s29
	ds_read_b128 v[176:179], v147 offset:49152
	ds_read_b128 v[180:183], v147 offset:50176
	ds_read_b128 v[184:187], v147 offset:51200
	ds_read_b128 v[188:191], v147 offset:52224
	ds_read_b128 v[192:195], v147 offset:53248
	ds_read_b128 v[196:199], v147 offset:54272
	ds_read_b128 v[200:203], v147 offset:55296
	ds_read_b128 v[204:207], v147 offset:56320
	global_load_lds_dwordx4 v[140:141], off
	s_add_i32 m0, s29, 0x2000
	s_add_u32 s6, s6, 0x80080
	v_lshl_add_u64 v[140:141], v[208:209], 0, s[68:69]
	s_addc_u32 s7, s7, 0
	s_add_i32 s29, s31, s49
	global_load_lds_dwordx4 v[140:141], off
	v_lshl_add_u64 v[140:141], s[6:7], 0, v[0:1]
	s_mov_b32 m0, s29
	s_nop 0
	global_load_lds_dwordx4 v[140:141], off
	v_lshl_add_u64 v[140:141], s[6:7], 0, v[130:131]
	s_add_i32 m0, s29, 0x2000
	s_nop 0
	global_load_lds_dwordx4 v[140:141], off
	v_lshl_add_u64 v[140:141], v[210:211], 0, s[68:69]
	s_mov_b32 m0, s55
	s_nop 0
	global_load_lds_dwordx4 v[140:141], off
	v_lshl_add_u64 v[140:141], v[212:213], 0, s[68:69]
	s_mov_b32 m0, s56
	s_nop 0
	global_load_lds_dwordx4 v[140:141], off
	s_waitcnt vmcnt(8)
	s_waitcnt lgkmcnt(0)
	s_setprio 1
	s_barrier
	v_mfma_f32_16x16x32_bf16 v[62:65], v[136:139], v[176:179], v[62:65]
	v_mfma_f32_16x16x32_bf16 v[58:61], v[152:155], v[176:179], v[58:61]
	v_mfma_f32_16x16x32_bf16 v[46:49], v[136:139], v[184:187], v[46:49]
	v_mfma_f32_16x16x32_bf16 v[42:45], v[152:155], v[184:187], v[42:45]
	v_mfma_f32_16x16x32_bf16 v[30:33], v[136:139], v[192:195], v[30:33]
	v_mfma_f32_16x16x32_bf16 v[26:29], v[152:155], v[192:195], v[26:29]
	v_mfma_f32_16x16x32_bf16 v[14:17], v[136:139], v[200:203], v[14:17]
	v_mfma_f32_16x16x32_bf16 v[10:13], v[152:155], v[200:203], v[10:13]
	v_mfma_f32_16x16x32_bf16 v[62:65], v[148:151], v[180:183], v[62:65]
	v_mfma_f32_16x16x32_bf16 v[58:61], v[156:159], v[180:183], v[58:61]
	v_mfma_f32_16x16x32_bf16 v[46:49], v[148:151], v[188:191], v[46:49]
	v_mfma_f32_16x16x32_bf16 v[42:45], v[156:159], v[188:191], v[42:45]
	v_mfma_f32_16x16x32_bf16 v[30:33], v[148:151], v[196:199], v[30:33]
	v_mfma_f32_16x16x32_bf16 v[26:29], v[156:159], v[196:199], v[26:29]
	v_mfma_f32_16x16x32_bf16 v[14:17], v[148:151], v[204:207], v[14:17]
	v_mfma_f32_16x16x32_bf16 v[10:13], v[156:159], v[204:207], v[10:13]
	s_setprio 0
	s_setprio 1
	v_mfma_f32_16x16x32_bf16 v[54:57], v[160:163], v[176:179], v[54:57]
	v_mfma_f32_16x16x32_bf16 v[50:53], v[168:171], v[176:179], v[50:53]
	v_mfma_f32_16x16x32_bf16 v[38:41], v[160:163], v[184:187], v[38:41]
	v_mfma_f32_16x16x32_bf16 v[34:37], v[168:171], v[184:187], v[34:37]
	v_mfma_f32_16x16x32_bf16 v[22:25], v[160:163], v[192:195], v[22:25]
	v_mfma_f32_16x16x32_bf16 v[18:21], v[168:171], v[192:195], v[18:21]
	v_mfma_f32_16x16x32_bf16 v[6:9], v[160:163], v[200:203], v[6:9]
	v_mfma_f32_16x16x32_bf16 v[2:5], v[168:171], v[200:203], v[2:5]
	v_mfma_f32_16x16x32_bf16 v[54:57], v[164:167], v[180:183], v[54:57]
	v_mfma_f32_16x16x32_bf16 v[50:53], v[172:175], v[180:183], v[50:53]
	v_mfma_f32_16x16x32_bf16 v[38:41], v[164:167], v[188:191], v[38:41]
	v_mfma_f32_16x16x32_bf16 v[34:37], v[172:175], v[188:191], v[34:37]
	v_mfma_f32_16x16x32_bf16 v[22:25], v[164:167], v[196:199], v[22:25]
	v_mfma_f32_16x16x32_bf16 v[18:21], v[172:175], v[196:199], v[18:21]
	v_mfma_f32_16x16x32_bf16 v[6:9], v[164:167], v[204:207], v[6:9]
	v_mfma_f32_16x16x32_bf16 v[2:5], v[172:175], v[204:207], v[2:5]
	s_barrier
	s_setprio 0
	s_add_i32 s28, s28, 2
	s_add_u32 s4, s4, 0x100
	s_addc_u32 s5, s5, 0
	s_add_u32 s22, s22, 0x100
	s_addc_u32 s23, s23, 0
	s_cmp_gt_u32 s28, 29
	s_cbranch_scc0 .LBB0_838
	s_and_b64 vcc, exec, s[26:27]
	s_cbranch_vccz .LBB0_841
	s_barrier

; #define PG8_STAGE(bufoff, gbase, voff) do { _Pragma("unroll") for (int _i = 0; _i < 2; ++_i) \
;         __builtin_amdgcn_global_load_lds((const unsigned*)((const char*)(gbase) + (voff)[_i]), (LAS unsigned*)(lds + (bufoff) + ldsw + _i * 8192), 16, 0, 0); } while (0)
; #define PG8_LDA(dst, b, h) do { _Pragma("unroll") for (int m = 0; m < 4; ++m) _Pragma("unroll") for (int k = 0; k < 2; ++k) dst[m][k] = *(const LAS bf16x8*)(lds + PG8_SA(b, h) + aoff + m * 2048 + k * 1024); } while (0)
; #define PG8_LDB(dst, b, h) do { _Pragma("unroll") for (int n = 0; n < 2; ++n) _Pragma("unroll") for (int k = 0; k < 2; ++k) dst[n][k] = *(const LAS bf16x8*)(lds + PG8_SB(b, h) + boff + n * 2048 + k * 1024); } while (0)
; #define PG8_MMA(ai, bj, At, Bt) do { __builtin_amdgcn_s_setprio(1); _Pragma("unroll") for (int m = 0; m < 4; ++m) _Pragma("unroll") for (int n = 0; n < 2; ++n) _Pragma("unroll") for (int k = 0; k < 2; ++k) \
;         acc[ai][bj][m][n] = __builtin_amdgcn_mfma_f32_16x16x32_bf16(Bt[n][k], At[m][k], acc[ai][bj][m][n], 0, 0, 0); __builtin_amdgcn_s_setprio(0); } while (0)
; #define PG8_WAIT_V(n) asm volatile("s_waitcnt vmcnt(" #n ")" ::: "memory")
; #define PG8_WAIT_L(n) asm volatile("s_waitcnt lgkmcnt(" #n ")" ::: "memory")
; template <class Epi, class Sched, bool ALIGN_EPI, bool LAST_FUSED = false, bool PERM = false, bool CARRY = false>
; __device__ __forceinline__ void gemm_phase(LAS unsigned char* lds, const int tid, const int K, const int lda, const int ldb, const Sched& S, const Epi& E) {
;     ...
;         for (int t = 0; t < nt; t += 2) {
;             const bool last = (t == nt - 2);
;             const char* a1 = cA + (size_t)(t + 1) * kstep;
;             const char* a2 = last ? nA : cA + (size_t)(t + 2) * kstep; const char* b2 = last ? nB : cB + (size_t)(t + 2) * kstep;
;             const char* a3 = a2 + kstep; const char* b3 = b2 + kstep;
;             PG8_LDB(B0, 0, 0); PG8_LDB(B1, 0, 1); PG8_SCHED; PG8_LDA(At, 0, 0); PG8_STAGE(PG8_SA(1, 1), a1 + hstepA, voffA);
;             PG8_WAIT_V(8); PG8_WAIT_L(0); PG8_BAR; PG8_MMA(0, 0, At, B0); PG8_MMA(0, 1, At, B1); PG8_BAR; PG8_SCHED;
;             PG8_LDA(At, 0, 1); PG8_STAGE(PG8_SB(0, 0), b2, voffB); PG8_STAGE(PG8_SB(0, 1), b2 + hstepB, voffB); PG8_STAGE(PG8_SA(0, 0), a2, voffA);
;             PG8_WAIT_V(8); PG8_WAIT_L(0); PG8_BAR; PG8_MMA(1, 0, At, B0); PG8_MMA(1, 1, At, B1); PG8_BAR; PG8_SCHED;
.LBB0_1077:
	s_add_u32 s23, s26, 0xfff80080
	s_addc_u32 s28, s27, -1
	s_add_i32 s29, 0, 0x10000
	s_cmp_eq_u32 s15, 28
	s_cselect_b32 s37, s17, s28
	s_cselect_b32 s36, s16, s23
	s_cselect_b32 s31, s19, s13
	s_cselect_b32 s30, s18, s5
	s_add_i32 s23, 0, 0x14000
	v_add_u32_e32 v152, s29, v142
	v_add_u32_e32 v168, s23, v142
	ds_read_b128 v[136:139], v152
	ds_read_b128 v[144:147], v152 offset:1024
	ds_read_b128 v[148:151], v152 offset:2048
	ds_read_b128 v[152:155], v152 offset:3072
	ds_read_b128 v[156:159], v168
	ds_read_b128 v[160:163], v168 offset:1024
	ds_read_b128 v[164:167], v168 offset:2048
	ds_read_b128 v[168:171], v168 offset:3072
	v_lshl_add_u64 v[204:205], s[26:27], 0, v[132:133]
	s_add_i32 m0, s46, 0xc000
	ds_read_b128 v[172:175], v143
	ds_read_b128 v[176:179], v143 offset:1024
	ds_read_b128 v[180:183], v143 offset:2048
	ds_read_b128 v[184:187], v143 offset:3072
	ds_read_b128 v[188:191], v143 offset:4096
	ds_read_b128 v[192:195], v143 offset:5120
	ds_read_b128 v[196:199], v143 offset:6144
	ds_read_b128 v[200:203], v143 offset:7168
	global_load_lds_dwordx4 v[204:205], off
	v_lshl_add_u64 v[204:205], s[26:27], 0, v[134:135]
	s_add_i32 m0, s46, 0xe000
	s_nop 0
	global_load_lds_dwordx4 v[204:205], off
	s_waitcnt vmcnt(8)
	s_waitcnt lgkmcnt(0)
	s_setprio 1
	s_barrier
	v_mfma_f32_16x16x32_bf16 v[126:129], v[136:139], v[172:175], v[126:129]
	v_mfma_f32_16x16x32_bf16 v[122:125], v[148:151], v[172:175], v[122:125]
	v_mfma_f32_16x16x32_bf16 v[110:113], v[136:139], v[180:183], v[110:113]
	v_mfma_f32_16x16x32_bf16 v[106:109], v[148:151], v[180:183], v[106:109]
	v_mfma_f32_16x16x32_bf16 v[94:97], v[136:139], v[188:191], v[94:97]
	v_mfma_f32_16x16x32_bf16 v[90:93], v[148:151], v[188:191], v[90:93]
	v_mfma_f32_16x16x32_bf16 v[78:81], v[136:139], v[196:199], v[78:81]
	v_mfma_f32_16x16x32_bf16 v[74:77], v[148:151], v[196:199], v[74:77]
	v_mfma_f32_16x16x32_bf16 v[126:129], v[144:147], v[176:179], v[126:129]
	v_mfma_f32_16x16x32_bf16 v[122:125], v[152:155], v[176:179], v[122:125]
	v_mfma_f32_16x16x32_bf16 v[110:113], v[144:147], v[184:187], v[110:113]
	v_mfma_f32_16x16x32_bf16 v[106:109], v[152:155], v[184:187], v[106:109]
	v_mfma_f32_16x16x32_bf16 v[94:97], v[144:147], v[192:195], v[94:97]
	v_mfma_f32_16x16x32_bf16 v[90:93], v[152:155], v[192:195], v[90:93]
	v_mfma_f32_16x16x32_bf16 v[78:81], v[144:147], v[200:203], v[78:81]
	v_mfma_f32_16x16x32_bf16 v[74:77], v[152:155], v[200:203], v[74:77]
	s_setprio 0
	s_setprio 1
	v_mfma_f32_16x16x32_bf16 v[118:121], v[156:159], v[172:175], v[118:121]
	v_mfma_f32_16x16x32_bf16 v[114:117], v[164:167], v[172:175], v[114:117]
	v_mfma_f32_16x16x32_bf16 v[102:105], v[156:159], v[180:183], v[102:105]
	v_mfma_f32_16x16x32_bf16 v[98:101], v[164:167], v[180:183], v[98:101]
	v_mfma_f32_16x16x32_bf16 v[86:89], v[156:159], v[188:191], v[86:89]
	v_mfma_f32_16x16x32_bf16 v[82:85], v[164:167], v[188:191], v[82:85]
	v_mfma_f32_16x16x32_bf16 v[70:73], v[156:159], v[196:199], v[70:73]
	v_mfma_f32_16x16x32_bf16 v[66:69], v[164:167], v[196:199], v[66:69]
	v_mfma_f32_16x16x32_bf16 v[118:121], v[160:163], v[176:179], v[118:121]
	v_mfma_f32_16x16x32_bf16 v[114:117], v[168:171], v[176:179], v[114:117]
	v_mfma_f32_16x16x32_bf16 v[102:105], v[160:163], v[184:187], v[102:105]
	v_mfma_f32_16x16x32_bf16 v[98:101], v[168:171], v[184:187], v[98:101]
	v_mfma_f32_16x16x32_bf16 v[86:89], v[160:163], v[192:195], v[86:89]
	v_mfma_f32_16x16x32_bf16 v[82:85], v[168:171], v[192:195], v[82:85]
	v_mfma_f32_16x16x32_bf16 v[70:73], v[160:163], v[200:203], v[70:73]
	v_mfma_f32_16x16x32_bf16 v[66:69], v[168:171], v[200:203], v[66:69]
	s_barrier
	s_setprio 0
	s_add_i32 s28, s29, s43
	v_lshl_add_u64 v[204:205], s[30:31], 0, v[0:1]
	s_mov_b32 m0, s28
	ds_read_b128 v[172:175], v143 offset:16384
	ds_read_b128 v[176:179], v143 offset:17408
	ds_read_b128 v[180:183], v143 offset:18432
	ds_read_b128 v[184:187], v143 offset:19456
	ds_read_b128 v[188:191], v143 offset:20480
	ds_read_b128 v[192:195], v143 offset:21504
	ds_read_b128 v[196:199], v143 offset:22528
	ds_read_b128 v[200:203], v143 offset:23552
	global_load_lds_dwordx4 v[204:205], off
	s_add_i32 m0, s28, 0x2000
	s_add_u32 s28, s30, 0x80000
	v_lshl_add_u64 v[206:207], s[30:31], 0, v[130:131]
	s_addc_u32 s29, s31, 0
	s_add_i32 s23, s23, s43
	global_load_lds_dwordx4 v[206:207], off
	v_lshl_add_u64 v[208:209], s[28:29], 0, v[0:1]
	s_mov_b32 m0, s23
	v_lshl_add_u64 v[210:211], s[36:37], 0, v[130:131]
	global_load_lds_dwordx4 v[208:209], off
	v_lshl_add_u64 v[208:209], s[28:29], 0, v[130:131]
	s_add_i32 m0, s23, 0x2000
	s_nop 0
	global_load_lds_dwordx4 v[208:209], off
	v_lshl_add_u64 v[208:209], s[36:37], 0, v[0:1]
	s_mov_b32 m0, s46
	s_nop 0
	global_load_lds_dwordx4 v[208:209], off
	s_mov_b32 m0, s47
	s_nop 0
	global_load_lds_dwordx4 v[210:211], off
	s_waitcnt vmcnt(8)
	s_waitcnt lgkmcnt(0)
	s_setprio 1
	s_barrier
; #define PG8_STAGE(bufoff, gbase, voff) do { _Pragma("unroll") for (int _i = 0; _i < 2; ++_i) \
;         __builtin_amdgcn_global_load_lds((const unsigned*)((const char*)(gbase) + (voff)[_i]), (LAS unsigned*)(lds + (bufoff) + ldsw + _i * 8192), 16, 0, 0); } while (0)
; #define PG8_LDA(dst, b, h) do { _Pragma("unroll") for (int m = 0; m < 4; ++m) _Pragma("unroll") for (int k = 0; k < 2; ++k) dst[m][k] = *(const LAS bf16x8*)(lds + PG8_SA(b, h) + aoff + m * 2048 + k * 1024); } while (0)
; #define PG8_LDB(dst, b, h) do { _Pragma("unroll") for (int n = 0; n < 2; ++n) _Pragma("unroll") for (int k = 0; k < 2; ++k) dst[n][k] = *(const LAS bf16x8*)(lds + PG8_SB(b, h) + boff + n * 2048 + k * 1024); } while (0)
; #define PG8_MMA(ai, bj, At, Bt) do { __builtin_amdgcn_s_setprio(1); _Pragma("unroll") for (int m = 0; m < 4; ++m) _Pragma("unroll") for (int n = 0; n < 2; ++n) _Pragma("unroll") for (int k = 0; k < 2; ++k) \
;         acc[ai][bj][m][n] = __builtin_amdgcn_mfma_f32_16x16x32_bf16(Bt[n][k], At[m][k], acc[ai][bj][m][n], 0, 0, 0); __builtin_amdgcn_s_setprio(0); } while (0)
; #define PG8_WAIT_V(n) asm volatile("s_waitcnt vmcnt(" #n ")" ::: "memory")
; #define PG8_WAIT_L(n) asm volatile("s_waitcnt lgkmcnt(" #n ")" ::: "memory")
; #define PG8_BAR __builtin_amdgcn_s_barrier()
; #define PG8_SCHED __builtin_amdgcn_sched_barrier(0)
; template <class Epi, class Sched, bool ALIGN_EPI, bool LAST_FUSED = false, bool PERM = false, bool CARRY = false>
; __device__ __forceinline__ void gemm_phase(LAS unsigned char* lds, const int tid, const int K, const int lda, const int ldb, const Sched& S, const Epi& E) {
;     ...
;             PG8_WAIT_V(8); PG8_WAIT_L(0); PG8_BAR; PG8_MMA(1, 0, At, B0); PG8_MMA(1, 1, At, B1); PG8_BAR; PG8_SCHED;
;             PG8_LDB(B0, 1, 0); PG8_LDB(B1, 1, 1); PG8_SCHED; PG8_LDA(At, 1, 0); PG8_STAGE(PG8_SA(0, 1), a2 + hstepA, voffA);
;             PG8_WAIT_V(8); PG8_WAIT_L(0); PG8_BAR; PG8_MMA(0, 0, At, B0); PG8_MMA(0, 1, At, B1); PG8_BAR; PG8_SCHED;
;             PG8_LDA(At, 1, 1); PG8_STAGE(PG8_SB(1, 0), b3, voffB); PG8_STAGE(PG8_SB(1, 1), b3 + hstepB, voffB); PG8_STAGE(PG8_SA(1, 0), a3, voffA);
;             PG8_WAIT_V(8); PG8_WAIT_L(0); PG8_BAR; PG8_MMA(1, 0, At, B0); PG8_MMA(1, 1, At, B1); PG8_BAR; PG8_SCHED;
	v_mfma_f32_16x16x32_bf16 v[62:65], v[136:139], v[172:175], v[62:65]
	v_mfma_f32_16x16x32_bf16 v[58:61], v[148:151], v[172:175], v[58:61]
	v_mfma_f32_16x16x32_bf16 v[46:49], v[136:139], v[180:183], v[46:49]
	v_mfma_f32_16x16x32_bf16 v[42:45], v[148:151], v[180:183], v[42:45]
	v_mfma_f32_16x16x32_bf16 v[30:33], v[136:139], v[188:191], v[30:33]
	v_mfma_f32_16x16x32_bf16 v[26:29], v[148:151], v[188:191], v[26:29]
	v_mfma_f32_16x16x32_bf16 v[14:17], v[136:139], v[196:199], v[14:17]
	v_mfma_f32_16x16x32_bf16 v[10:13], v[148:151], v[196:199], v[10:13]
	v_mfma_f32_16x16x32_bf16 v[62:65], v[144:147], v[176:179], v[62:65]
	v_mfma_f32_16x16x32_bf16 v[58:61], v[152:155], v[176:179], v[58:61]
	v_mfma_f32_16x16x32_bf16 v[46:49], v[144:147], v[184:187], v[46:49]
	v_mfma_f32_16x16x32_bf16 v[42:45], v[152:155], v[184:187], v[42:45]
	v_mfma_f32_16x16x32_bf16 v[30:33], v[144:147], v[192:195], v[30:33]
	v_mfma_f32_16x16x32_bf16 v[26:29], v[152:155], v[192:195], v[26:29]
	v_mfma_f32_16x16x32_bf16 v[14:17], v[144:147], v[200:203], v[14:17]
	v_mfma_f32_16x16x32_bf16 v[10:13], v[152:155], v[200:203], v[10:13]
	s_setprio 0
	s_setprio 1
	v_mfma_f32_16x16x32_bf16 v[54:57], v[156:159], v[172:175], v[54:57]
	v_mfma_f32_16x16x32_bf16 v[50:53], v[164:167], v[172:175], v[50:53]
	v_mfma_f32_16x16x32_bf16 v[38:41], v[156:159], v[180:183], v[38:41]
	v_mfma_f32_16x16x32_bf16 v[34:37], v[164:167], v[180:183], v[34:37]
	v_mfma_f32_16x16x32_bf16 v[22:25], v[156:159], v[188:191], v[22:25]
	v_mfma_f32_16x16x32_bf16 v[18:21], v[164:167], v[188:191], v[18:21]
	v_mfma_f32_16x16x32_bf16 v[6:9], v[156:159], v[196:199], v[6:9]
	v_mfma_f32_16x16x32_bf16 v[2:5], v[164:167], v[196:199], v[2:5]
	v_mfma_f32_16x16x32_bf16 v[54:57], v[160:163], v[176:179], v[54:57]
	v_mfma_f32_16x16x32_bf16 v[50:53], v[168:171], v[176:179], v[50:53]
	v_mfma_f32_16x16x32_bf16 v[38:41], v[160:163], v[184:187], v[38:41]
	v_mfma_f32_16x16x32_bf16 v[34:37], v[168:171], v[184:187], v[34:37]
	v_mfma_f32_16x16x32_bf16 v[22:25], v[160:163], v[192:195], v[22:25]
	v_mfma_f32_16x16x32_bf16 v[18:21], v[168:171], v[192:195], v[18:21]
	v_mfma_f32_16x16x32_bf16 v[6:9], v[160:163], v[200:203], v[6:9]
	v_mfma_f32_16x16x32_bf16 v[2:5], v[168:171], v[200:203], v[2:5]
	s_barrier
	s_setprio 0
	s_add_i32 s23, 0, 0x18000
	s_add_i32 s35, 0, 0x1c000
	v_add_u32_e32 v152, s23, v142
	v_add_u32_e32 v168, s35, v142
	ds_read_b128 v[136:139], v152
	ds_read_b128 v[144:147], v152 offset:1024
	ds_read_b128 v[148:151], v152 offset:2048
	ds_read_b128 v[152:155], v152 offset:3072
	ds_read_b128 v[156:159], v168
	ds_read_b128 v[160:163], v168 offset:1024
	ds_read_b128 v[164:167], v168 offset:2048
	ds_read_b128 v[168:171], v168 offset:3072
	s_add_u32 s28, s36, 0x80000
	s_addc_u32 s29, s37, 0
	s_mov_b32 m0, s48
	v_lshl_add_u64 v[212:213], s[28:29], 0, v[0:1]
	ds_read_b128 v[172:175], v143 offset:32768
	ds_read_b128 v[176:179], v143 offset:33792
	ds_read_b128 v[180:183], v143 offset:34816
	ds_read_b128 v[184:187], v143 offset:35840
	ds_read_b128 v[188:191], v143 offset:36864
	ds_read_b128 v[192:195], v143 offset:37888
	ds_read_b128 v[196:199], v143 offset:38912
	ds_read_b128 v[200:203], v143 offset:39936
	global_load_lds_dwordx4 v[212:213], off
	v_lshl_add_u64 v[212:213], s[28:29], 0, v[130:131]
	s_mov_b32 m0, s49
	s_nop 0
	global_load_lds_dwordx4 v[212:213], off
	s_waitcnt vmcnt(8)
	s_waitcnt lgkmcnt(0)
	s_setprio 1
	s_barrier
	v_mfma_f32_16x16x32_bf16 v[126:129], v[136:139], v[172:175], v[126:129]
	v_mfma_f32_16x16x32_bf16 v[122:125], v[148:151], v[172:175], v[122:125]
	v_mfma_f32_16x16x32_bf16 v[110:113], v[136:139], v[180:183], v[110:113]
	v_mfma_f32_16x16x32_bf16 v[106:109], v[148:151], v[180:183], v[106:109]
	v_mfma_f32_16x16x32_bf16 v[94:97], v[136:139], v[188:191], v[94:97]
	v_mfma_f32_16x16x32_bf16 v[90:93], v[148:151], v[188:191], v[90:93]
	v_mfma_f32_16x16x32_bf16 v[78:81], v[136:139], v[196:199], v[78:81]
	v_mfma_f32_16x16x32_bf16 v[74:77], v[148:151], v[196:199], v[74:77]
	v_mfma_f32_16x16x32_bf16 v[126:129], v[144:147], v[176:179], v[126:129]
	v_mfma_f32_16x16x32_bf16 v[122:125], v[152:155], v[176:179], v[122:125]
	v_mfma_f32_16x16x32_bf16 v[110:113], v[144:147], v[184:187], v[110:113]
	v_mfma_f32_16x16x32_bf16 v[106:109], v[152:155], v[184:187], v[106:109]
	v_mfma_f32_16x16x32_bf16 v[94:97], v[144:147], v[192:195], v[94:97]
	v_mfma_f32_16x16x32_bf16 v[90:93], v[152:155], v[192:195], v[90:93]
	v_mfma_f32_16x16x32_bf16 v[78:81], v[144:147], v[200:203], v[78:81]
	v_mfma_f32_16x16x32_bf16 v[74:77], v[152:155], v[200:203], v[74:77]
	s_setprio 0
	s_setprio 1
	v_mfma_f32_16x16x32_bf16 v[118:121], v[156:159], v[172:175], v[118:121]
	v_mfma_f32_16x16x32_bf16 v[114:117], v[164:167], v[172:175], v[114:117]
	v_mfma_f32_16x16x32_bf16 v[102:105], v[156:159], v[180:183], v[102:105]
	v_mfma_f32_16x16x32_bf16 v[98:101], v[164:167], v[180:183], v[98:101]
	v_mfma_f32_16x16x32_bf16 v[86:89], v[156:159], v[188:191], v[86:89]
	v_mfma_f32_16x16x32_bf16 v[82:85], v[164:167], v[188:191], v[82:85]
	v_mfma_f32_16x16x32_bf16 v[70:73], v[156:159], v[196:199], v[70:73]
	v_mfma_f32_16x16x32_bf16 v[66:69], v[164:167], v[196:199], v[66:69]
	v_mfma_f32_16x16x32_bf16 v[118:121], v[160:163], v[176:179], v[118:121]
	v_mfma_f32_16x16x32_bf16 v[114:117], v[168:171], v[176:179], v[114:117]
	v_mfma_f32_16x16x32_bf16 v[102:105], v[160:163], v[184:187], v[102:105]
	v_mfma_f32_16x16x32_bf16 v[98:101], v[168:171], v[184:187], v[98:101]
	v_mfma_f32_16x16x32_bf16 v[86:89], v[160:163], v[192:195], v[86:89]
	v_mfma_f32_16x16x32_bf16 v[82:85], v[168:171], v[192:195], v[82:85]
	v_mfma_f32_16x16x32_bf16 v[70:73], v[160:163], v[200:203], v[70:73]
	v_mfma_f32_16x16x32_bf16 v[66:69], v[168:171], v[200:203], v[66:69]
	s_barrier
; #define PG8_STAGE(bufoff, gbase, voff) do { _Pragma("unroll") for (int _i = 0; _i < 2; ++_i) \
;         __builtin_amdgcn_global_load_lds((const unsigned*)((const char*)(gbase) + (voff)[_i]), (LAS unsigned*)(lds + (bufoff) + ldsw + _i * 8192), 16, 0, 0); } while (0)
; #define PG8_LDA(dst, b, h) do { _Pragma("unroll") for (int m = 0; m < 4; ++m) _Pragma("unroll") for (int k = 0; k < 2; ++k) dst[m][k] = *(const LAS bf16x8*)(lds + PG8_SA(b, h) + aoff + m * 2048 + k * 1024); } while (0)
; #define PG8_MMA(ai, bj, At, Bt) do { __builtin_amdgcn_s_setprio(1); _Pragma("unroll") for (int m = 0; m < 4; ++m) _Pragma("unroll") for (int n = 0; n < 2; ++n) _Pragma("unroll") for (int k = 0; k < 2; ++k) \
;         acc[ai][bj][m][n] = __builtin_amdgcn_mfma_f32_16x16x32_bf16(Bt[n][k], At[m][k], acc[ai][bj][m][n], 0, 0, 0); __builtin_amdgcn_s_setprio(0); } while (0)
; #define PG8_WAIT_V(n) asm volatile("s_waitcnt vmcnt(" #n ")" ::: "memory")
; #define PG8_WAIT_L(n) asm volatile("s_waitcnt lgkmcnt(" #n ")" ::: "memory")
; #define PG8_BAR __builtin_amdgcn_s_barrier()
; #define PG8_SCHED __builtin_amdgcn_sched_barrier(0)
; template <class Epi, class Sched, bool ALIGN_EPI, bool LAST_FUSED = false, bool PERM = false, bool CARRY = false>
; __device__ __forceinline__ void gemm_phase(LAS unsigned char* lds, const int tid, const int K, const int lda, const int ldb, const Sched& S, const Epi& E) {
;     ...
;             PG8_LDA(At, 1, 1); PG8_STAGE(PG8_SB(1, 0), b3, voffB); PG8_STAGE(PG8_SB(1, 1), b3 + hstepB, voffB); PG8_STAGE(PG8_SA(1, 0), a3, voffA);
;             PG8_WAIT_V(8); PG8_WAIT_L(0); PG8_BAR; PG8_MMA(1, 0, At, B0); PG8_MMA(1, 1, At, B1); PG8_BAR; PG8_SCHED;
;         }
;         if constexpr (ALIGN_EPI) { if (wr == 0) PG8_BAR; }
	s_setprio 0
	s_add_i32 s23, s23, s43
	v_lshl_add_u64 v[204:205], v[204:205], 0, s[68:69]
	s_mov_b32 m0, s23
	ds_read_b128 v[172:175], v143 offset:49152
	ds_read_b128 v[176:179], v143 offset:50176
	ds_read_b128 v[180:183], v143 offset:51200
	ds_read_b128 v[184:187], v143 offset:52224
	ds_read_b128 v[188:191], v143 offset:53248
	ds_read_b128 v[192:195], v143 offset:54272
	ds_read_b128 v[196:199], v143 offset:55296
	ds_read_b128 v[200:203], v143 offset:56320
	global_load_lds_dwordx4 v[204:205], off
	s_add_i32 m0, s23, 0x2000
	s_add_u32 s28, s30, 0x80080
	v_lshl_add_u64 v[204:205], v[206:207], 0, s[68:69]
	s_addc_u32 s29, s31, 0
	s_add_i32 s23, s35, s43
	global_load_lds_dwordx4 v[204:205], off
	v_lshl_add_u64 v[204:205], s[28:29], 0, v[0:1]
	s_mov_b32 m0, s23
	s_nop 0
	global_load_lds_dwordx4 v[204:205], off
	v_lshl_add_u64 v[204:205], s[28:29], 0, v[130:131]
	s_add_i32 m0, s23, 0x2000
	s_nop 0
	global_load_lds_dwordx4 v[204:205], off
	v_lshl_add_u64 v[204:205], v[208:209], 0, s[68:69]
	s_mov_b32 m0, s51
	s_nop 0
	global_load_lds_dwordx4 v[204:205], off
	v_lshl_add_u64 v[204:205], v[210:211], 0, s[68:69]
	s_mov_b32 m0, s52
	s_nop 0
	global_load_lds_dwordx4 v[204:205], off
	s_waitcnt vmcnt(8)
	s_waitcnt lgkmcnt(0)
	s_setprio 1
	s_barrier
	v_mfma_f32_16x16x32_bf16 v[62:65], v[136:139], v[172:175], v[62:65]
	v_mfma_f32_16x16x32_bf16 v[58:61], v[148:151], v[172:175], v[58:61]
	v_mfma_f32_16x16x32_bf16 v[46:49], v[136:139], v[180:183], v[46:49]
	v_mfma_f32_16x16x32_bf16 v[42:45], v[148:151], v[180:183], v[42:45]
	v_mfma_f32_16x16x32_bf16 v[30:33], v[136:139], v[188:191], v[30:33]
	v_mfma_f32_16x16x32_bf16 v[26:29], v[148:151], v[188:191], v[26:29]
	v_mfma_f32_16x16x32_bf16 v[14:17], v[136:139], v[196:199], v[14:17]
	v_mfma_f32_16x16x32_bf16 v[10:13], v[148:151], v[196:199], v[10:13]
	v_mfma_f32_16x16x32_bf16 v[62:65], v[144:147], v[176:179], v[62:65]
	v_mfma_f32_16x16x32_bf16 v[58:61], v[152:155], v[176:179], v[58:61]
	v_mfma_f32_16x16x32_bf16 v[46:49], v[144:147], v[184:187], v[46:49]
	v_mfma_f32_16x16x32_bf16 v[42:45], v[152:155], v[184:187], v[42:45]
	v_mfma_f32_16x16x32_bf16 v[30:33], v[144:147], v[192:195], v[30:33]
	v_mfma_f32_16x16x32_bf16 v[26:29], v[152:155], v[192:195], v[26:29]
	v_mfma_f32_16x16x32_bf16 v[14:17], v[144:147], v[200:203], v[14:17]
	v_mfma_f32_16x16x32_bf16 v[10:13], v[152:155], v[200:203], v[10:13]
	s_setprio 0
	s_setprio 1
	v_mfma_f32_16x16x32_bf16 v[54:57], v[156:159], v[172:175], v[54:57]
	v_mfma_f32_16x16x32_bf16 v[50:53], v[164:167], v[172:175], v[50:53]
	v_mfma_f32_16x16x32_bf16 v[38:41], v[156:159], v[180:183], v[38:41]
	v_mfma_f32_16x16x32_bf16 v[34:37], v[164:167], v[180:183], v[34:37]
	v_mfma_f32_16x16x32_bf16 v[22:25], v[156:159], v[188:191], v[22:25]
	v_mfma_f32_16x16x32_bf16 v[18:21], v[164:167], v[188:191], v[18:21]
	v_mfma_f32_16x16x32_bf16 v[6:9], v[156:159], v[196:199], v[6:9]
	v_mfma_f32_16x16x32_bf16 v[2:5], v[164:167], v[196:199], v[2:5]
	v_mfma_f32_16x16x32_bf16 v[54:57], v[160:163], v[176:179], v[54:57]
	v_mfma_f32_16x16x32_bf16 v[50:53], v[168:171], v[176:179], v[50:53]
	v_mfma_f32_16x16x32_bf16 v[38:41], v[160:163], v[184:187], v[38:41]
	v_mfma_f32_16x16x32_bf16 v[34:37], v[168:171], v[184:187], v[34:37]
	v_mfma_f32_16x16x32_bf16 v[22:25], v[160:163], v[192:195], v[22:25]
	v_mfma_f32_16x16x32_bf16 v[18:21], v[168:171], v[192:195], v[18:21]
	v_mfma_f32_16x16x32_bf16 v[6:9], v[160:163], v[200:203], v[6:9]
	v_mfma_f32_16x16x32_bf16 v[2:5], v[168:171], v[200:203], v[2:5]
	s_barrier
	s_setprio 0
	s_add_i32 s15, s15, 2
	s_add_u32 s26, s26, 0x100
	s_addc_u32 s27, s27, 0
	s_add_u32 s5, s5, 0x100
	s_addc_u32 s13, s13, 0
	s_cmp_gt_u32 s15, 29
	s_cbranch_scc0 .LBB0_1077
	s_and_b64 vcc, exec, s[10:11]
	s_cbranch_vccz .LBB0_1080
	s_barrier

; #define PG8_STAGE(bufoff, gbase, voff) do { _Pragma("unroll") for (int _i = 0; _i < 2; ++_i) \
;         __builtin_amdgcn_global_load_lds((const unsigned*)((const char*)(gbase) + (voff)[_i]), (LAS unsigned*)(lds + (bufoff) + ldsw + _i * 8192), 16, 0, 0); } while (0)
; #define PG8_LDA(dst, b, h) do { _Pragma("unroll") for (int m = 0; m < 4; ++m) _Pragma("unroll") for (int k = 0; k < 2; ++k) dst[m][k] = *(const LAS bf16x8*)(lds + PG8_SA(b, h) + aoff + m * 2048 + k * 1024); } while (0)
; #define PG8_LDB(dst, b, h) do { _Pragma("unroll") for (int n = 0; n < 2; ++n) _Pragma("unroll") for (int k = 0; k < 2; ++k) dst[n][k] = *(const LAS bf16x8*)(lds + PG8_SB(b, h) + boff + n * 2048 + k * 1024); } while (0)
; #define PG8_MMA(ai, bj, At, Bt) do { __builtin_amdgcn_s_setprio(1); _Pragma("unroll") for (int m = 0; m < 4; ++m) _Pragma("unroll") for (int n = 0; n < 2; ++n) _Pragma("unroll") for (int k = 0; k < 2; ++k) \
;         acc[ai][bj][m][n] = __builtin_amdgcn_mfma_f32_16x16x32_bf16(Bt[n][k], At[m][k], acc[ai][bj][m][n], 0, 0, 0); __builtin_amdgcn_s_setprio(0); } while (0)
; #define PG8_WAIT_V(n) asm volatile("s_waitcnt vmcnt(" #n ")" ::: "memory")
; #define PG8_WAIT_L(n) asm volatile("s_waitcnt lgkmcnt(" #n ")" ::: "memory")
; template <class Epi, class Sched, bool ALIGN_EPI, bool LAST_FUSED = false, bool PERM = false, bool CARRY = false>
; __device__ __forceinline__ void gemm_phase(LAS unsigned char* lds, const int tid, const int K, const int lda, const int ldb, const Sched& S, const Epi& E) {
;     ...
;         for (int t = 0; t < nt; t += 2) {
;             const bool last = (t == nt - 2);
;             const char* a1 = cA + (size_t)(t + 1) * kstep;
;             const char* a2 = last ? nA : cA + (size_t)(t + 2) * kstep; const char* b2 = last ? nB : cB + (size_t)(t + 2) * kstep;
;             const char* a3 = a2 + kstep; const char* b3 = b2 + kstep;
;             PG8_LDB(B0, 0, 0); PG8_LDB(B1, 0, 1); PG8_SCHED; PG8_LDA(At, 0, 0); PG8_STAGE(PG8_SA(1, 1), a1 + hstepA, voffA);
;             PG8_WAIT_V(8); PG8_WAIT_L(0); PG8_BAR; PG8_MMA(0, 0, At, B0); PG8_MMA(0, 1, At, B1); PG8_BAR; PG8_SCHED;
;             PG8_LDA(At, 0, 1); PG8_STAGE(PG8_SB(0, 0), b2, voffB); PG8_STAGE(PG8_SB(0, 1), b2 + hstepB, voffB); PG8_STAGE(PG8_SA(0, 0), a2, voffA);
;             PG8_WAIT_V(8); PG8_WAIT_L(0); PG8_BAR; PG8_MMA(1, 0, At, B0); PG8_MMA(1, 1, At, B1); PG8_BAR; PG8_SCHED;
.LBB0_1367:
	s_add_u32 s19, s38, s17
	s_addc_u32 s23, s39, 0
	s_add_u32 s35, s19, 0x100
	s_addc_u32 s37, s23, 0
	s_and_b64 s[28:29], s[46:47], exec
	s_cselect_b32 s51, s27, s37
	s_cselect_b32 s50, s26, s35
	s_add_u32 s17, s40, s17
	s_addc_u32 s28, s41, 0
	s_add_u32 s17, s17, 0x100
	s_addc_u32 s35, s28, 0
	s_add_i32 s45, 0, 0x10000
	s_and_b64 s[28:29], s[46:47], exec
	s_cselect_b32 s55, s31, s35
	s_cselect_b32 s54, s30, s17
	s_add_i32 s47, 0, 0x14000
	s_add_u32 s52, s19, 0x80080
	s_addc_u32 s53, s23, 0
	s_add_i32 s44, s45, s61
	s_add_i32 m0, s63, 0xc000
	s_add_i32 s79, s63, 0xe000
	s_add_i32 s29, s44, 0x2000
	s_add_u32 s58, s54, 0x10000
	v_add_u32_e32 v46, s45, v216
	v_add_u32_e32 v164, s47, v216
	s_addc_u32 s59, s55, 0
	s_add_i32 s37, s47, s61
	ds_read_b128 v[26:29], v46
	ds_read_b128 v[34:37], v46 offset:1024
	ds_read_b128 v[38:41], v46 offset:2048
	ds_read_b128 v[46:49], v46 offset:3072
	ds_read_b128 v[54:57], v164
	ds_read_b128 v[58:61], v164 offset:1024
	ds_read_b128 v[160:163], v164 offset:2048
	ds_read_b128 v[164:167], v164 offset:3072
	s_add_i32 s35, s37, 0x2000
	s_add_i32 s28, 0, 0x18000
	s_add_i32 s23, 0, 0x1c000
	s_add_u32 s48, s50, 0x80000
	s_addc_u32 s49, s51, 0
	s_add_i32 s19, s28, s61
	s_add_i32 s17, s19, 0x2000
	s_add_u32 s46, s54, 0x10080
	s_addc_u32 s47, s55, 0
	s_add_i32 s78, s23, s61
	s_add_i32 s45, s78, 0x2000
	v_lshl_add_u64 v[200:201], s[52:53], 0, v[158:159]
	ds_read_b128 v[168:171], v217
	ds_read_b128 v[172:175], v217 offset:1024
	ds_read_b128 v[176:179], v217 offset:2048
	ds_read_b128 v[180:183], v217 offset:3072
	ds_read_b128 v[184:187], v217 offset:4096
	ds_read_b128 v[188:191], v217 offset:5120
	ds_read_b128 v[192:195], v217 offset:6144
	ds_read_b128 v[196:199], v217 offset:7168
	global_load_lds_dwordx4 v[200:201], off
	v_lshl_add_u64 v[200:201], s[52:53], 0, v[156:157]
	s_mov_b32 m0, s79
	s_nop 0
	global_load_lds_dwordx4 v[200:201], off
	s_waitcnt vmcnt(8)
	s_waitcnt lgkmcnt(0)
	s_setprio 1
	s_barrier
	v_mfma_f32_16x16x32_bf16 v[150:153], v[26:29], v[168:171], v[150:153]
	v_mfma_f32_16x16x32_bf16 v[142:145], v[38:41], v[168:171], v[142:145]
	v_mfma_f32_16x16x32_bf16 v[134:137], v[26:29], v[176:179], v[134:137]
	v_mfma_f32_16x16x32_bf16 v[126:129], v[38:41], v[176:179], v[126:129]
	v_mfma_f32_16x16x32_bf16 v[118:121], v[26:29], v[184:187], v[118:121]
	v_mfma_f32_16x16x32_bf16 v[110:113], v[38:41], v[184:187], v[110:113]
	v_mfma_f32_16x16x32_bf16 v[102:105], v[26:29], v[192:195], v[102:105]
	v_mfma_f32_16x16x32_bf16 v[94:97], v[38:41], v[192:195], v[94:97]
	v_mfma_f32_16x16x32_bf16 v[150:153], v[34:37], v[172:175], v[150:153]
	v_mfma_f32_16x16x32_bf16 v[142:145], v[46:49], v[172:175], v[142:145]
	v_mfma_f32_16x16x32_bf16 v[134:137], v[34:37], v[180:183], v[134:137]
	v_mfma_f32_16x16x32_bf16 v[126:129], v[46:49], v[180:183], v[126:129]
	v_mfma_f32_16x16x32_bf16 v[118:121], v[34:37], v[188:191], v[118:121]
	v_mfma_f32_16x16x32_bf16 v[110:113], v[46:49], v[188:191], v[110:113]
	v_mfma_f32_16x16x32_bf16 v[102:105], v[34:37], v[196:199], v[102:105]
	v_mfma_f32_16x16x32_bf16 v[94:97], v[46:49], v[196:199], v[94:97]
	s_setprio 0
	s_setprio 1
	v_mfma_f32_16x16x32_bf16 v[146:149], v[54:57], v[168:171], v[146:149]
	v_mfma_f32_16x16x32_bf16 v[138:141], v[160:163], v[168:171], v[138:141]
	v_mfma_f32_16x16x32_bf16 v[130:133], v[54:57], v[176:179], v[130:133]
	v_mfma_f32_16x16x32_bf16 v[122:125], v[160:163], v[176:179], v[122:125]
	v_mfma_f32_16x16x32_bf16 v[114:117], v[54:57], v[184:187], v[114:117]
	v_mfma_f32_16x16x32_bf16 v[106:109], v[160:163], v[184:187], v[106:109]
	v_mfma_f32_16x16x32_bf16 v[98:101], v[54:57], v[192:195], v[98:101]
	v_mfma_f32_16x16x32_bf16 v[90:93], v[160:163], v[192:195], v[90:93]
	v_mfma_f32_16x16x32_bf16 v[146:149], v[58:61], v[172:175], v[146:149]
	v_mfma_f32_16x16x32_bf16 v[138:141], v[164:167], v[172:175], v[138:141]
	v_mfma_f32_16x16x32_bf16 v[130:133], v[58:61], v[180:183], v[130:133]
	v_mfma_f32_16x16x32_bf16 v[122:125], v[164:167], v[180:183], v[122:125]
	v_mfma_f32_16x16x32_bf16 v[114:117], v[58:61], v[188:191], v[114:117]
	v_mfma_f32_16x16x32_bf16 v[106:109], v[164:167], v[188:191], v[106:109]
	v_mfma_f32_16x16x32_bf16 v[98:101], v[58:61], v[196:199], v[98:101]
	v_mfma_f32_16x16x32_bf16 v[90:93], v[164:167], v[196:199], v[90:93]
	s_barrier
	s_setprio 0
	s_mov_b32 m0, s44
	v_lshl_add_u64 v[204:205], s[54:55], 0, v[0:1]
	ds_read_b128 v[168:171], v217 offset:16384
	ds_read_b128 v[172:175], v217 offset:17408
	ds_read_b128 v[176:179], v217 offset:18432
	ds_read_b128 v[180:183], v217 offset:19456
	ds_read_b128 v[184:187], v217 offset:20480
	ds_read_b128 v[188:191], v217 offset:21504
	ds_read_b128 v[192:195], v217 offset:22528
	ds_read_b128 v[196:199], v217 offset:23552
	global_load_lds_dwordx4 v[204:205], off
	v_lshl_add_u64 v[206:207], s[54:55], 0, v[154:155]
	s_mov_b32 m0, s29
	v_lshl_add_u64 v[200:201], s[58:59], 0, v[0:1]
	global_load_lds_dwordx4 v[206:207], off
	s_mov_b32 m0, s37
	v_lshl_add_u64 v[208:209], s[50:51], 0, v[158:159]
	global_load_lds_dwordx4 v[200:201], off
	v_lshl_add_u64 v[200:201], s[58:59], 0, v[154:155]
	s_mov_b32 m0, s35
	v_lshl_add_u64 v[210:211], s[50:51], 0, v[156:157]
	global_load_lds_dwordx4 v[200:201], off
	s_mov_b32 m0, s63
	s_nop 0
	global_load_lds_dwordx4 v[208:209], off
	s_mov_b32 m0, s64
	s_nop 0
	global_load_lds_dwordx4 v[210:211], off
	s_waitcnt vmcnt(8)
	s_waitcnt lgkmcnt(0)
	s_setprio 1
	s_barrier
; #define PG8_STAGE(bufoff, gbase, voff) do { _Pragma("unroll") for (int _i = 0; _i < 2; ++_i) \
;         __builtin_amdgcn_global_load_lds((const unsigned*)((const char*)(gbase) + (voff)[_i]), (LAS unsigned*)(lds + (bufoff) + ldsw + _i * 8192), 16, 0, 0); } while (0)
; #define PG8_LDA(dst, b, h) do { _Pragma("unroll") for (int m = 0; m < 4; ++m) _Pragma("unroll") for (int k = 0; k < 2; ++k) dst[m][k] = *(const LAS bf16x8*)(lds + PG8_SA(b, h) + aoff + m * 2048 + k * 1024); } while (0)
; #define PG8_LDB(dst, b, h) do { _Pragma("unroll") for (int n = 0; n < 2; ++n) _Pragma("unroll") for (int k = 0; k < 2; ++k) dst[n][k] = *(const LAS bf16x8*)(lds + PG8_SB(b, h) + boff + n * 2048 + k * 1024); } while (0)
; #define PG8_MMA(ai, bj, At, Bt) do { __builtin_amdgcn_s_setprio(1); _Pragma("unroll") for (int m = 0; m < 4; ++m) _Pragma("unroll") for (int n = 0; n < 2; ++n) _Pragma("unroll") for (int k = 0; k < 2; ++k) \
;         acc[ai][bj][m][n] = __builtin_amdgcn_mfma_f32_16x16x32_bf16(Bt[n][k], At[m][k], acc[ai][bj][m][n], 0, 0, 0); __builtin_amdgcn_s_setprio(0); } while (0)
; #define PG8_WAIT_V(n) asm volatile("s_waitcnt vmcnt(" #n ")" ::: "memory")
; #define PG8_WAIT_L(n) asm volatile("s_waitcnt lgkmcnt(" #n ")" ::: "memory")
; #define PG8_BAR __builtin_amdgcn_s_barrier()
; #define PG8_SCHED __builtin_amdgcn_sched_barrier(0)
; template <class Epi, class Sched, bool ALIGN_EPI, bool LAST_FUSED = false, bool PERM = false, bool CARRY = false>
; __device__ __forceinline__ void gemm_phase(LAS unsigned char* lds, const int tid, const int K, const int lda, const int ldb, const Sched& S, const Epi& E) {
;     ...
;             PG8_WAIT_V(8); PG8_WAIT_L(0); PG8_BAR; PG8_MMA(1, 0, At, B0); PG8_MMA(1, 1, At, B1); PG8_BAR; PG8_SCHED;
;             PG8_LDB(B0, 1, 0); PG8_LDB(B1, 1, 1); PG8_SCHED; PG8_LDA(At, 1, 0); PG8_STAGE(PG8_SA(0, 1), a2 + hstepA, voffA);
;             PG8_WAIT_V(8); PG8_WAIT_L(0); PG8_BAR; PG8_MMA(0, 0, At, B0); PG8_MMA(0, 1, At, B1); PG8_BAR; PG8_SCHED;
;             PG8_LDA(At, 1, 1); PG8_STAGE(PG8_SB(1, 0), b3, voffB); PG8_STAGE(PG8_SB(1, 1), b3 + hstepB, voffB); PG8_STAGE(PG8_SA(1, 0), a3, voffA);
;             PG8_WAIT_V(8); PG8_WAIT_L(0); PG8_BAR; PG8_MMA(1, 0, At, B0); PG8_MMA(1, 1, At, B1); PG8_BAR; PG8_SCHED;
	v_mfma_f32_16x16x32_bf16 v[86:89], v[26:29], v[168:171], v[86:89]
	v_mfma_f32_16x16x32_bf16 v[78:81], v[38:41], v[168:171], v[78:81]
	v_mfma_f32_16x16x32_bf16 v[70:73], v[26:29], v[176:179], v[70:73]
	v_mfma_f32_16x16x32_bf16 v[62:65], v[38:41], v[176:179], v[62:65]
	v_mfma_f32_16x16x32_bf16 v[42:45], v[26:29], v[184:187], v[42:45]
	v_mfma_f32_16x16x32_bf16 v[22:25], v[38:41], v[184:187], v[22:25]
	v_mfma_f32_16x16x32_bf16 v[14:17], v[26:29], v[192:195], v[14:17]
	v_mfma_f32_16x16x32_bf16 v[6:9], v[38:41], v[192:195], v[6:9]
	v_mfma_f32_16x16x32_bf16 v[86:89], v[34:37], v[172:175], v[86:89]
	v_mfma_f32_16x16x32_bf16 v[78:81], v[46:49], v[172:175], v[78:81]
	v_mfma_f32_16x16x32_bf16 v[70:73], v[34:37], v[180:183], v[70:73]
	v_mfma_f32_16x16x32_bf16 v[62:65], v[46:49], v[180:183], v[62:65]
	v_mfma_f32_16x16x32_bf16 v[42:45], v[34:37], v[188:191], v[42:45]
	v_mfma_f32_16x16x32_bf16 v[22:25], v[46:49], v[188:191], v[22:25]
	v_mfma_f32_16x16x32_bf16 v[14:17], v[34:37], v[196:199], v[14:17]
	v_mfma_f32_16x16x32_bf16 v[6:9], v[46:49], v[196:199], v[6:9]
	s_setprio 0
	s_setprio 1
	v_mfma_f32_16x16x32_bf16 v[30:33], v[54:57], v[184:187], v[30:33]
	v_mfma_f32_16x16x32_bf16 v[18:21], v[160:163], v[184:187], v[18:21]
	v_mfma_f32_16x16x32_bf16 v[10:13], v[54:57], v[192:195], v[10:13]
	v_mfma_f32_16x16x32_bf16 v[2:5], v[160:163], v[192:195], v[2:5]
	v_mfma_f32_16x16x32_bf16 v[26:29], v[54:57], v[168:171], v[82:85]
	v_mfma_f32_16x16x32_bf16 v[34:37], v[160:163], v[168:171], v[74:77]
	v_mfma_f32_16x16x32_bf16 v[38:41], v[54:57], v[176:179], v[66:69]
	v_mfma_f32_16x16x32_bf16 v[46:49], v[160:163], v[176:179], v[50:53]
	v_mfma_f32_16x16x32_bf16 v[30:33], v[58:61], v[188:191], v[30:33]
	v_mfma_f32_16x16x32_bf16 v[18:21], v[164:167], v[188:191], v[18:21]
	v_mfma_f32_16x16x32_bf16 v[10:13], v[58:61], v[196:199], v[10:13]
	v_mfma_f32_16x16x32_bf16 v[2:5], v[164:167], v[196:199], v[2:5]
	v_mfma_f32_16x16x32_bf16 v[26:29], v[58:61], v[172:175], v[26:29]
	v_mfma_f32_16x16x32_bf16 v[34:37], v[164:167], v[172:175], v[34:37]
	v_mfma_f32_16x16x32_bf16 v[38:41], v[58:61], v[180:183], v[38:41]
	v_mfma_f32_16x16x32_bf16 v[46:49], v[164:167], v[180:183], v[46:49]
	s_barrier
	s_setprio 0
	v_add_u32_e32 v66, s28, v216
	v_add_u32_e32 v74, s23, v216
	ds_read_b128 v[50:53], v66
	ds_read_b128 v[54:57], v66 offset:1024
	ds_read_b128 v[58:61], v66 offset:2048
	ds_read_b128 v[66:69], v66 offset:3072
	ds_read_b128 v[160:163], v74
	ds_read_b128 v[164:167], v74 offset:1024
	ds_read_b128 v[168:171], v74 offset:2048
	ds_read_b128 v[172:175], v74 offset:3072
	s_mov_b32 m0, s65
	v_lshl_add_u64 v[200:201], s[48:49], 0, v[158:159]
	ds_read_b128 v[74:77], v217 offset:32768
	ds_read_b128 v[82:85], v217 offset:33792
	ds_read_b128 v[176:179], v217 offset:34816
	ds_read_b128 v[180:183], v217 offset:35840
	ds_read_b128 v[184:187], v217 offset:36864
	ds_read_b128 v[188:191], v217 offset:37888
	ds_read_b128 v[192:195], v217 offset:38912
	ds_read_b128 v[196:199], v217 offset:39936
	global_load_lds_dwordx4 v[200:201], off
	v_lshl_add_u64 v[200:201], s[48:49], 0, v[156:157]
	s_mov_b32 m0, s66
	s_nop 0
	global_load_lds_dwordx4 v[200:201], off
	s_waitcnt vmcnt(8)
	s_waitcnt lgkmcnt(0)
	s_setprio 1
	s_barrier
	v_mfma_f32_16x16x32_bf16 v[150:153], v[50:53], v[74:77], v[150:153]
	v_mfma_f32_16x16x32_bf16 v[142:145], v[58:61], v[74:77], v[142:145]
	v_mfma_f32_16x16x32_bf16 v[134:137], v[50:53], v[176:179], v[134:137]
	v_mfma_f32_16x16x32_bf16 v[126:129], v[58:61], v[176:179], v[126:129]
	v_mfma_f32_16x16x32_bf16 v[118:121], v[50:53], v[184:187], v[118:121]
	v_mfma_f32_16x16x32_bf16 v[110:113], v[58:61], v[184:187], v[110:113]
	v_mfma_f32_16x16x32_bf16 v[102:105], v[50:53], v[192:195], v[102:105]
	v_mfma_f32_16x16x32_bf16 v[94:97], v[58:61], v[192:195], v[94:97]
	v_mfma_f32_16x16x32_bf16 v[150:153], v[54:57], v[82:85], v[150:153]
	v_mfma_f32_16x16x32_bf16 v[142:145], v[66:69], v[82:85], v[142:145]
	v_mfma_f32_16x16x32_bf16 v[134:137], v[54:57], v[180:183], v[134:137]
	v_mfma_f32_16x16x32_bf16 v[126:129], v[66:69], v[180:183], v[126:129]
	v_mfma_f32_16x16x32_bf16 v[118:121], v[54:57], v[188:191], v[118:121]
	v_mfma_f32_16x16x32_bf16 v[110:113], v[66:69], v[188:191], v[110:113]
	v_mfma_f32_16x16x32_bf16 v[102:105], v[54:57], v[196:199], v[102:105]
	v_mfma_f32_16x16x32_bf16 v[94:97], v[66:69], v[196:199], v[94:97]
	s_setprio 0
	s_setprio 1
	v_mfma_f32_16x16x32_bf16 v[146:149], v[160:163], v[74:77], v[146:149]
	v_mfma_f32_16x16x32_bf16 v[74:77], v[168:171], v[74:77], v[138:141]
	v_mfma_f32_16x16x32_bf16 v[138:141], v[172:175], v[82:85], v[74:77]
	v_mfma_f32_16x16x32_bf16 v[74:77], v[160:163], v[176:179], v[130:133]
	v_mfma_f32_16x16x32_bf16 v[130:133], v[164:167], v[180:183], v[74:77]
	v_mfma_f32_16x16x32_bf16 v[74:77], v[168:171], v[176:179], v[122:125]
	v_mfma_f32_16x16x32_bf16 v[122:125], v[172:175], v[180:183], v[74:77]
	v_mfma_f32_16x16x32_bf16 v[74:77], v[160:163], v[184:187], v[114:117]
	v_mfma_f32_16x16x32_bf16 v[114:117], v[164:167], v[188:191], v[74:77]
	v_mfma_f32_16x16x32_bf16 v[74:77], v[168:171], v[184:187], v[106:109]
	v_mfma_f32_16x16x32_bf16 v[106:109], v[172:175], v[188:191], v[74:77]
	v_mfma_f32_16x16x32_bf16 v[74:77], v[160:163], v[192:195], v[98:101]
	v_mfma_f32_16x16x32_bf16 v[98:101], v[164:167], v[196:199], v[74:77]
	v_mfma_f32_16x16x32_bf16 v[74:77], v[168:171], v[192:195], v[90:93]
	v_mfma_f32_16x16x32_bf16 v[146:149], v[164:167], v[82:85], v[146:149]
	v_mfma_f32_16x16x32_bf16 v[90:93], v[172:175], v[196:199], v[74:77]
	s_barrier
; #define PG8_STAGE(bufoff, gbase, voff) do { _Pragma("unroll") for (int _i = 0; _i < 2; ++_i) \
;         __builtin_amdgcn_global_load_lds((const unsigned*)((const char*)(gbase) + (voff)[_i]), (LAS unsigned*)(lds + (bufoff) + ldsw + _i * 8192), 16, 0, 0); } while (0)
; #define PG8_LDA(dst, b, h) do { _Pragma("unroll") for (int m = 0; m < 4; ++m) _Pragma("unroll") for (int k = 0; k < 2; ++k) dst[m][k] = *(const LAS bf16x8*)(lds + PG8_SA(b, h) + aoff + m * 2048 + k * 1024); } while (0)
; #define PG8_MMA(ai, bj, At, Bt) do { __builtin_amdgcn_s_setprio(1); _Pragma("unroll") for (int m = 0; m < 4; ++m) _Pragma("unroll") for (int n = 0; n < 2; ++n) _Pragma("unroll") for (int k = 0; k < 2; ++k) \
;         acc[ai][bj][m][n] = __builtin_amdgcn_mfma_f32_16x16x32_bf16(Bt[n][k], At[m][k], acc[ai][bj][m][n], 0, 0, 0); __builtin_amdgcn_s_setprio(0); } while (0)
; #define PG8_WAIT_V(n) asm volatile("s_waitcnt vmcnt(" #n ")" ::: "memory")
; #define PG8_WAIT_L(n) asm volatile("s_waitcnt lgkmcnt(" #n ")" ::: "memory")
; #define PG8_BAR __builtin_amdgcn_s_barrier()
; #define PG8_SCHED __builtin_amdgcn_sched_barrier(0)
; template <class Epi, class Sched, bool ALIGN_EPI, bool LAST_FUSED = false, bool PERM = false, bool CARRY = false>
; __device__ __forceinline__ void gemm_phase(LAS unsigned char* lds, const int tid, const int K, const int lda, const int ldb, const Sched& S, const Epi& E) {
;     ...
;             PG8_LDA(At, 1, 1); PG8_STAGE(PG8_SB(1, 0), b3, voffB); PG8_STAGE(PG8_SB(1, 1), b3 + hstepB, voffB); PG8_STAGE(PG8_SA(1, 0), a3, voffA);
;             PG8_WAIT_V(8); PG8_WAIT_L(0); PG8_BAR; PG8_MMA(1, 0, At, B0); PG8_MMA(1, 1, At, B1); PG8_BAR; PG8_SCHED;
;         }
;         if constexpr (ALIGN_EPI) { if (wr == 0) PG8_BAR; }
	s_setprio 0
	s_mov_b32 m0, s19
	v_lshl_add_u64 v[82:83], v[204:205], 0, s[68:69]
	s_nop 1
	ds_read_b128 v[74:77], v217 offset:49152
	ds_read_b128 v[176:179], v217 offset:50176
	ds_read_b128 v[180:183], v217 offset:51200
	ds_read_b128 v[184:187], v217 offset:52224
	ds_read_b128 v[188:191], v217 offset:53248
	ds_read_b128 v[192:195], v217 offset:54272
	ds_read_b128 v[196:199], v217 offset:55296
	ds_read_b128 v[200:203], v217 offset:56320
	global_load_lds_dwordx4 v[82:83], off
	v_lshl_add_u64 v[82:83], v[206:207], 0, s[68:69]
	s_mov_b32 m0, s17
	s_nop 0
	global_load_lds_dwordx4 v[82:83], off
	v_lshl_add_u64 v[82:83], s[46:47], 0, v[0:1]
	s_mov_b32 m0, s78
	s_nop 0
	global_load_lds_dwordx4 v[82:83], off
	v_lshl_add_u64 v[82:83], s[46:47], 0, v[154:155]
	s_mov_b32 m0, s45
	s_nop 0
	global_load_lds_dwordx4 v[82:83], off
	v_lshl_add_u64 v[82:83], v[208:209], 0, s[68:69]
	s_mov_b32 m0, s74
	s_nop 0
	global_load_lds_dwordx4 v[82:83], off
	v_lshl_add_u64 v[82:83], v[210:211], 0, s[68:69]
	s_mov_b32 m0, s75
	s_nop 0
	global_load_lds_dwordx4 v[82:83], off
	s_waitcnt vmcnt(8)
	s_waitcnt lgkmcnt(0)
	s_setprio 1
	s_barrier
	v_mfma_f32_16x16x32_bf16 v[82:85], v[50:53], v[74:77], v[86:89]
	v_mfma_f32_16x16x32_bf16 v[78:81], v[58:61], v[74:77], v[78:81]
	v_mfma_f32_16x16x32_bf16 v[70:73], v[50:53], v[180:183], v[70:73]
	v_mfma_f32_16x16x32_bf16 v[62:65], v[58:61], v[180:183], v[62:65]
	v_mfma_f32_16x16x32_bf16 v[42:45], v[50:53], v[188:191], v[42:45]
	v_mfma_f32_16x16x32_bf16 v[22:25], v[58:61], v[188:191], v[22:25]
	v_mfma_f32_16x16x32_bf16 v[14:17], v[50:53], v[196:199], v[14:17]
	v_mfma_f32_16x16x32_bf16 v[6:9], v[58:61], v[196:199], v[6:9]
	v_mfma_f32_16x16x32_bf16 v[86:89], v[54:57], v[176:179], v[82:85]
	v_mfma_f32_16x16x32_bf16 v[78:81], v[66:69], v[176:179], v[78:81]
	v_mfma_f32_16x16x32_bf16 v[70:73], v[54:57], v[184:187], v[70:73]
	v_mfma_f32_16x16x32_bf16 v[62:65], v[66:69], v[184:187], v[62:65]
	v_mfma_f32_16x16x32_bf16 v[42:45], v[54:57], v[192:195], v[42:45]
	v_mfma_f32_16x16x32_bf16 v[22:25], v[66:69], v[192:195], v[22:25]
	v_mfma_f32_16x16x32_bf16 v[14:17], v[54:57], v[200:203], v[14:17]
	v_mfma_f32_16x16x32_bf16 v[6:9], v[66:69], v[200:203], v[6:9]
	s_setprio 0
	s_setprio 1
	v_mfma_f32_16x16x32_bf16 v[26:29], v[160:163], v[74:77], v[26:29]
	v_mfma_f32_16x16x32_bf16 v[82:85], v[164:167], v[176:179], v[26:29]
	v_mfma_f32_16x16x32_bf16 v[26:29], v[168:171], v[74:77], v[34:37]
	v_mfma_f32_16x16x32_bf16 v[74:77], v[172:175], v[176:179], v[26:29]
	v_mfma_f32_16x16x32_bf16 v[26:29], v[160:163], v[180:183], v[38:41]
	v_mfma_f32_16x16x32_bf16 v[66:69], v[164:167], v[184:187], v[26:29]
	v_mfma_f32_16x16x32_bf16 v[26:29], v[168:171], v[180:183], v[46:49]
	v_mfma_f32_16x16x32_bf16 v[50:53], v[172:175], v[184:187], v[26:29]
	v_mfma_f32_16x16x32_bf16 v[26:29], v[160:163], v[188:191], v[30:33]
	v_mfma_f32_16x16x32_bf16 v[18:21], v[168:171], v[188:191], v[18:21]
	v_mfma_f32_16x16x32_bf16 v[10:13], v[160:163], v[196:199], v[10:13]
	v_mfma_f32_16x16x32_bf16 v[2:5], v[168:171], v[196:199], v[2:5]
	v_mfma_f32_16x16x32_bf16 v[30:33], v[164:167], v[192:195], v[26:29]
	v_mfma_f32_16x16x32_bf16 v[18:21], v[172:175], v[192:195], v[18:21]
	v_mfma_f32_16x16x32_bf16 v[10:13], v[164:167], v[200:203], v[10:13]
	v_mfma_f32_16x16x32_bf16 v[2:5], v[172:175], v[200:203], v[2:5]
	s_barrier
	s_setprio 0
	s_movk_i32 s17, 0x100
	s_andn2_b64 vcc, exec, s[42:43]
	s_mov_b64 s[46:47], -1
	s_mov_b64 s[42:43], 0
	s_cbranch_vccz .LBB0_1367
	s_and_b64 vcc, exec, s[14:15]
	s_cbranch_vccz .LBB0_1370
	s_barrier

; #define PG8_STAGE(bufoff, gbase, voff) do { _Pragma("unroll") for (int _i = 0; _i < 2; ++_i) \
;         __builtin_amdgcn_global_load_lds((const unsigned*)((const char*)(gbase) + (voff)[_i]), (LAS unsigned*)(lds + (bufoff) + ldsw + _i * 8192), 16, 0, 0); } while (0)
; #define PG8_LDA(dst, b, h) do { _Pragma("unroll") for (int m = 0; m < 4; ++m) _Pragma("unroll") for (int k = 0; k < 2; ++k) dst[m][k] = *(const LAS bf16x8*)(lds + PG8_SA(b, h) + aoff + m * 2048 + k * 1024); } while (0)
; #define PG8_LDB(dst, b, h) do { _Pragma("unroll") for (int n = 0; n < 2; ++n) _Pragma("unroll") for (int k = 0; k < 2; ++k) dst[n][k] = *(const LAS bf16x8*)(lds + PG8_SB(b, h) + boff + n * 2048 + k * 1024); } while (0)
; #define PG8_MMA(ai, bj, At, Bt) do { __builtin_amdgcn_s_setprio(1); _Pragma("unroll") for (int m = 0; m < 4; ++m) _Pragma("unroll") for (int n = 0; n < 2; ++n) _Pragma("unroll") for (int k = 0; k < 2; ++k) \
;         acc[ai][bj][m][n] = __builtin_amdgcn_mfma_f32_16x16x32_bf16(Bt[n][k], At[m][k], acc[ai][bj][m][n], 0, 0, 0); __builtin_amdgcn_s_setprio(0); } while (0)
; #define PG8_WAIT_V(n) asm volatile("s_waitcnt vmcnt(" #n ")" ::: "memory")
; #define PG8_WAIT_L(n) asm volatile("s_waitcnt lgkmcnt(" #n ")" ::: "memory")
; template <class Epi, class Sched, bool ALIGN_EPI, bool LAST_FUSED = false, bool PERM = false, bool CARRY = false>
; __device__ __forceinline__ void gemm_phase(LAS unsigned char* lds, const int tid, const int K, const int lda, const int ldb, const Sched& S, const Epi& E) {
;     ...
;         for (int t = 0; t < nt; t += 2) {
;             const bool last = (t == nt - 2);
;             const char* a1 = cA + (size_t)(t + 1) * kstep;
;             const char* a2 = last ? nA : cA + (size_t)(t + 2) * kstep; const char* b2 = last ? nB : cB + (size_t)(t + 2) * kstep;
;             const char* a3 = a2 + kstep; const char* b3 = b2 + kstep;
;             PG8_LDB(B0, 0, 0); PG8_LDB(B1, 0, 1); PG8_SCHED; PG8_LDA(At, 0, 0); PG8_STAGE(PG8_SA(1, 1), a1 + hstepA, voffA);
;             PG8_WAIT_V(8); PG8_WAIT_L(0); PG8_BAR; PG8_MMA(0, 0, At, B0); PG8_MMA(0, 1, At, B1); PG8_BAR; PG8_SCHED;
;             PG8_LDA(At, 0, 1); PG8_STAGE(PG8_SB(0, 0), b2, voffB); PG8_STAGE(PG8_SB(0, 1), b2 + hstepB, voffB); PG8_STAGE(PG8_SA(0, 0), a2, voffA);
;             PG8_WAIT_V(8); PG8_WAIT_L(0); PG8_BAR; PG8_MMA(1, 0, At, B0); PG8_MMA(1, 1, At, B1); PG8_BAR; PG8_SCHED;
.LBB0_1585:
	s_add_u32 s52, s42, s48
	s_addc_u32 s53, s43, s49
	s_add_u32 s76, s40, s48
	s_addc_u32 s77, s41, s49
	s_add_i32 s96, 0, 0x10000
	s_cmp_eq_u32 s3, s95
	s_cselect_b32 s53, s24, s53
	s_cselect_b32 s52, s55, s52
	s_cselect_b32 s77, s93, s77
	s_cselect_b32 s76, s94, s76
	s_add_i32 vcc_lo, 0, 0x14000
	v_add_u32_e32 v156, s96, v140
	v_add_u32_e32 v172, vcc_lo, v140
	ds_read_b128 v[142:145], v156
	ds_read_b128 v[146:149], v156 offset:1024
	ds_read_b128 v[150:153], v156 offset:2048
	ds_read_b128 v[156:159], v156 offset:3072
	ds_read_b128 v[160:163], v172
	ds_read_b128 v[164:167], v172 offset:1024
	ds_read_b128 v[168:171], v172 offset:2048
	ds_read_b128 v[172:175], v172 offset:3072
	v_lshl_add_u64 v[208:209], s[42:43], 0, v[138:139]
	s_add_i32 m0, s35, 0xc000
	ds_read_b128 v[176:179], v141
	ds_read_b128 v[180:183], v141 offset:1024
	ds_read_b128 v[184:187], v141 offset:2048
	ds_read_b128 v[188:191], v141 offset:3072
	ds_read_b128 v[192:195], v141 offset:4096
	ds_read_b128 v[196:199], v141 offset:5120
	ds_read_b128 v[200:203], v141 offset:6144
	ds_read_b128 v[204:207], v141 offset:7168
	global_load_lds_dwordx4 v[208:209], off
	v_lshl_add_u64 v[208:209], s[42:43], 0, v[128:129]
	s_add_i32 m0, s35, 0xe000
	s_nop 0
	global_load_lds_dwordx4 v[208:209], off
	s_waitcnt vmcnt(8)
	s_waitcnt lgkmcnt(0)
	s_setprio 1
	s_barrier
	v_mfma_f32_16x16x32_bf16 v[62:65], v[142:145], v[176:179], v[62:65]
	v_mfma_f32_16x16x32_bf16 v[42:45], v[150:153], v[176:179], v[42:45]
	v_mfma_f32_16x16x32_bf16 v[18:21], v[142:145], v[184:187], v[18:21]
	v_mfma_f32_16x16x32_bf16 v[14:17], v[150:153], v[184:187], v[14:17]
	v_mfma_f32_16x16x32_bf16 v[38:41], v[142:145], v[192:195], v[38:41]
	v_mfma_f32_16x16x32_bf16 v[30:33], v[150:153], v[192:195], v[30:33]
	v_mfma_f32_16x16x32_bf16 v[58:61], v[142:145], v[200:203], v[58:61]
	v_mfma_f32_16x16x32_bf16 v[54:57], v[150:153], v[200:203], v[54:57]
	v_mfma_f32_16x16x32_bf16 v[62:65], v[146:149], v[180:183], v[62:65]
	v_mfma_f32_16x16x32_bf16 v[42:45], v[156:159], v[180:183], v[42:45]
	v_mfma_f32_16x16x32_bf16 v[18:21], v[146:149], v[188:191], v[18:21]
	v_mfma_f32_16x16x32_bf16 v[14:17], v[156:159], v[188:191], v[14:17]
	v_mfma_f32_16x16x32_bf16 v[38:41], v[146:149], v[196:199], v[38:41]
	v_mfma_f32_16x16x32_bf16 v[30:33], v[156:159], v[196:199], v[30:33]
	v_mfma_f32_16x16x32_bf16 v[58:61], v[146:149], v[204:207], v[58:61]
	v_mfma_f32_16x16x32_bf16 v[54:57], v[156:159], v[204:207], v[54:57]
	s_setprio 0
	s_setprio 1
	v_mfma_f32_16x16x32_bf16 v[34:37], v[160:163], v[176:179], v[34:37]
	v_mfma_f32_16x16x32_bf16 v[2:5], v[168:171], v[176:179], v[2:5]
	v_mfma_f32_16x16x32_bf16 v[10:13], v[160:163], v[184:187], v[10:13]
	v_mfma_f32_16x16x32_bf16 v[6:9], v[168:171], v[184:187], v[6:9]
	v_mfma_f32_16x16x32_bf16 v[26:29], v[160:163], v[192:195], v[26:29]
	v_mfma_f32_16x16x32_bf16 v[22:25], v[168:171], v[192:195], v[22:25]
	v_mfma_f32_16x16x32_bf16 v[50:53], v[160:163], v[200:203], v[50:53]
	v_mfma_f32_16x16x32_bf16 v[46:49], v[168:171], v[200:203], v[46:49]
	v_mfma_f32_16x16x32_bf16 v[34:37], v[164:167], v[180:183], v[34:37]
	v_mfma_f32_16x16x32_bf16 v[2:5], v[172:175], v[180:183], v[2:5]
	v_mfma_f32_16x16x32_bf16 v[10:13], v[164:167], v[188:191], v[10:13]
	v_mfma_f32_16x16x32_bf16 v[6:9], v[172:175], v[188:191], v[6:9]
	v_mfma_f32_16x16x32_bf16 v[26:29], v[164:167], v[196:199], v[26:29]
	v_mfma_f32_16x16x32_bf16 v[22:25], v[172:175], v[196:199], v[22:25]
	v_mfma_f32_16x16x32_bf16 v[50:53], v[164:167], v[204:207], v[50:53]
	v_mfma_f32_16x16x32_bf16 v[46:49], v[172:175], v[204:207], v[46:49]
	s_barrier
	s_setprio 0
	s_add_i32 s96, s96, s87
	v_lshl_add_u64 v[208:209], s[76:77], 0, v[0:1]
	s_mov_b32 m0, s96
	ds_read_b128 v[176:179], v141 offset:16384
	ds_read_b128 v[180:183], v141 offset:17408
	ds_read_b128 v[184:187], v141 offset:18432
	ds_read_b128 v[188:191], v141 offset:19456
	ds_read_b128 v[192:195], v141 offset:20480
	ds_read_b128 v[196:199], v141 offset:21504
	ds_read_b128 v[200:203], v141 offset:22528
	ds_read_b128 v[204:207], v141 offset:23552
	global_load_lds_dwordx4 v[208:209], off
	s_add_i32 m0, s96, 0x2000
	s_add_u32 s96, s76, 0x80000
	v_lshl_add_u64 v[210:211], s[76:77], 0, v[122:123]
	s_addc_u32 s97, s77, 0
	s_add_i32 vcc_lo, vcc_lo, s87
	global_load_lds_dwordx4 v[210:211], off
	v_lshl_add_u64 v[212:213], s[96:97], 0, v[0:1]
	s_mov_b32 m0, vcc_lo
	v_lshl_add_u64 v[214:215], s[52:53], 0, v[122:123]
	global_load_lds_dwordx4 v[212:213], off
	v_lshl_add_u64 v[212:213], s[96:97], 0, v[122:123]
	s_add_i32 m0, vcc_lo, 0x2000
	s_nop 0
	global_load_lds_dwordx4 v[212:213], off
	v_lshl_add_u64 v[212:213], s[52:53], 0, v[0:1]
	s_mov_b32 m0, s35
	s_nop 0
	global_load_lds_dwordx4 v[212:213], off
	s_mov_b32 m0, s28
	s_nop 0
	global_load_lds_dwordx4 v[214:215], off
	s_waitcnt vmcnt(8)
	s_waitcnt lgkmcnt(0)
	s_setprio 1
	s_barrier
; #define PG8_STAGE(bufoff, gbase, voff) do { _Pragma("unroll") for (int _i = 0; _i < 2; ++_i) \
;         __builtin_amdgcn_global_load_lds((const unsigned*)((const char*)(gbase) + (voff)[_i]), (LAS unsigned*)(lds + (bufoff) + ldsw + _i * 8192), 16, 0, 0); } while (0)
; #define PG8_LDA(dst, b, h) do { _Pragma("unroll") for (int m = 0; m < 4; ++m) _Pragma("unroll") for (int k = 0; k < 2; ++k) dst[m][k] = *(const LAS bf16x8*)(lds + PG8_SA(b, h) + aoff + m * 2048 + k * 1024); } while (0)
; #define PG8_LDB(dst, b, h) do { _Pragma("unroll") for (int n = 0; n < 2; ++n) _Pragma("unroll") for (int k = 0; k < 2; ++k) dst[n][k] = *(const LAS bf16x8*)(lds + PG8_SB(b, h) + boff + n * 2048 + k * 1024); } while (0)
; #define PG8_MMA(ai, bj, At, Bt) do { __builtin_amdgcn_s_setprio(1); _Pragma("unroll") for (int m = 0; m < 4; ++m) _Pragma("unroll") for (int n = 0; n < 2; ++n) _Pragma("unroll") for (int k = 0; k < 2; ++k) \
;         acc[ai][bj][m][n] = __builtin_amdgcn_mfma_f32_16x16x32_bf16(Bt[n][k], At[m][k], acc[ai][bj][m][n], 0, 0, 0); __builtin_amdgcn_s_setprio(0); } while (0)
; #define PG8_WAIT_V(n) asm volatile("s_waitcnt vmcnt(" #n ")" ::: "memory")
; #define PG8_WAIT_L(n) asm volatile("s_waitcnt lgkmcnt(" #n ")" ::: "memory")
; #define PG8_BAR __builtin_amdgcn_s_barrier()
; #define PG8_SCHED __builtin_amdgcn_sched_barrier(0)
; template <class Epi, class Sched, bool ALIGN_EPI, bool LAST_FUSED = false, bool PERM = false, bool CARRY = false>
; __device__ __forceinline__ void gemm_phase(LAS unsigned char* lds, const int tid, const int K, const int lda, const int ldb, const Sched& S, const Epi& E) {
;     ...
;             PG8_WAIT_V(8); PG8_WAIT_L(0); PG8_BAR; PG8_MMA(1, 0, At, B0); PG8_MMA(1, 1, At, B1); PG8_BAR; PG8_SCHED;
;             PG8_LDB(B0, 1, 0); PG8_LDB(B1, 1, 1); PG8_SCHED; PG8_LDA(At, 1, 0); PG8_STAGE(PG8_SA(0, 1), a2 + hstepA, voffA);
;             PG8_WAIT_V(8); PG8_WAIT_L(0); PG8_BAR; PG8_MMA(0, 0, At, B0); PG8_MMA(0, 1, At, B1); PG8_BAR; PG8_SCHED;
;             PG8_LDA(At, 1, 1); PG8_STAGE(PG8_SB(1, 0), b3, voffB); PG8_STAGE(PG8_SB(1, 1), b3 + hstepB, voffB); PG8_STAGE(PG8_SA(1, 0), a3, voffA);
;             PG8_WAIT_V(8); PG8_WAIT_L(0); PG8_BAR; PG8_MMA(1, 0, At, B0); PG8_MMA(1, 1, At, B1); PG8_BAR; PG8_SCHED;
	v_mfma_f32_16x16x32_bf16 v[78:81], v[142:145], v[176:179], v[78:81]
	v_mfma_f32_16x16x32_bf16 v[74:77], v[150:153], v[176:179], v[74:77]
	v_mfma_f32_16x16x32_bf16 v[98:101], v[142:145], v[184:187], v[98:101]
	v_mfma_f32_16x16x32_bf16 v[94:97], v[150:153], v[184:187], v[94:97]
	v_mfma_f32_16x16x32_bf16 v[118:121], v[142:145], v[192:195], v[118:121]
	v_mfma_f32_16x16x32_bf16 v[114:117], v[150:153], v[192:195], v[114:117]
	v_mfma_f32_16x16x32_bf16 v[134:137], v[142:145], v[200:203], v[134:137]
	v_mfma_f32_16x16x32_bf16 v[130:133], v[150:153], v[200:203], v[130:133]
	v_mfma_f32_16x16x32_bf16 v[78:81], v[146:149], v[180:183], v[78:81]
	v_mfma_f32_16x16x32_bf16 v[74:77], v[156:159], v[180:183], v[74:77]
	v_mfma_f32_16x16x32_bf16 v[98:101], v[146:149], v[188:191], v[98:101]
	v_mfma_f32_16x16x32_bf16 v[94:97], v[156:159], v[188:191], v[94:97]
	v_mfma_f32_16x16x32_bf16 v[118:121], v[146:149], v[196:199], v[118:121]
	v_mfma_f32_16x16x32_bf16 v[114:117], v[156:159], v[196:199], v[114:117]
	v_mfma_f32_16x16x32_bf16 v[134:137], v[146:149], v[204:207], v[134:137]
	v_mfma_f32_16x16x32_bf16 v[130:133], v[156:159], v[204:207], v[130:133]
	s_setprio 0
	s_setprio 1
	v_mfma_f32_16x16x32_bf16 v[70:73], v[160:163], v[176:179], v[70:73]
	v_mfma_f32_16x16x32_bf16 v[66:69], v[168:171], v[176:179], v[66:69]
	v_mfma_f32_16x16x32_bf16 v[90:93], v[160:163], v[184:187], v[90:93]
	v_mfma_f32_16x16x32_bf16 v[86:89], v[168:171], v[184:187], v[86:89]
	v_mfma_f32_16x16x32_bf16 v[110:113], v[160:163], v[192:195], v[110:113]
	v_mfma_f32_16x16x32_bf16 v[106:109], v[168:171], v[192:195], v[106:109]
	v_mfma_f32_16x16x32_bf16 v[102:105], v[160:163], v[200:203], v[102:105]
	v_mfma_f32_16x16x32_bf16 v[82:85], v[168:171], v[200:203], v[82:85]
	v_mfma_f32_16x16x32_bf16 v[70:73], v[164:167], v[180:183], v[70:73]
	v_mfma_f32_16x16x32_bf16 v[66:69], v[172:175], v[180:183], v[66:69]
	v_mfma_f32_16x16x32_bf16 v[90:93], v[164:167], v[188:191], v[90:93]
	v_mfma_f32_16x16x32_bf16 v[86:89], v[172:175], v[188:191], v[86:89]
	v_mfma_f32_16x16x32_bf16 v[110:113], v[164:167], v[196:199], v[110:113]
	v_mfma_f32_16x16x32_bf16 v[106:109], v[172:175], v[196:199], v[106:109]
	v_mfma_f32_16x16x32_bf16 v[102:105], v[164:167], v[204:207], v[102:105]
	v_mfma_f32_16x16x32_bf16 v[82:85], v[172:175], v[204:207], v[82:85]
	s_barrier
	s_setprio 0
	s_add_i32 s96, 0, 0x18000
	s_add_i32 s97, 0, 0x1c000
	v_add_u32_e32 v156, s96, v140
	v_add_u32_e32 v172, s97, v140
	ds_read_b128 v[142:145], v156
	ds_read_b128 v[146:149], v156 offset:1024
	ds_read_b128 v[150:153], v156 offset:2048
	ds_read_b128 v[156:159], v156 offset:3072
	ds_read_b128 v[160:163], v172
	ds_read_b128 v[164:167], v172 offset:1024
	ds_read_b128 v[168:171], v172 offset:2048
	ds_read_b128 v[172:175], v172 offset:3072
	s_add_u32 s52, s52, 0x80000
	s_addc_u32 s53, s53, 0
	s_mov_b32 m0, s29
	v_lshl_add_u64 v[216:217], s[52:53], 0, v[0:1]
	ds_read_b128 v[176:179], v141 offset:32768
	ds_read_b128 v[180:183], v141 offset:33792
	ds_read_b128 v[184:187], v141 offset:34816
	ds_read_b128 v[188:191], v141 offset:35840
	ds_read_b128 v[192:195], v141 offset:36864
	ds_read_b128 v[196:199], v141 offset:37888
	ds_read_b128 v[200:203], v141 offset:38912
	ds_read_b128 v[204:207], v141 offset:39936
	global_load_lds_dwordx4 v[216:217], off
	v_lshl_add_u64 v[216:217], s[52:53], 0, v[122:123]
	s_mov_b32 m0, s14
	s_nop 0
	global_load_lds_dwordx4 v[216:217], off
	s_waitcnt vmcnt(8)
	s_waitcnt lgkmcnt(0)
	s_setprio 1
	s_barrier
	v_mfma_f32_16x16x32_bf16 v[62:65], v[142:145], v[176:179], v[62:65]
	v_mfma_f32_16x16x32_bf16 v[42:45], v[150:153], v[176:179], v[42:45]
	v_mfma_f32_16x16x32_bf16 v[18:21], v[142:145], v[184:187], v[18:21]
	v_mfma_f32_16x16x32_bf16 v[14:17], v[150:153], v[184:187], v[14:17]
	v_mfma_f32_16x16x32_bf16 v[38:41], v[142:145], v[192:195], v[38:41]
	v_mfma_f32_16x16x32_bf16 v[30:33], v[150:153], v[192:195], v[30:33]
	v_mfma_f32_16x16x32_bf16 v[58:61], v[142:145], v[200:203], v[58:61]
	v_mfma_f32_16x16x32_bf16 v[54:57], v[150:153], v[200:203], v[54:57]
	v_mfma_f32_16x16x32_bf16 v[62:65], v[146:149], v[180:183], v[62:65]
	v_mfma_f32_16x16x32_bf16 v[42:45], v[156:159], v[180:183], v[42:45]
	v_mfma_f32_16x16x32_bf16 v[18:21], v[146:149], v[188:191], v[18:21]
	v_mfma_f32_16x16x32_bf16 v[14:17], v[156:159], v[188:191], v[14:17]
	v_mfma_f32_16x16x32_bf16 v[38:41], v[146:149], v[196:199], v[38:41]
	v_mfma_f32_16x16x32_bf16 v[30:33], v[156:159], v[196:199], v[30:33]
	v_mfma_f32_16x16x32_bf16 v[58:61], v[146:149], v[204:207], v[58:61]
	v_mfma_f32_16x16x32_bf16 v[54:57], v[156:159], v[204:207], v[54:57]
	s_setprio 0
	s_setprio 1
	v_mfma_f32_16x16x32_bf16 v[34:37], v[160:163], v[176:179], v[34:37]
	v_mfma_f32_16x16x32_bf16 v[2:5], v[168:171], v[176:179], v[2:5]
	v_mfma_f32_16x16x32_bf16 v[10:13], v[160:163], v[184:187], v[10:13]
	v_mfma_f32_16x16x32_bf16 v[6:9], v[168:171], v[184:187], v[6:9]
	v_mfma_f32_16x16x32_bf16 v[26:29], v[160:163], v[192:195], v[26:29]
	v_mfma_f32_16x16x32_bf16 v[22:25], v[168:171], v[192:195], v[22:25]
	v_mfma_f32_16x16x32_bf16 v[50:53], v[160:163], v[200:203], v[50:53]
	v_mfma_f32_16x16x32_bf16 v[46:49], v[168:171], v[200:203], v[46:49]
	v_mfma_f32_16x16x32_bf16 v[34:37], v[164:167], v[180:183], v[34:37]
	v_mfma_f32_16x16x32_bf16 v[2:5], v[172:175], v[180:183], v[2:5]
	v_mfma_f32_16x16x32_bf16 v[10:13], v[164:167], v[188:191], v[10:13]
	v_mfma_f32_16x16x32_bf16 v[6:9], v[172:175], v[188:191], v[6:9]
	v_mfma_f32_16x16x32_bf16 v[26:29], v[164:167], v[196:199], v[26:29]
	v_mfma_f32_16x16x32_bf16 v[22:25], v[172:175], v[196:199], v[22:25]
	v_mfma_f32_16x16x32_bf16 v[50:53], v[164:167], v[204:207], v[50:53]
	v_mfma_f32_16x16x32_bf16 v[46:49], v[172:175], v[204:207], v[46:49]
	s_barrier
; #define PG8_STAGE(bufoff, gbase, voff) do { _Pragma("unroll") for (int _i = 0; _i < 2; ++_i) \
;         __builtin_amdgcn_global_load_lds((const unsigned*)((const char*)(gbase) + (voff)[_i]), (LAS unsigned*)(lds + (bufoff) + ldsw + _i * 8192), 16, 0, 0); } while (0)
; #define PG8_LDA(dst, b, h) do { _Pragma("unroll") for (int m = 0; m < 4; ++m) _Pragma("unroll") for (int k = 0; k < 2; ++k) dst[m][k] = *(const LAS bf16x8*)(lds + PG8_SA(b, h) + aoff + m * 2048 + k * 1024); } while (0)
; #define PG8_MMA(ai, bj, At, Bt) do { __builtin_amdgcn_s_setprio(1); _Pragma("unroll") for (int m = 0; m < 4; ++m) _Pragma("unroll") for (int n = 0; n < 2; ++n) _Pragma("unroll") for (int k = 0; k < 2; ++k) \
;         acc[ai][bj][m][n] = __builtin_amdgcn_mfma_f32_16x16x32_bf16(Bt[n][k], At[m][k], acc[ai][bj][m][n], 0, 0, 0); __builtin_amdgcn_s_setprio(0); } while (0)
; #define PG8_WAIT_V(n) asm volatile("s_waitcnt vmcnt(" #n ")" ::: "memory")
; #define PG8_WAIT_L(n) asm volatile("s_waitcnt lgkmcnt(" #n ")" ::: "memory")
; #define PG8_BAR __builtin_amdgcn_s_barrier()
; #define PG8_SCHED __builtin_amdgcn_sched_barrier(0)
; template <class Epi, class Sched, bool ALIGN_EPI, bool LAST_FUSED = false, bool PERM = false, bool CARRY = false>
; __device__ __forceinline__ void gemm_phase(LAS unsigned char* lds, const int tid, const int K, const int lda, const int ldb, const Sched& S, const Epi& E) {
;     ...
;             PG8_LDA(At, 1, 1); PG8_STAGE(PG8_SB(1, 0), b3, voffB); PG8_STAGE(PG8_SB(1, 1), b3 + hstepB, voffB); PG8_STAGE(PG8_SA(1, 0), a3, voffA);
;             PG8_WAIT_V(8); PG8_WAIT_L(0); PG8_BAR; PG8_MMA(1, 0, At, B0); PG8_MMA(1, 1, At, B1); PG8_BAR; PG8_SCHED;
;         }
;         if constexpr (ALIGN_EPI) { if (wr == 0) PG8_BAR; }
	s_setprio 0
	s_add_i32 s52, s96, s87
	v_lshl_add_u64 v[208:209], v[208:209], 0, s[68:69]
	s_mov_b32 m0, s52
	ds_read_b128 v[176:179], v141 offset:49152
	ds_read_b128 v[180:183], v141 offset:50176
	ds_read_b128 v[184:187], v141 offset:51200
	ds_read_b128 v[188:191], v141 offset:52224
	ds_read_b128 v[192:195], v141 offset:53248
	ds_read_b128 v[196:199], v141 offset:54272
	ds_read_b128 v[200:203], v141 offset:55296
	ds_read_b128 v[204:207], v141 offset:56320
	global_load_lds_dwordx4 v[208:209], off
	s_add_i32 m0, s52, 0x2000
	s_add_u32 s52, s76, 0x80080
	v_lshl_add_u64 v[208:209], v[210:211], 0, s[68:69]
	s_addc_u32 s53, s77, 0
	s_add_i32 s76, s97, s87
	global_load_lds_dwordx4 v[208:209], off
	v_lshl_add_u64 v[208:209], s[52:53], 0, v[0:1]
	s_mov_b32 m0, s76
	s_nop 0
	global_load_lds_dwordx4 v[208:209], off
	v_lshl_add_u64 v[208:209], s[52:53], 0, v[122:123]
	s_add_i32 m0, s76, 0x2000
	s_nop 0
	global_load_lds_dwordx4 v[208:209], off
	v_lshl_add_u64 v[208:209], v[212:213], 0, s[68:69]
	s_mov_b32 m0, s85
	s_nop 0
	global_load_lds_dwordx4 v[208:209], off
	v_lshl_add_u64 v[208:209], v[214:215], 0, s[68:69]
	s_mov_b32 m0, s89
	s_nop 0
	global_load_lds_dwordx4 v[208:209], off
	s_waitcnt vmcnt(8)
	s_waitcnt lgkmcnt(0)
	s_setprio 1
	s_barrier
	v_mfma_f32_16x16x32_bf16 v[78:81], v[142:145], v[176:179], v[78:81]
	v_mfma_f32_16x16x32_bf16 v[74:77], v[150:153], v[176:179], v[74:77]
	v_mfma_f32_16x16x32_bf16 v[98:101], v[142:145], v[184:187], v[98:101]
	v_mfma_f32_16x16x32_bf16 v[94:97], v[150:153], v[184:187], v[94:97]
	v_mfma_f32_16x16x32_bf16 v[118:121], v[142:145], v[192:195], v[118:121]
	v_mfma_f32_16x16x32_bf16 v[114:117], v[150:153], v[192:195], v[114:117]
	v_mfma_f32_16x16x32_bf16 v[134:137], v[142:145], v[200:203], v[134:137]
	v_mfma_f32_16x16x32_bf16 v[130:133], v[150:153], v[200:203], v[130:133]
	v_mfma_f32_16x16x32_bf16 v[78:81], v[146:149], v[180:183], v[78:81]
	v_mfma_f32_16x16x32_bf16 v[74:77], v[156:159], v[180:183], v[74:77]
	v_mfma_f32_16x16x32_bf16 v[98:101], v[146:149], v[188:191], v[98:101]
	v_mfma_f32_16x16x32_bf16 v[94:97], v[156:159], v[188:191], v[94:97]
	v_mfma_f32_16x16x32_bf16 v[118:121], v[146:149], v[196:199], v[118:121]
	v_mfma_f32_16x16x32_bf16 v[114:117], v[156:159], v[196:199], v[114:117]
	v_mfma_f32_16x16x32_bf16 v[134:137], v[146:149], v[204:207], v[134:137]
	v_mfma_f32_16x16x32_bf16 v[130:133], v[156:159], v[204:207], v[130:133]
	s_setprio 0
	s_setprio 1
	v_mfma_f32_16x16x32_bf16 v[70:73], v[160:163], v[176:179], v[70:73]
	v_mfma_f32_16x16x32_bf16 v[66:69], v[168:171], v[176:179], v[66:69]
	v_mfma_f32_16x16x32_bf16 v[90:93], v[160:163], v[184:187], v[90:93]
	v_mfma_f32_16x16x32_bf16 v[86:89], v[168:171], v[184:187], v[86:89]
	v_mfma_f32_16x16x32_bf16 v[110:113], v[160:163], v[192:195], v[110:113]
	v_mfma_f32_16x16x32_bf16 v[106:109], v[168:171], v[192:195], v[106:109]
	v_mfma_f32_16x16x32_bf16 v[102:105], v[160:163], v[200:203], v[102:105]
	v_mfma_f32_16x16x32_bf16 v[82:85], v[168:171], v[200:203], v[82:85]
	v_mfma_f32_16x16x32_bf16 v[70:73], v[164:167], v[180:183], v[70:73]
	v_mfma_f32_16x16x32_bf16 v[66:69], v[172:175], v[180:183], v[66:69]
	v_mfma_f32_16x16x32_bf16 v[90:93], v[164:167], v[188:191], v[90:93]
	v_mfma_f32_16x16x32_bf16 v[86:89], v[172:175], v[188:191], v[86:89]
	v_mfma_f32_16x16x32_bf16 v[110:113], v[164:167], v[196:199], v[110:113]
	v_mfma_f32_16x16x32_bf16 v[106:109], v[172:175], v[196:199], v[106:109]
	v_mfma_f32_16x16x32_bf16 v[102:105], v[164:167], v[204:207], v[102:105]
	v_mfma_f32_16x16x32_bf16 v[82:85], v[172:175], v[204:207], v[82:85]
	s_barrier
	s_setprio 0
	s_add_i32 s52, s95, 2
	s_add_u32 s48, s48, 0x100
	s_addc_u32 s49, s49, 0
	v_lshl_add_u64 v[138:139], v[138:139], 0, s[72:73]
	v_lshl_add_u64 v[128:129], v[128:129], 0, s[72:73]
	s_cmp_ge_i32 s95, s3
	s_mov_b32 s95, s52
	s_cbranch_scc0 .LBB0_1585
	s_and_b64 vcc, exec, s[36:37]
	s_cbranch_vccz .LBB0_1588
	s_barrier

; #define PG8_STAGE(bufoff, gbase, voff) do { _Pragma("unroll") for (int _i = 0; _i < 2; ++_i) \
;         __builtin_amdgcn_global_load_lds((const unsigned*)((const char*)(gbase) + (voff)[_i]), (LAS unsigned*)(lds + (bufoff) + ldsw + _i * 8192), 16, 0, 0); } while (0)
; #define PG8_LDA(dst, b, h) do { _Pragma("unroll") for (int m = 0; m < 4; ++m) _Pragma("unroll") for (int k = 0; k < 2; ++k) dst[m][k] = *(const LAS bf16x8*)(lds + PG8_SA(b, h) + aoff + m * 2048 + k * 1024); } while (0)
; #define PG8_LDB(dst, b, h) do { _Pragma("unroll") for (int n = 0; n < 2; ++n) _Pragma("unroll") for (int k = 0; k < 2; ++k) dst[n][k] = *(const LAS bf16x8*)(lds + PG8_SB(b, h) + boff + n * 2048 + k * 1024); } while (0)
; #define PG8_MMA(ai, bj, At, Bt) do { __builtin_amdgcn_s_setprio(1); _Pragma("unroll") for (int m = 0; m < 4; ++m) _Pragma("unroll") for (int n = 0; n < 2; ++n) _Pragma("unroll") for (int k = 0; k < 2; ++k) \
;         acc[ai][bj][m][n] = __builtin_amdgcn_mfma_f32_16x16x32_bf16(Bt[n][k], At[m][k], acc[ai][bj][m][n], 0, 0, 0); __builtin_amdgcn_s_setprio(0); } while (0)
; #define PG8_WAIT_V(n) asm volatile("s_waitcnt vmcnt(" #n ")" ::: "memory")
; #define PG8_WAIT_L(n) asm volatile("s_waitcnt lgkmcnt(" #n ")" ::: "memory")
; template <class Epi, class Sched, bool ALIGN_EPI, bool LAST_FUSED = false, bool PERM = false, bool CARRY = false>
; __device__ __forceinline__ void gemm_phase(LAS unsigned char* lds, const int tid, const int K, const int lda, const int ldb, const Sched& S, const Epi& E) {
;     ...
;         for (int t = 0; t < nt; t += 2) {
;             const bool last = (t == nt - 2);
;             const char* a1 = cA + (size_t)(t + 1) * kstep;
;             const char* a2 = last ? nA : cA + (size_t)(t + 2) * kstep; const char* b2 = last ? nB : cB + (size_t)(t + 2) * kstep;
;             const char* a3 = a2 + kstep; const char* b3 = b2 + kstep;
;             PG8_LDB(B0, 0, 0); PG8_LDB(B1, 0, 1); PG8_SCHED; PG8_LDA(At, 0, 0); PG8_STAGE(PG8_SA(1, 1), a1 + hstepA, voffA);
;             PG8_WAIT_V(8); PG8_WAIT_L(0); PG8_BAR; PG8_MMA(0, 0, At, B0); PG8_MMA(0, 1, At, B1); PG8_BAR; PG8_SCHED;
;             PG8_LDA(At, 0, 1); PG8_STAGE(PG8_SB(0, 0), b2, voffB); PG8_STAGE(PG8_SB(0, 1), b2 + hstepB, voffB); PG8_STAGE(PG8_SA(0, 0), a2, voffA);
;             PG8_WAIT_V(8); PG8_WAIT_L(0); PG8_BAR; PG8_MMA(1, 0, At, B0); PG8_MMA(1, 1, At, B1); PG8_BAR; PG8_SCHED;
.LBB0_1662:
	s_add_u32 s52, s38, s48
	s_addc_u32 s53, s39, s49
	s_add_u32 s66, s40, s48
	s_addc_u32 s67, s41, s49
	s_waitcnt lgkmcnt(0)
	s_add_i32 s90, 0, 0x10000
	s_cmp_eq_u32 s3, s89
	s_cselect_b32 s53, s24, s53
	s_cselect_b32 s52, s85, s52
	s_cselect_b32 s67, s86, s67
	s_cselect_b32 s66, s87, s66
	s_add_i32 s92, 0, 0x14000
	v_add_u32_e32 v156, s90, v140
	v_add_u32_e32 v172, s92, v140
	ds_read_b128 v[142:145], v156
	ds_read_b128 v[146:149], v156 offset:1024
	ds_read_b128 v[150:153], v156 offset:2048
	ds_read_b128 v[156:159], v156 offset:3072
	ds_read_b128 v[160:163], v172
	ds_read_b128 v[164:167], v172 offset:1024
	ds_read_b128 v[168:171], v172 offset:2048
	ds_read_b128 v[172:175], v172 offset:3072
	v_lshl_add_u64 v[208:209], s[38:39], 0, v[138:139]
	s_add_i32 m0, s35, 0xc000
	ds_read_b128 v[176:179], v141
	ds_read_b128 v[180:183], v141 offset:1024
	ds_read_b128 v[184:187], v141 offset:2048
	ds_read_b128 v[188:191], v141 offset:3072
	ds_read_b128 v[192:195], v141 offset:4096
	ds_read_b128 v[196:199], v141 offset:5120
	ds_read_b128 v[200:203], v141 offset:6144
	ds_read_b128 v[204:207], v141 offset:7168
	global_load_lds_dwordx4 v[208:209], off
	v_lshl_add_u64 v[208:209], s[38:39], 0, v[128:129]
	s_add_i32 m0, s35, 0xe000
	s_nop 0
	global_load_lds_dwordx4 v[208:209], off
	s_waitcnt vmcnt(8)
	s_waitcnt lgkmcnt(0)
	s_setprio 1
	s_barrier
	v_mfma_f32_16x16x32_bf16 v[62:65], v[142:145], v[176:179], v[62:65]
	v_mfma_f32_16x16x32_bf16 v[42:45], v[150:153], v[176:179], v[42:45]
	v_mfma_f32_16x16x32_bf16 v[18:21], v[142:145], v[184:187], v[18:21]
	v_mfma_f32_16x16x32_bf16 v[14:17], v[150:153], v[184:187], v[14:17]
	v_mfma_f32_16x16x32_bf16 v[38:41], v[142:145], v[192:195], v[38:41]
	v_mfma_f32_16x16x32_bf16 v[30:33], v[150:153], v[192:195], v[30:33]
	v_mfma_f32_16x16x32_bf16 v[58:61], v[142:145], v[200:203], v[58:61]
	v_mfma_f32_16x16x32_bf16 v[54:57], v[150:153], v[200:203], v[54:57]
	v_mfma_f32_16x16x32_bf16 v[62:65], v[146:149], v[180:183], v[62:65]
	v_mfma_f32_16x16x32_bf16 v[42:45], v[156:159], v[180:183], v[42:45]
	v_mfma_f32_16x16x32_bf16 v[18:21], v[146:149], v[188:191], v[18:21]
	v_mfma_f32_16x16x32_bf16 v[14:17], v[156:159], v[188:191], v[14:17]
	v_mfma_f32_16x16x32_bf16 v[38:41], v[146:149], v[196:199], v[38:41]
	v_mfma_f32_16x16x32_bf16 v[30:33], v[156:159], v[196:199], v[30:33]
	v_mfma_f32_16x16x32_bf16 v[58:61], v[146:149], v[204:207], v[58:61]
	v_mfma_f32_16x16x32_bf16 v[54:57], v[156:159], v[204:207], v[54:57]
	s_setprio 0
	s_setprio 1
	v_mfma_f32_16x16x32_bf16 v[34:37], v[160:163], v[176:179], v[34:37]
	v_mfma_f32_16x16x32_bf16 v[2:5], v[168:171], v[176:179], v[2:5]
	v_mfma_f32_16x16x32_bf16 v[10:13], v[160:163], v[184:187], v[10:13]
	v_mfma_f32_16x16x32_bf16 v[6:9], v[168:171], v[184:187], v[6:9]
	v_mfma_f32_16x16x32_bf16 v[26:29], v[160:163], v[192:195], v[26:29]
	v_mfma_f32_16x16x32_bf16 v[22:25], v[168:171], v[192:195], v[22:25]
	v_mfma_f32_16x16x32_bf16 v[50:53], v[160:163], v[200:203], v[50:53]
	v_mfma_f32_16x16x32_bf16 v[46:49], v[168:171], v[200:203], v[46:49]
	v_mfma_f32_16x16x32_bf16 v[34:37], v[164:167], v[180:183], v[34:37]
	v_mfma_f32_16x16x32_bf16 v[2:5], v[172:175], v[180:183], v[2:5]
	v_mfma_f32_16x16x32_bf16 v[10:13], v[164:167], v[188:191], v[10:13]
	v_mfma_f32_16x16x32_bf16 v[6:9], v[172:175], v[188:191], v[6:9]
	v_mfma_f32_16x16x32_bf16 v[26:29], v[164:167], v[196:199], v[26:29]
	v_mfma_f32_16x16x32_bf16 v[22:25], v[172:175], v[196:199], v[22:25]
	v_mfma_f32_16x16x32_bf16 v[50:53], v[164:167], v[204:207], v[50:53]
	v_mfma_f32_16x16x32_bf16 v[46:49], v[172:175], v[204:207], v[46:49]
	s_barrier
	s_setprio 0
	s_add_i32 s90, s90, s76
	v_lshl_add_u64 v[208:209], s[66:67], 0, v[0:1]
	s_mov_b32 m0, s90
	ds_read_b128 v[176:179], v141 offset:16384
	ds_read_b128 v[180:183], v141 offset:17408
	ds_read_b128 v[184:187], v141 offset:18432
	ds_read_b128 v[188:191], v141 offset:19456
	ds_read_b128 v[192:195], v141 offset:20480
	ds_read_b128 v[196:199], v141 offset:21504
	ds_read_b128 v[200:203], v141 offset:22528
	ds_read_b128 v[204:207], v141 offset:23552
	global_load_lds_dwordx4 v[208:209], off
	s_add_i32 m0, s90, 0x2000
	s_add_u32 s90, s66, 0x100000
	v_lshl_add_u64 v[210:211], s[66:67], 0, v[122:123]
	s_addc_u32 s91, s67, 0
	s_add_i32 s92, s92, s76
	global_load_lds_dwordx4 v[210:211], off
	v_lshl_add_u64 v[212:213], s[90:91], 0, v[0:1]
	s_mov_b32 m0, s92
	v_lshl_add_u64 v[214:215], s[52:53], 0, v[122:123]
	global_load_lds_dwordx4 v[212:213], off
	v_lshl_add_u64 v[212:213], s[90:91], 0, v[122:123]
	s_add_i32 m0, s92, 0x2000
	s_nop 0
	global_load_lds_dwordx4 v[212:213], off
	v_lshl_add_u64 v[212:213], s[52:53], 0, v[0:1]
	s_mov_b32 m0, s35
	s_nop 0
	global_load_lds_dwordx4 v[212:213], off
	s_mov_b32 m0, s28
	s_nop 0
	global_load_lds_dwordx4 v[214:215], off
	s_waitcnt vmcnt(8)
	s_waitcnt lgkmcnt(0)
	s_setprio 1
	s_barrier
; #define PG8_STAGE(bufoff, gbase, voff) do { _Pragma("unroll") for (int _i = 0; _i < 2; ++_i) \
;         __builtin_amdgcn_global_load_lds((const unsigned*)((const char*)(gbase) + (voff)[_i]), (LAS unsigned*)(lds + (bufoff) + ldsw + _i * 8192), 16, 0, 0); } while (0)
; #define PG8_LDA(dst, b, h) do { _Pragma("unroll") for (int m = 0; m < 4; ++m) _Pragma("unroll") for (int k = 0; k < 2; ++k) dst[m][k] = *(const LAS bf16x8*)(lds + PG8_SA(b, h) + aoff + m * 2048 + k * 1024); } while (0)
; #define PG8_LDB(dst, b, h) do { _Pragma("unroll") for (int n = 0; n < 2; ++n) _Pragma("unroll") for (int k = 0; k < 2; ++k) dst[n][k] = *(const LAS bf16x8*)(lds + PG8_SB(b, h) + boff + n * 2048 + k * 1024); } while (0)
; #define PG8_MMA(ai, bj, At, Bt) do { __builtin_amdgcn_s_setprio(1); _Pragma("unroll") for (int m = 0; m < 4; ++m) _Pragma("unroll") for (int n = 0; n < 2; ++n) _Pragma("unroll") for (int k = 0; k < 2; ++k) \
;         acc[ai][bj][m][n] = __builtin_amdgcn_mfma_f32_16x16x32_bf16(Bt[n][k], At[m][k], acc[ai][bj][m][n], 0, 0, 0); __builtin_amdgcn_s_setprio(0); } while (0)
; #define PG8_WAIT_V(n) asm volatile("s_waitcnt vmcnt(" #n ")" ::: "memory")
; #define PG8_WAIT_L(n) asm volatile("s_waitcnt lgkmcnt(" #n ")" ::: "memory")
; #define PG8_BAR __builtin_amdgcn_s_barrier()
; #define PG8_SCHED __builtin_amdgcn_sched_barrier(0)
; template <class Epi, class Sched, bool ALIGN_EPI, bool LAST_FUSED = false, bool PERM = false, bool CARRY = false>
; __device__ __forceinline__ void gemm_phase(LAS unsigned char* lds, const int tid, const int K, const int lda, const int ldb, const Sched& S, const Epi& E) {
;     ...
;             PG8_WAIT_V(8); PG8_WAIT_L(0); PG8_BAR; PG8_MMA(1, 0, At, B0); PG8_MMA(1, 1, At, B1); PG8_BAR; PG8_SCHED;
;             PG8_LDB(B0, 1, 0); PG8_LDB(B1, 1, 1); PG8_SCHED; PG8_LDA(At, 1, 0); PG8_STAGE(PG8_SA(0, 1), a2 + hstepA, voffA);
;             PG8_WAIT_V(8); PG8_WAIT_L(0); PG8_BAR; PG8_MMA(0, 0, At, B0); PG8_MMA(0, 1, At, B1); PG8_BAR; PG8_SCHED;
;             PG8_LDA(At, 1, 1); PG8_STAGE(PG8_SB(1, 0), b3, voffB); PG8_STAGE(PG8_SB(1, 1), b3 + hstepB, voffB); PG8_STAGE(PG8_SA(1, 0), a3, voffA);
;             PG8_WAIT_V(8); PG8_WAIT_L(0); PG8_BAR; PG8_MMA(1, 0, At, B0); PG8_MMA(1, 1, At, B1); PG8_BAR; PG8_SCHED;
	v_mfma_f32_16x16x32_bf16 v[78:81], v[142:145], v[176:179], v[78:81]
	v_mfma_f32_16x16x32_bf16 v[74:77], v[150:153], v[176:179], v[74:77]
	v_mfma_f32_16x16x32_bf16 v[98:101], v[142:145], v[184:187], v[98:101]
	v_mfma_f32_16x16x32_bf16 v[94:97], v[150:153], v[184:187], v[94:97]
	v_mfma_f32_16x16x32_bf16 v[118:121], v[142:145], v[192:195], v[118:121]
	v_mfma_f32_16x16x32_bf16 v[114:117], v[150:153], v[192:195], v[114:117]
	v_mfma_f32_16x16x32_bf16 v[134:137], v[142:145], v[200:203], v[134:137]
	v_mfma_f32_16x16x32_bf16 v[130:133], v[150:153], v[200:203], v[130:133]
	v_mfma_f32_16x16x32_bf16 v[78:81], v[146:149], v[180:183], v[78:81]
	v_mfma_f32_16x16x32_bf16 v[74:77], v[156:159], v[180:183], v[74:77]
	v_mfma_f32_16x16x32_bf16 v[98:101], v[146:149], v[188:191], v[98:101]
	v_mfma_f32_16x16x32_bf16 v[94:97], v[156:159], v[188:191], v[94:97]
	v_mfma_f32_16x16x32_bf16 v[118:121], v[146:149], v[196:199], v[118:121]
	v_mfma_f32_16x16x32_bf16 v[114:117], v[156:159], v[196:199], v[114:117]
	v_mfma_f32_16x16x32_bf16 v[134:137], v[146:149], v[204:207], v[134:137]
	v_mfma_f32_16x16x32_bf16 v[130:133], v[156:159], v[204:207], v[130:133]
	s_setprio 0
	s_setprio 1
	v_mfma_f32_16x16x32_bf16 v[70:73], v[160:163], v[176:179], v[70:73]
	v_mfma_f32_16x16x32_bf16 v[66:69], v[168:171], v[176:179], v[66:69]
	v_mfma_f32_16x16x32_bf16 v[90:93], v[160:163], v[184:187], v[90:93]
	v_mfma_f32_16x16x32_bf16 v[86:89], v[168:171], v[184:187], v[86:89]
	v_mfma_f32_16x16x32_bf16 v[110:113], v[160:163], v[192:195], v[110:113]
	v_mfma_f32_16x16x32_bf16 v[106:109], v[168:171], v[192:195], v[106:109]
	v_mfma_f32_16x16x32_bf16 v[102:105], v[160:163], v[200:203], v[102:105]
	v_mfma_f32_16x16x32_bf16 v[82:85], v[168:171], v[200:203], v[82:85]
	v_mfma_f32_16x16x32_bf16 v[70:73], v[164:167], v[180:183], v[70:73]
	v_mfma_f32_16x16x32_bf16 v[66:69], v[172:175], v[180:183], v[66:69]
	v_mfma_f32_16x16x32_bf16 v[90:93], v[164:167], v[188:191], v[90:93]
	v_mfma_f32_16x16x32_bf16 v[86:89], v[172:175], v[188:191], v[86:89]
	v_mfma_f32_16x16x32_bf16 v[110:113], v[164:167], v[196:199], v[110:113]
	v_mfma_f32_16x16x32_bf16 v[106:109], v[172:175], v[196:199], v[106:109]
	v_mfma_f32_16x16x32_bf16 v[102:105], v[164:167], v[204:207], v[102:105]
	v_mfma_f32_16x16x32_bf16 v[82:85], v[172:175], v[204:207], v[82:85]
	s_barrier
	s_setprio 0
	s_add_i32 s90, 0, 0x18000
	s_add_i32 s91, 0, 0x1c000
	v_add_u32_e32 v156, s90, v140
	v_add_u32_e32 v172, s91, v140
	ds_read_b128 v[142:145], v156
	ds_read_b128 v[146:149], v156 offset:1024
	ds_read_b128 v[150:153], v156 offset:2048
	ds_read_b128 v[156:159], v156 offset:3072
	ds_read_b128 v[160:163], v172
	ds_read_b128 v[164:167], v172 offset:1024
	ds_read_b128 v[168:171], v172 offset:2048
	ds_read_b128 v[172:175], v172 offset:3072
	s_add_u32 s52, s52, 0x100000
	s_addc_u32 s53, s53, 0
	s_mov_b32 m0, s29
	v_lshl_add_u64 v[216:217], s[52:53], 0, v[0:1]
	ds_read_b128 v[176:179], v141 offset:32768
	ds_read_b128 v[180:183], v141 offset:33792
	ds_read_b128 v[184:187], v141 offset:34816
	ds_read_b128 v[188:191], v141 offset:35840
	ds_read_b128 v[192:195], v141 offset:36864
	ds_read_b128 v[196:199], v141 offset:37888
	ds_read_b128 v[200:203], v141 offset:38912
	ds_read_b128 v[204:207], v141 offset:39936
	global_load_lds_dwordx4 v[216:217], off
	v_lshl_add_u64 v[216:217], s[52:53], 0, v[122:123]
	s_mov_b32 m0, s14
	s_nop 0
	global_load_lds_dwordx4 v[216:217], off
	s_waitcnt vmcnt(8)
	s_waitcnt lgkmcnt(0)
	s_setprio 1
	s_barrier
	v_mfma_f32_16x16x32_bf16 v[62:65], v[142:145], v[176:179], v[62:65]
	v_mfma_f32_16x16x32_bf16 v[42:45], v[150:153], v[176:179], v[42:45]
	v_mfma_f32_16x16x32_bf16 v[18:21], v[142:145], v[184:187], v[18:21]
	v_mfma_f32_16x16x32_bf16 v[14:17], v[150:153], v[184:187], v[14:17]
	v_mfma_f32_16x16x32_bf16 v[38:41], v[142:145], v[192:195], v[38:41]
	v_mfma_f32_16x16x32_bf16 v[30:33], v[150:153], v[192:195], v[30:33]
	v_mfma_f32_16x16x32_bf16 v[58:61], v[142:145], v[200:203], v[58:61]
	v_mfma_f32_16x16x32_bf16 v[54:57], v[150:153], v[200:203], v[54:57]
	v_mfma_f32_16x16x32_bf16 v[62:65], v[146:149], v[180:183], v[62:65]
	v_mfma_f32_16x16x32_bf16 v[42:45], v[156:159], v[180:183], v[42:45]
	v_mfma_f32_16x16x32_bf16 v[18:21], v[146:149], v[188:191], v[18:21]
	v_mfma_f32_16x16x32_bf16 v[14:17], v[156:159], v[188:191], v[14:17]
	v_mfma_f32_16x16x32_bf16 v[38:41], v[146:149], v[196:199], v[38:41]
	v_mfma_f32_16x16x32_bf16 v[30:33], v[156:159], v[196:199], v[30:33]
	v_mfma_f32_16x16x32_bf16 v[58:61], v[146:149], v[204:207], v[58:61]
	v_mfma_f32_16x16x32_bf16 v[54:57], v[156:159], v[204:207], v[54:57]
	s_setprio 0
	s_setprio 1
	v_mfma_f32_16x16x32_bf16 v[34:37], v[160:163], v[176:179], v[34:37]
	v_mfma_f32_16x16x32_bf16 v[2:5], v[168:171], v[176:179], v[2:5]
	v_mfma_f32_16x16x32_bf16 v[10:13], v[160:163], v[184:187], v[10:13]
	v_mfma_f32_16x16x32_bf16 v[6:9], v[168:171], v[184:187], v[6:9]
	v_mfma_f32_16x16x32_bf16 v[26:29], v[160:163], v[192:195], v[26:29]
	v_mfma_f32_16x16x32_bf16 v[22:25], v[168:171], v[192:195], v[22:25]
	v_mfma_f32_16x16x32_bf16 v[50:53], v[160:163], v[200:203], v[50:53]
	v_mfma_f32_16x16x32_bf16 v[46:49], v[168:171], v[200:203], v[46:49]
	v_mfma_f32_16x16x32_bf16 v[34:37], v[164:167], v[180:183], v[34:37]
	v_mfma_f32_16x16x32_bf16 v[2:5], v[172:175], v[180:183], v[2:5]
	v_mfma_f32_16x16x32_bf16 v[10:13], v[164:167], v[188:191], v[10:13]
	v_mfma_f32_16x16x32_bf16 v[6:9], v[172:175], v[188:191], v[6:9]
	v_mfma_f32_16x16x32_bf16 v[26:29], v[164:167], v[196:199], v[26:29]
	v_mfma_f32_16x16x32_bf16 v[22:25], v[172:175], v[196:199], v[22:25]
	v_mfma_f32_16x16x32_bf16 v[50:53], v[164:167], v[204:207], v[50:53]
	v_mfma_f32_16x16x32_bf16 v[46:49], v[172:175], v[204:207], v[46:49]
	s_barrier
; #define PG8_STAGE(bufoff, gbase, voff) do { _Pragma("unroll") for (int _i = 0; _i < 2; ++_i) \
;         __builtin_amdgcn_global_load_lds((const unsigned*)((const char*)(gbase) + (voff)[_i]), (LAS unsigned*)(lds + (bufoff) + ldsw + _i * 8192), 16, 0, 0); } while (0)
; #define PG8_LDA(dst, b, h) do { _Pragma("unroll") for (int m = 0; m < 4; ++m) _Pragma("unroll") for (int k = 0; k < 2; ++k) dst[m][k] = *(const LAS bf16x8*)(lds + PG8_SA(b, h) + aoff + m * 2048 + k * 1024); } while (0)
; #define PG8_MMA(ai, bj, At, Bt) do { __builtin_amdgcn_s_setprio(1); _Pragma("unroll") for (int m = 0; m < 4; ++m) _Pragma("unroll") for (int n = 0; n < 2; ++n) _Pragma("unroll") for (int k = 0; k < 2; ++k) \
;         acc[ai][bj][m][n] = __builtin_amdgcn_mfma_f32_16x16x32_bf16(Bt[n][k], At[m][k], acc[ai][bj][m][n], 0, 0, 0); __builtin_amdgcn_s_setprio(0); } while (0)
; #define PG8_WAIT_V(n) asm volatile("s_waitcnt vmcnt(" #n ")" ::: "memory")
; #define PG8_WAIT_L(n) asm volatile("s_waitcnt lgkmcnt(" #n ")" ::: "memory")
; #define PG8_BAR __builtin_amdgcn_s_barrier()
; #define PG8_SCHED __builtin_amdgcn_sched_barrier(0)
; template <class Epi, class Sched, bool ALIGN_EPI, bool LAST_FUSED = false, bool PERM = false, bool CARRY = false>
; __device__ __forceinline__ void gemm_phase(LAS unsigned char* lds, const int tid, const int K, const int lda, const int ldb, const Sched& S, const Epi& E) {
;     ...
;             PG8_LDA(At, 1, 1); PG8_STAGE(PG8_SB(1, 0), b3, voffB); PG8_STAGE(PG8_SB(1, 1), b3 + hstepB, voffB); PG8_STAGE(PG8_SA(1, 0), a3, voffA);
;             PG8_WAIT_V(8); PG8_WAIT_L(0); PG8_BAR; PG8_MMA(1, 0, At, B0); PG8_MMA(1, 1, At, B1); PG8_BAR; PG8_SCHED;
;         }
;         if constexpr (ALIGN_EPI) { if (wr == 0) PG8_BAR; }
	s_setprio 0
	s_add_i32 s52, s90, s76
	v_lshl_add_u64 v[208:209], v[208:209], 0, s[68:69]
	s_mov_b32 m0, s52
	ds_read_b128 v[176:179], v141 offset:49152
	ds_read_b128 v[180:183], v141 offset:50176
	ds_read_b128 v[184:187], v141 offset:51200
	ds_read_b128 v[188:191], v141 offset:52224
	ds_read_b128 v[192:195], v141 offset:53248
	ds_read_b128 v[196:199], v141 offset:54272
	ds_read_b128 v[200:203], v141 offset:55296
	ds_read_b128 v[204:207], v141 offset:56320
	global_load_lds_dwordx4 v[208:209], off
	s_add_i32 m0, s52, 0x2000
	s_add_u32 s52, s66, 0x100080
	v_lshl_add_u64 v[208:209], v[210:211], 0, s[68:69]
	s_addc_u32 s53, s67, 0
	s_add_i32 s66, s91, s76
	global_load_lds_dwordx4 v[208:209], off
	v_lshl_add_u64 v[208:209], s[52:53], 0, v[0:1]
	s_mov_b32 m0, s66
	s_nop 0
	global_load_lds_dwordx4 v[208:209], off
	v_lshl_add_u64 v[208:209], s[52:53], 0, v[122:123]
	s_add_i32 m0, s66, 0x2000
	s_nop 0
	global_load_lds_dwordx4 v[208:209], off
	v_lshl_add_u64 v[208:209], v[212:213], 0, s[68:69]
	s_mov_b32 m0, s77
	s_nop 0
	global_load_lds_dwordx4 v[208:209], off
	v_lshl_add_u64 v[208:209], v[214:215], 0, s[68:69]
	s_mov_b32 m0, s79
	s_nop 0
	global_load_lds_dwordx4 v[208:209], off
	s_waitcnt vmcnt(8)
	s_waitcnt lgkmcnt(0)
	s_setprio 1
	s_barrier
	v_mfma_f32_16x16x32_bf16 v[78:81], v[142:145], v[176:179], v[78:81]
	v_mfma_f32_16x16x32_bf16 v[74:77], v[150:153], v[176:179], v[74:77]
	v_mfma_f32_16x16x32_bf16 v[98:101], v[142:145], v[184:187], v[98:101]
	v_mfma_f32_16x16x32_bf16 v[94:97], v[150:153], v[184:187], v[94:97]
	v_mfma_f32_16x16x32_bf16 v[118:121], v[142:145], v[192:195], v[118:121]
	v_mfma_f32_16x16x32_bf16 v[114:117], v[150:153], v[192:195], v[114:117]
	v_mfma_f32_16x16x32_bf16 v[134:137], v[142:145], v[200:203], v[134:137]
	v_mfma_f32_16x16x32_bf16 v[130:133], v[150:153], v[200:203], v[130:133]
	v_mfma_f32_16x16x32_bf16 v[78:81], v[146:149], v[180:183], v[78:81]
	v_mfma_f32_16x16x32_bf16 v[74:77], v[156:159], v[180:183], v[74:77]
	v_mfma_f32_16x16x32_bf16 v[98:101], v[146:149], v[188:191], v[98:101]
	v_mfma_f32_16x16x32_bf16 v[94:97], v[156:159], v[188:191], v[94:97]
	v_mfma_f32_16x16x32_bf16 v[118:121], v[146:149], v[196:199], v[118:121]
	v_mfma_f32_16x16x32_bf16 v[114:117], v[156:159], v[196:199], v[114:117]
	v_mfma_f32_16x16x32_bf16 v[134:137], v[146:149], v[204:207], v[134:137]
	v_mfma_f32_16x16x32_bf16 v[130:133], v[156:159], v[204:207], v[130:133]
	s_setprio 0
	s_setprio 1
	v_mfma_f32_16x16x32_bf16 v[70:73], v[160:163], v[176:179], v[70:73]
	v_mfma_f32_16x16x32_bf16 v[66:69], v[168:171], v[176:179], v[66:69]
	v_mfma_f32_16x16x32_bf16 v[90:93], v[160:163], v[184:187], v[90:93]
	v_mfma_f32_16x16x32_bf16 v[86:89], v[168:171], v[184:187], v[86:89]
	v_mfma_f32_16x16x32_bf16 v[110:113], v[160:163], v[192:195], v[110:113]
	v_mfma_f32_16x16x32_bf16 v[106:109], v[168:171], v[192:195], v[106:109]
	v_mfma_f32_16x16x32_bf16 v[102:105], v[160:163], v[200:203], v[102:105]
	v_mfma_f32_16x16x32_bf16 v[82:85], v[168:171], v[200:203], v[82:85]
	v_mfma_f32_16x16x32_bf16 v[70:73], v[164:167], v[180:183], v[70:73]
	v_mfma_f32_16x16x32_bf16 v[66:69], v[172:175], v[180:183], v[66:69]
	v_mfma_f32_16x16x32_bf16 v[90:93], v[164:167], v[188:191], v[90:93]
	v_mfma_f32_16x16x32_bf16 v[86:89], v[172:175], v[188:191], v[86:89]
	v_mfma_f32_16x16x32_bf16 v[110:113], v[164:167], v[196:199], v[110:113]
	v_mfma_f32_16x16x32_bf16 v[106:109], v[172:175], v[196:199], v[106:109]
	v_mfma_f32_16x16x32_bf16 v[102:105], v[164:167], v[204:207], v[102:105]
	v_mfma_f32_16x16x32_bf16 v[82:85], v[172:175], v[204:207], v[82:85]
	s_barrier
	s_setprio 0
	s_add_i32 s52, s89, 2
	s_add_u32 s48, s48, 0x100
	s_addc_u32 s49, s49, 0
	v_lshl_add_u64 v[138:139], v[138:139], 0, s[72:73]
	v_lshl_add_u64 v[128:129], v[128:129], 0, s[72:73]
	s_cmp_ge_i32 s89, s3
	s_mov_b32 s89, s52
	s_cbranch_scc0 .LBB0_1662
	s_and_b64 vcc, exec, s[36:37]
	s_cbranch_vccz .LBB0_1665
	s_barrier

; #define PG8_STAGE(bufoff, gbase, voff) do { _Pragma("unroll") for (int _i = 0; _i < 2; ++_i) \
;         __builtin_amdgcn_global_load_lds((const unsigned*)((const char*)(gbase) + (voff)[_i]), (LAS unsigned*)(lds + (bufoff) + ldsw + _i * 8192), 16, 0, 0); } while (0)
; #define PG8_LDA(dst, b, h) do { _Pragma("unroll") for (int m = 0; m < 4; ++m) _Pragma("unroll") for (int k = 0; k < 2; ++k) dst[m][k] = *(const LAS bf16x8*)(lds + PG8_SA(b, h) + aoff + m * 2048 + k * 1024); } while (0)
; #define PG8_LDB(dst, b, h) do { _Pragma("unroll") for (int n = 0; n < 2; ++n) _Pragma("unroll") for (int k = 0; k < 2; ++k) dst[n][k] = *(const LAS bf16x8*)(lds + PG8_SB(b, h) + boff + n * 2048 + k * 1024); } while (0)
; #define PG8_MMA(ai, bj, At, Bt) do { __builtin_amdgcn_s_setprio(1); _Pragma("unroll") for (int m = 0; m < 4; ++m) _Pragma("unroll") for (int n = 0; n < 2; ++n) _Pragma("unroll") for (int k = 0; k < 2; ++k) \
;         acc[ai][bj][m][n] = __builtin_amdgcn_mfma_f32_16x16x32_bf16(Bt[n][k], At[m][k], acc[ai][bj][m][n], 0, 0, 0); __builtin_amdgcn_s_setprio(0); } while (0)
; #define PG8_WAIT_V(n) asm volatile("s_waitcnt vmcnt(" #n ")" ::: "memory")
; #define PG8_WAIT_L(n) asm volatile("s_waitcnt lgkmcnt(" #n ")" ::: "memory")
; template <class Epi, class Sched, bool ALIGN_EPI, bool LAST_FUSED = false, bool PERM = false, bool CARRY = false>
; __device__ __forceinline__ void gemm_phase(LAS unsigned char* lds, const int tid, const int K, const int lda, const int ldb, const Sched& S, const Epi& E) {
;     ...
;         for (int t = 0; t < nt; t += 2) {
;             const bool last = (t == nt - 2);
;             const char* a1 = cA + (size_t)(t + 1) * kstep;
;             const char* a2 = last ? nA : cA + (size_t)(t + 2) * kstep; const char* b2 = last ? nB : cB + (size_t)(t + 2) * kstep;
;             const char* a3 = a2 + kstep; const char* b3 = b2 + kstep;
;             PG8_LDB(B0, 0, 0); PG8_LDB(B1, 0, 1); PG8_SCHED; PG8_LDA(At, 0, 0); PG8_STAGE(PG8_SA(1, 1), a1 + hstepA, voffA);
;             PG8_WAIT_V(8); PG8_WAIT_L(0); PG8_BAR; PG8_MMA(0, 0, At, B0); PG8_MMA(0, 1, At, B1); PG8_BAR; PG8_SCHED;
;             PG8_LDA(At, 0, 1); PG8_STAGE(PG8_SB(0, 0), b2, voffB); PG8_STAGE(PG8_SB(0, 1), b2 + hstepB, voffB); PG8_STAGE(PG8_SA(0, 0), a2, voffA);
;             PG8_WAIT_V(8); PG8_WAIT_L(0); PG8_BAR; PG8_MMA(1, 0, At, B0); PG8_MMA(1, 1, At, B1); PG8_BAR; PG8_SCHED;
.LBB0_1763:
	s_add_u32 s16, s48, 0xfff80080
	s_addc_u32 s17, s49, -1
	s_add_i32 s67, 0, 0x10000
	s_cmp_eq_u32 s41, 28
	s_cselect_b32 s53, s43, s17
	s_cselect_b32 s52, s42, s16
	v_add_u32_e32 v140, s67, v146
	s_cselect_b32 s55, s51, s39
	s_cselect_b32 s54, s50, s27
	s_add_i32 s16, 0, 0x14000
	ds_read_b128 v[148:151], v140
	ds_read_b128 v[152:155], v140 offset:1024
	ds_read_b128 v[156:159], v140 offset:2048
	ds_read_b128 v[160:163], v140 offset:3072
	v_add_u32_e32 v140, s16, v146
	ds_read_b128 v[164:167], v140
	ds_read_b128 v[168:171], v140 offset:1024
	ds_read_b128 v[172:175], v140 offset:2048
	ds_read_b128 v[176:179], v140 offset:3072
	v_lshl_add_u64 v[140:141], s[48:49], 0, v[136:137]
	s_add_i32 m0, s47, 0xc000
	ds_read_b128 v[180:183], v147
	ds_read_b128 v[184:187], v147 offset:1024
	ds_read_b128 v[188:191], v147 offset:2048
	ds_read_b128 v[192:195], v147 offset:3072
	ds_read_b128 v[196:199], v147 offset:4096
	ds_read_b128 v[200:203], v147 offset:5120
	ds_read_b128 v[204:207], v147 offset:6144
	ds_read_b128 v[208:211], v147 offset:7168
	global_load_lds_dwordx4 v[140:141], off
	v_lshl_add_u64 v[140:141], s[48:49], 0, v[138:139]
	s_add_i32 m0, s47, 0xe000
	s_nop 0
	global_load_lds_dwordx4 v[140:141], off
	s_waitcnt vmcnt(8)
	s_waitcnt lgkmcnt(0)
	s_setprio 1
	s_barrier
	v_mfma_f32_16x16x32_bf16 v[126:129], v[148:151], v[180:183], v[126:129]
	v_mfma_f32_16x16x32_bf16 v[122:125], v[156:159], v[180:183], v[122:125]
	v_mfma_f32_16x16x32_bf16 v[110:113], v[148:151], v[188:191], v[110:113]
	v_mfma_f32_16x16x32_bf16 v[106:109], v[156:159], v[188:191], v[106:109]
	v_mfma_f32_16x16x32_bf16 v[94:97], v[148:151], v[196:199], v[94:97]
	v_mfma_f32_16x16x32_bf16 v[90:93], v[156:159], v[196:199], v[90:93]
	v_mfma_f32_16x16x32_bf16 v[78:81], v[148:151], v[204:207], v[78:81]
	v_mfma_f32_16x16x32_bf16 v[74:77], v[156:159], v[204:207], v[74:77]
	v_mfma_f32_16x16x32_bf16 v[126:129], v[152:155], v[184:187], v[126:129]
	v_mfma_f32_16x16x32_bf16 v[122:125], v[160:163], v[184:187], v[122:125]
	v_mfma_f32_16x16x32_bf16 v[110:113], v[152:155], v[192:195], v[110:113]
	v_mfma_f32_16x16x32_bf16 v[106:109], v[160:163], v[192:195], v[106:109]
	v_mfma_f32_16x16x32_bf16 v[94:97], v[152:155], v[200:203], v[94:97]
	v_mfma_f32_16x16x32_bf16 v[90:93], v[160:163], v[200:203], v[90:93]
	v_mfma_f32_16x16x32_bf16 v[78:81], v[152:155], v[208:211], v[78:81]
	v_mfma_f32_16x16x32_bf16 v[74:77], v[160:163], v[208:211], v[74:77]
	s_setprio 0
	s_setprio 1
	v_mfma_f32_16x16x32_bf16 v[118:121], v[164:167], v[180:183], v[118:121]
	v_mfma_f32_16x16x32_bf16 v[114:117], v[172:175], v[180:183], v[114:117]
	v_mfma_f32_16x16x32_bf16 v[102:105], v[164:167], v[188:191], v[102:105]
	v_mfma_f32_16x16x32_bf16 v[98:101], v[172:175], v[188:191], v[98:101]
	v_mfma_f32_16x16x32_bf16 v[86:89], v[164:167], v[196:199], v[86:89]
	v_mfma_f32_16x16x32_bf16 v[82:85], v[172:175], v[196:199], v[82:85]
	v_mfma_f32_16x16x32_bf16 v[70:73], v[164:167], v[204:207], v[70:73]
	v_mfma_f32_16x16x32_bf16 v[66:69], v[172:175], v[204:207], v[66:69]
	v_mfma_f32_16x16x32_bf16 v[118:121], v[168:171], v[184:187], v[118:121]
	v_mfma_f32_16x16x32_bf16 v[114:117], v[176:179], v[184:187], v[114:117]
	v_mfma_f32_16x16x32_bf16 v[102:105], v[168:171], v[192:195], v[102:105]
	v_mfma_f32_16x16x32_bf16 v[98:101], v[176:179], v[192:195], v[98:101]
	v_mfma_f32_16x16x32_bf16 v[86:89], v[168:171], v[200:203], v[86:89]
	v_mfma_f32_16x16x32_bf16 v[82:85], v[176:179], v[200:203], v[82:85]
	v_mfma_f32_16x16x32_bf16 v[70:73], v[168:171], v[208:211], v[70:73]
	v_mfma_f32_16x16x32_bf16 v[66:69], v[176:179], v[208:211], v[66:69]
	s_barrier
	s_setprio 0
	s_add_i32 s17, s67, s45
	v_lshl_add_u64 v[140:141], s[54:55], 0, v[0:1]
	s_mov_b32 m0, s17
	ds_read_b128 v[180:183], v147 offset:16384
	ds_read_b128 v[184:187], v147 offset:17408
	ds_read_b128 v[188:191], v147 offset:18432
	ds_read_b128 v[192:195], v147 offset:19456
	ds_read_b128 v[196:199], v147 offset:20480
	ds_read_b128 v[200:203], v147 offset:21504
	ds_read_b128 v[204:207], v147 offset:22528
	ds_read_b128 v[208:211], v147 offset:23552
	global_load_lds_dwordx4 v[140:141], off
	s_add_i32 m0, s17, 0x2000
	s_add_u32 s70, s54, 0x80000
	v_lshl_add_u64 v[212:213], s[54:55], 0, v[130:131]
	s_addc_u32 s71, s55, 0
	s_add_i32 s16, s16, s45
	global_load_lds_dwordx4 v[212:213], off
	v_lshl_add_u64 v[214:215], s[70:71], 0, v[0:1]
	s_mov_b32 m0, s16
	v_lshl_add_u64 v[216:217], s[52:53], 0, v[132:133]
	global_load_lds_dwordx4 v[214:215], off
	v_lshl_add_u64 v[214:215], s[70:71], 0, v[130:131]
	s_add_i32 m0, s16, 0x2000
	s_nop 0
	global_load_lds_dwordx4 v[214:215], off
	v_lshl_add_u64 v[214:215], s[52:53], 0, v[134:135]
	s_mov_b32 m0, s47
	s_nop 0
	global_load_lds_dwordx4 v[214:215], off
	s_mov_b32 m0, s57
	s_nop 0
	global_load_lds_dwordx4 v[216:217], off
	s_waitcnt vmcnt(8)
	s_waitcnt lgkmcnt(0)
	s_setprio 1
	s_barrier
; #define PG8_STAGE(bufoff, gbase, voff) do { _Pragma("unroll") for (int _i = 0; _i < 2; ++_i) \
;         __builtin_amdgcn_global_load_lds((const unsigned*)((const char*)(gbase) + (voff)[_i]), (LAS unsigned*)(lds + (bufoff) + ldsw + _i * 8192), 16, 0, 0); } while (0)
; #define PG8_LDA(dst, b, h) do { _Pragma("unroll") for (int m = 0; m < 4; ++m) _Pragma("unroll") for (int k = 0; k < 2; ++k) dst[m][k] = *(const LAS bf16x8*)(lds + PG8_SA(b, h) + aoff + m * 2048 + k * 1024); } while (0)
; #define PG8_LDB(dst, b, h) do { _Pragma("unroll") for (int n = 0; n < 2; ++n) _Pragma("unroll") for (int k = 0; k < 2; ++k) dst[n][k] = *(const LAS bf16x8*)(lds + PG8_SB(b, h) + boff + n * 2048 + k * 1024); } while (0)
; #define PG8_MMA(ai, bj, At, Bt) do { __builtin_amdgcn_s_setprio(1); _Pragma("unroll") for (int m = 0; m < 4; ++m) _Pragma("unroll") for (int n = 0; n < 2; ++n) _Pragma("unroll") for (int k = 0; k < 2; ++k) \
;         acc[ai][bj][m][n] = __builtin_amdgcn_mfma_f32_16x16x32_bf16(Bt[n][k], At[m][k], acc[ai][bj][m][n], 0, 0, 0); __builtin_amdgcn_s_setprio(0); } while (0)
; #define PG8_WAIT_V(n) asm volatile("s_waitcnt vmcnt(" #n ")" ::: "memory")
; #define PG8_WAIT_L(n) asm volatile("s_waitcnt lgkmcnt(" #n ")" ::: "memory")
; #define PG8_BAR __builtin_amdgcn_s_barrier()
; #define PG8_SCHED __builtin_amdgcn_sched_barrier(0)
; template <class Epi, class Sched, bool ALIGN_EPI, bool LAST_FUSED = false, bool PERM = false, bool CARRY = false>
; __device__ __forceinline__ void gemm_phase(LAS unsigned char* lds, const int tid, const int K, const int lda, const int ldb, const Sched& S, const Epi& E) {
;     ...
;             PG8_WAIT_V(8); PG8_WAIT_L(0); PG8_BAR; PG8_MMA(1, 0, At, B0); PG8_MMA(1, 1, At, B1); PG8_BAR; PG8_SCHED;
;             PG8_LDB(B0, 1, 0); PG8_LDB(B1, 1, 1); PG8_SCHED; PG8_LDA(At, 1, 0); PG8_STAGE(PG8_SA(0, 1), a2 + hstepA, voffA);
;             PG8_WAIT_V(8); PG8_WAIT_L(0); PG8_BAR; PG8_MMA(0, 0, At, B0); PG8_MMA(0, 1, At, B1); PG8_BAR; PG8_SCHED;
;             PG8_LDA(At, 1, 1); PG8_STAGE(PG8_SB(1, 0), b3, voffB); PG8_STAGE(PG8_SB(1, 1), b3 + hstepB, voffB); PG8_STAGE(PG8_SA(1, 0), a3, voffA);
;             PG8_WAIT_V(8); PG8_WAIT_L(0); PG8_BAR; PG8_MMA(1, 0, At, B0); PG8_MMA(1, 1, At, B1); PG8_BAR; PG8_SCHED;
	v_mfma_f32_16x16x32_bf16 v[62:65], v[148:151], v[180:183], v[62:65]
	v_mfma_f32_16x16x32_bf16 v[58:61], v[156:159], v[180:183], v[58:61]
	v_mfma_f32_16x16x32_bf16 v[46:49], v[148:151], v[188:191], v[46:49]
	v_mfma_f32_16x16x32_bf16 v[42:45], v[156:159], v[188:191], v[42:45]
	v_mfma_f32_16x16x32_bf16 v[30:33], v[148:151], v[196:199], v[30:33]
	v_mfma_f32_16x16x32_bf16 v[26:29], v[156:159], v[196:199], v[26:29]
	v_mfma_f32_16x16x32_bf16 v[14:17], v[148:151], v[204:207], v[14:17]
	v_mfma_f32_16x16x32_bf16 v[10:13], v[156:159], v[204:207], v[10:13]
	v_mfma_f32_16x16x32_bf16 v[62:65], v[152:155], v[184:187], v[62:65]
	v_mfma_f32_16x16x32_bf16 v[58:61], v[160:163], v[184:187], v[58:61]
	v_mfma_f32_16x16x32_bf16 v[46:49], v[152:155], v[192:195], v[46:49]
	v_mfma_f32_16x16x32_bf16 v[42:45], v[160:163], v[192:195], v[42:45]
	v_mfma_f32_16x16x32_bf16 v[30:33], v[152:155], v[200:203], v[30:33]
	v_mfma_f32_16x16x32_bf16 v[26:29], v[160:163], v[200:203], v[26:29]
	v_mfma_f32_16x16x32_bf16 v[14:17], v[152:155], v[208:211], v[14:17]
	v_mfma_f32_16x16x32_bf16 v[10:13], v[160:163], v[208:211], v[10:13]
	s_setprio 0
	s_setprio 1
	v_mfma_f32_16x16x32_bf16 v[54:57], v[164:167], v[180:183], v[54:57]
	v_mfma_f32_16x16x32_bf16 v[50:53], v[172:175], v[180:183], v[50:53]
	v_mfma_f32_16x16x32_bf16 v[38:41], v[164:167], v[188:191], v[38:41]
	v_mfma_f32_16x16x32_bf16 v[34:37], v[172:175], v[188:191], v[34:37]
	v_mfma_f32_16x16x32_bf16 v[22:25], v[164:167], v[196:199], v[22:25]
	v_mfma_f32_16x16x32_bf16 v[18:21], v[172:175], v[196:199], v[18:21]
	v_mfma_f32_16x16x32_bf16 v[6:9], v[164:167], v[204:207], v[6:9]
	v_mfma_f32_16x16x32_bf16 v[2:5], v[172:175], v[204:207], v[2:5]
	v_mfma_f32_16x16x32_bf16 v[54:57], v[168:171], v[184:187], v[54:57]
	v_mfma_f32_16x16x32_bf16 v[50:53], v[176:179], v[184:187], v[50:53]
	v_mfma_f32_16x16x32_bf16 v[38:41], v[168:171], v[192:195], v[38:41]
	v_mfma_f32_16x16x32_bf16 v[34:37], v[176:179], v[192:195], v[34:37]
	v_mfma_f32_16x16x32_bf16 v[22:25], v[168:171], v[200:203], v[22:25]
	v_mfma_f32_16x16x32_bf16 v[18:21], v[176:179], v[200:203], v[18:21]
	v_mfma_f32_16x16x32_bf16 v[6:9], v[168:171], v[208:211], v[6:9]
	v_mfma_f32_16x16x32_bf16 v[2:5], v[176:179], v[208:211], v[2:5]
	s_barrier
	s_setprio 0
	s_add_i32 s16, 0, 0x18000
	s_add_i32 s17, 0, 0x1c000
	v_add_u32_e32 v160, s16, v146
	v_add_u32_e32 v176, s17, v146
	ds_read_b128 v[148:151], v160
	ds_read_b128 v[152:155], v160 offset:1024
	ds_read_b128 v[156:159], v160 offset:2048
	ds_read_b128 v[160:163], v160 offset:3072
	ds_read_b128 v[164:167], v176
	ds_read_b128 v[168:171], v176 offset:1024
	ds_read_b128 v[172:175], v176 offset:2048
	ds_read_b128 v[176:179], v176 offset:3072
	s_add_u32 s52, s52, 0x80000
	s_addc_u32 s53, s53, 0
	s_mov_b32 m0, s58
	v_lshl_add_u64 v[218:219], s[52:53], 0, v[134:135]
	ds_read_b128 v[180:183], v147 offset:32768
	ds_read_b128 v[184:187], v147 offset:33792
	ds_read_b128 v[188:191], v147 offset:34816
	ds_read_b128 v[192:195], v147 offset:35840
	ds_read_b128 v[196:199], v147 offset:36864
	ds_read_b128 v[200:203], v147 offset:37888
	ds_read_b128 v[204:207], v147 offset:38912
	ds_read_b128 v[208:211], v147 offset:39936
	global_load_lds_dwordx4 v[218:219], off
	v_lshl_add_u64 v[218:219], s[52:53], 0, v[132:133]
	s_mov_b32 m0, s59
	s_nop 0
	global_load_lds_dwordx4 v[218:219], off
	s_waitcnt vmcnt(8)
	s_waitcnt lgkmcnt(0)
	s_setprio 1
	s_barrier
	v_mfma_f32_16x16x32_bf16 v[126:129], v[148:151], v[180:183], v[126:129]
	v_mfma_f32_16x16x32_bf16 v[122:125], v[156:159], v[180:183], v[122:125]
	v_mfma_f32_16x16x32_bf16 v[110:113], v[148:151], v[188:191], v[110:113]
	v_mfma_f32_16x16x32_bf16 v[106:109], v[156:159], v[188:191], v[106:109]
	v_mfma_f32_16x16x32_bf16 v[94:97], v[148:151], v[196:199], v[94:97]
	v_mfma_f32_16x16x32_bf16 v[90:93], v[156:159], v[196:199], v[90:93]
	v_mfma_f32_16x16x32_bf16 v[78:81], v[148:151], v[204:207], v[78:81]
	v_mfma_f32_16x16x32_bf16 v[74:77], v[156:159], v[204:207], v[74:77]
	v_mfma_f32_16x16x32_bf16 v[126:129], v[152:155], v[184:187], v[126:129]
	v_mfma_f32_16x16x32_bf16 v[122:125], v[160:163], v[184:187], v[122:125]
	v_mfma_f32_16x16x32_bf16 v[110:113], v[152:155], v[192:195], v[110:113]
	v_mfma_f32_16x16x32_bf16 v[106:109], v[160:163], v[192:195], v[106:109]
	v_mfma_f32_16x16x32_bf16 v[94:97], v[152:155], v[200:203], v[94:97]
	v_mfma_f32_16x16x32_bf16 v[90:93], v[160:163], v[200:203], v[90:93]
	v_mfma_f32_16x16x32_bf16 v[78:81], v[152:155], v[208:211], v[78:81]
	v_mfma_f32_16x16x32_bf16 v[74:77], v[160:163], v[208:211], v[74:77]
	s_setprio 0
	s_setprio 1
	v_mfma_f32_16x16x32_bf16 v[118:121], v[164:167], v[180:183], v[118:121]
	v_mfma_f32_16x16x32_bf16 v[114:117], v[172:175], v[180:183], v[114:117]
	v_mfma_f32_16x16x32_bf16 v[102:105], v[164:167], v[188:191], v[102:105]
	v_mfma_f32_16x16x32_bf16 v[98:101], v[172:175], v[188:191], v[98:101]
	v_mfma_f32_16x16x32_bf16 v[86:89], v[164:167], v[196:199], v[86:89]
	v_mfma_f32_16x16x32_bf16 v[82:85], v[172:175], v[196:199], v[82:85]
	v_mfma_f32_16x16x32_bf16 v[70:73], v[164:167], v[204:207], v[70:73]
	v_mfma_f32_16x16x32_bf16 v[66:69], v[172:175], v[204:207], v[66:69]
	v_mfma_f32_16x16x32_bf16 v[118:121], v[168:171], v[184:187], v[118:121]
	v_mfma_f32_16x16x32_bf16 v[114:117], v[176:179], v[184:187], v[114:117]
	v_mfma_f32_16x16x32_bf16 v[102:105], v[168:171], v[192:195], v[102:105]
	v_mfma_f32_16x16x32_bf16 v[98:101], v[176:179], v[192:195], v[98:101]
	v_mfma_f32_16x16x32_bf16 v[86:89], v[168:171], v[200:203], v[86:89]
	v_mfma_f32_16x16x32_bf16 v[82:85], v[176:179], v[200:203], v[82:85]
	v_mfma_f32_16x16x32_bf16 v[70:73], v[168:171], v[208:211], v[70:73]
	v_mfma_f32_16x16x32_bf16 v[66:69], v[176:179], v[208:211], v[66:69]
	s_barrier
; #define PG8_STAGE(bufoff, gbase, voff) do { _Pragma("unroll") for (int _i = 0; _i < 2; ++_i) \
;         __builtin_amdgcn_global_load_lds((const unsigned*)((const char*)(gbase) + (voff)[_i]), (LAS unsigned*)(lds + (bufoff) + ldsw + _i * 8192), 16, 0, 0); } while (0)
; #define PG8_LDA(dst, b, h) do { _Pragma("unroll") for (int m = 0; m < 4; ++m) _Pragma("unroll") for (int k = 0; k < 2; ++k) dst[m][k] = *(const LAS bf16x8*)(lds + PG8_SA(b, h) + aoff + m * 2048 + k * 1024); } while (0)
; #define PG8_MMA(ai, bj, At, Bt) do { __builtin_amdgcn_s_setprio(1); _Pragma("unroll") for (int m = 0; m < 4; ++m) _Pragma("unroll") for (int n = 0; n < 2; ++n) _Pragma("unroll") for (int k = 0; k < 2; ++k) \
;         acc[ai][bj][m][n] = __builtin_amdgcn_mfma_f32_16x16x32_bf16(Bt[n][k], At[m][k], acc[ai][bj][m][n], 0, 0, 0); __builtin_amdgcn_s_setprio(0); } while (0)
; #define PG8_WAIT_V(n) asm volatile("s_waitcnt vmcnt(" #n ")" ::: "memory")
; #define PG8_WAIT_L(n) asm volatile("s_waitcnt lgkmcnt(" #n ")" ::: "memory")
; #define PG8_BAR __builtin_amdgcn_s_barrier()
; #define PG8_SCHED __builtin_amdgcn_sched_barrier(0)
; template <class Epi, class Sched, bool ALIGN_EPI, bool LAST_FUSED = false, bool PERM = false, bool CARRY = false>
; __device__ __forceinline__ void gemm_phase(LAS unsigned char* lds, const int tid, const int K, const int lda, const int ldb, const Sched& S, const Epi& E) {
;     ...
;             PG8_LDA(At, 1, 1); PG8_STAGE(PG8_SB(1, 0), b3, voffB); PG8_STAGE(PG8_SB(1, 1), b3 + hstepB, voffB); PG8_STAGE(PG8_SA(1, 0), a3, voffA);
;             PG8_WAIT_V(8); PG8_WAIT_L(0); PG8_BAR; PG8_MMA(1, 0, At, B0); PG8_MMA(1, 1, At, B1); PG8_BAR; PG8_SCHED;
;         }
;         if constexpr (ALIGN_EPI) { if (wr == 0) PG8_BAR; }
	s_setprio 0
	s_add_i32 s16, s16, s45
	v_lshl_add_u64 v[140:141], v[140:141], 0, s[68:69]
	s_mov_b32 m0, s16
	ds_read_b128 v[180:183], v147 offset:49152
	ds_read_b128 v[184:187], v147 offset:50176
	ds_read_b128 v[188:191], v147 offset:51200
	ds_read_b128 v[192:195], v147 offset:52224
	ds_read_b128 v[196:199], v147 offset:53248
	ds_read_b128 v[200:203], v147 offset:54272
	ds_read_b128 v[204:207], v147 offset:55296
	ds_read_b128 v[208:211], v147 offset:56320
	global_load_lds_dwordx4 v[140:141], off
	s_add_i32 m0, s16, 0x2000
	s_add_u32 s52, s54, 0x80080
	v_lshl_add_u64 v[140:141], v[212:213], 0, s[68:69]
	s_addc_u32 s53, s55, 0
	s_add_i32 s16, s17, s45
	global_load_lds_dwordx4 v[140:141], off
	v_lshl_add_u64 v[140:141], s[52:53], 0, v[0:1]
	s_mov_b32 m0, s16
	s_nop 0
	global_load_lds_dwordx4 v[140:141], off
	v_lshl_add_u64 v[140:141], s[52:53], 0, v[130:131]
	s_add_i32 m0, s16, 0x2000
	s_nop 0
	global_load_lds_dwordx4 v[140:141], off
	v_lshl_add_u64 v[140:141], v[214:215], 0, s[68:69]
	s_mov_b32 m0, s61
	s_nop 0
	global_load_lds_dwordx4 v[140:141], off
	v_lshl_add_u64 v[140:141], v[216:217], 0, s[68:69]
	s_mov_b32 m0, s62
	s_nop 0
	global_load_lds_dwordx4 v[140:141], off
	s_waitcnt vmcnt(8)
	s_waitcnt lgkmcnt(0)
	s_setprio 1
	s_barrier
	v_mfma_f32_16x16x32_bf16 v[62:65], v[148:151], v[180:183], v[62:65]
	v_mfma_f32_16x16x32_bf16 v[58:61], v[156:159], v[180:183], v[58:61]
	v_mfma_f32_16x16x32_bf16 v[46:49], v[148:151], v[188:191], v[46:49]
	v_mfma_f32_16x16x32_bf16 v[42:45], v[156:159], v[188:191], v[42:45]
	v_mfma_f32_16x16x32_bf16 v[30:33], v[148:151], v[196:199], v[30:33]
	v_mfma_f32_16x16x32_bf16 v[26:29], v[156:159], v[196:199], v[26:29]
	v_mfma_f32_16x16x32_bf16 v[14:17], v[148:151], v[204:207], v[14:17]
	v_mfma_f32_16x16x32_bf16 v[10:13], v[156:159], v[204:207], v[10:13]
	v_mfma_f32_16x16x32_bf16 v[62:65], v[152:155], v[184:187], v[62:65]
	v_mfma_f32_16x16x32_bf16 v[58:61], v[160:163], v[184:187], v[58:61]
	v_mfma_f32_16x16x32_bf16 v[46:49], v[152:155], v[192:195], v[46:49]
	v_mfma_f32_16x16x32_bf16 v[42:45], v[160:163], v[192:195], v[42:45]
	v_mfma_f32_16x16x32_bf16 v[30:33], v[152:155], v[200:203], v[30:33]
	v_mfma_f32_16x16x32_bf16 v[26:29], v[160:163], v[200:203], v[26:29]
	v_mfma_f32_16x16x32_bf16 v[14:17], v[152:155], v[208:211], v[14:17]
	v_mfma_f32_16x16x32_bf16 v[10:13], v[160:163], v[208:211], v[10:13]
	s_setprio 0
	s_setprio 1
	v_mfma_f32_16x16x32_bf16 v[54:57], v[164:167], v[180:183], v[54:57]
	v_mfma_f32_16x16x32_bf16 v[50:53], v[172:175], v[180:183], v[50:53]
	v_mfma_f32_16x16x32_bf16 v[38:41], v[164:167], v[188:191], v[38:41]
	v_mfma_f32_16x16x32_bf16 v[34:37], v[172:175], v[188:191], v[34:37]
	v_mfma_f32_16x16x32_bf16 v[22:25], v[164:167], v[196:199], v[22:25]
	v_mfma_f32_16x16x32_bf16 v[18:21], v[172:175], v[196:199], v[18:21]
	v_mfma_f32_16x16x32_bf16 v[6:9], v[164:167], v[204:207], v[6:9]
	v_mfma_f32_16x16x32_bf16 v[2:5], v[172:175], v[204:207], v[2:5]
	v_mfma_f32_16x16x32_bf16 v[54:57], v[168:171], v[184:187], v[54:57]
	v_mfma_f32_16x16x32_bf16 v[50:53], v[176:179], v[184:187], v[50:53]
	v_mfma_f32_16x16x32_bf16 v[38:41], v[168:171], v[192:195], v[38:41]
	v_mfma_f32_16x16x32_bf16 v[34:37], v[176:179], v[192:195], v[34:37]
	v_mfma_f32_16x16x32_bf16 v[22:25], v[168:171], v[200:203], v[22:25]
	v_mfma_f32_16x16x32_bf16 v[18:21], v[176:179], v[200:203], v[18:21]
	v_mfma_f32_16x16x32_bf16 v[6:9], v[168:171], v[208:211], v[6:9]
	v_mfma_f32_16x16x32_bf16 v[2:5], v[176:179], v[208:211], v[2:5]
	s_barrier
	s_setprio 0
	s_add_i32 s41, s41, 2
	s_add_u32 s48, s48, 0x100
	s_addc_u32 s49, s49, 0
	s_add_u32 s27, s27, 0x100
	s_addc_u32 s39, s39, 0
	s_cmp_gt_u32 s41, 29
	s_cbranch_scc0 .LBB0_1763
	s_and_b64 vcc, exec, s[36:37]
	s_cbranch_vccz .LBB0_1766
	s_barrier

; #define PG8_STAGE(bufoff, gbase, voff) do { _Pragma("unroll") for (int _i = 0; _i < 2; ++_i) \
;         __builtin_amdgcn_global_load_lds((const unsigned*)((const char*)(gbase) + (voff)[_i]), (LAS unsigned*)(lds + (bufoff) + ldsw + _i * 8192), 16, 0, 0); } while (0)
; #define PG8_LDA(dst, b, h) do { _Pragma("unroll") for (int m = 0; m < 4; ++m) _Pragma("unroll") for (int k = 0; k < 2; ++k) dst[m][k] = *(const LAS bf16x8*)(lds + PG8_SA(b, h) + aoff + m * 2048 + k * 1024); } while (0)
; #define PG8_LDB(dst, b, h) do { _Pragma("unroll") for (int n = 0; n < 2; ++n) _Pragma("unroll") for (int k = 0; k < 2; ++k) dst[n][k] = *(const LAS bf16x8*)(lds + PG8_SB(b, h) + boff + n * 2048 + k * 1024); } while (0)
; #define PG8_MMA(ai, bj, At, Bt) do { __builtin_amdgcn_s_setprio(1); _Pragma("unroll") for (int m = 0; m < 4; ++m) _Pragma("unroll") for (int n = 0; n < 2; ++n) _Pragma("unroll") for (int k = 0; k < 2; ++k) \
;         acc[ai][bj][m][n] = __builtin_amdgcn_mfma_f32_16x16x32_bf16(Bt[n][k], At[m][k], acc[ai][bj][m][n], 0, 0, 0); __builtin_amdgcn_s_setprio(0); } while (0)
; #define PG8_WAIT_V(n) asm volatile("s_waitcnt vmcnt(" #n ")" ::: "memory")
; #define PG8_WAIT_L(n) asm volatile("s_waitcnt lgkmcnt(" #n ")" ::: "memory")
; template <class Epi, class Sched, bool ALIGN_EPI, bool LAST_FUSED = false, bool PERM = false, bool CARRY = false>
; __device__ __forceinline__ void gemm_phase(LAS unsigned char* lds, const int tid, const int K, const int lda, const int ldb, const Sched& S, const Epi& E) {
;     ...
;         for (int t = 0; t < nt; t += 2) {
;             const bool last = (t == nt - 2);
;             const char* a1 = cA + (size_t)(t + 1) * kstep;
;             const char* a2 = last ? nA : cA + (size_t)(t + 2) * kstep; const char* b2 = last ? nB : cB + (size_t)(t + 2) * kstep;
;             const char* a3 = a2 + kstep; const char* b3 = b2 + kstep;
;             PG8_LDB(B0, 0, 0); PG8_LDB(B1, 0, 1); PG8_SCHED; PG8_LDA(At, 0, 0); PG8_STAGE(PG8_SA(1, 1), a1 + hstepA, voffA);
;             PG8_WAIT_V(8); PG8_WAIT_L(0); PG8_BAR; PG8_MMA(0, 0, At, B0); PG8_MMA(0, 1, At, B1); PG8_BAR; PG8_SCHED;
;             PG8_LDA(At, 0, 1); PG8_STAGE(PG8_SB(0, 0), b2, voffB); PG8_STAGE(PG8_SB(0, 1), b2 + hstepB, voffB); PG8_STAGE(PG8_SA(0, 0), a2, voffA);
;             PG8_WAIT_V(8); PG8_WAIT_L(0); PG8_BAR; PG8_MMA(1, 0, At, B0); PG8_MMA(1, 1, At, B1); PG8_BAR; PG8_SCHED;
.LBB0_1854:
	s_add_u32 s16, s66, vcc_lo
	s_addc_u32 s17, s67, vcc_hi
	s_add_u32 s52, s50, vcc_lo
	s_addc_u32 s53, s51, vcc_hi
	s_add_i32 s92, 0, 0x10000
	s_cmp_eq_u32 s87, s60
	s_cselect_b32 s57, s24, s17
	s_cselect_b32 s56, s91, s16
	v_add_u32_e32 v154, s92, v140
	s_cselect_b32 s53, s70, s53
	s_cselect_b32 s52, s71, s52
	s_add_i32 s93, 0, 0x14000
	ds_read_b128 v[142:145], v154
	ds_read_b128 v[146:149], v154 offset:1024
	ds_read_b128 v[150:153], v154 offset:2048
	ds_read_b128 v[158:161], v154 offset:3072
	v_add_u32_e32 v154, s93, v140
	ds_read_b128 v[162:165], v154
	ds_read_b128 v[166:169], v154 offset:1024
	ds_read_b128 v[170:173], v154 offset:2048
	ds_read_b128 v[174:177], v154 offset:3072
	v_lshl_add_u64 v[154:155], s[66:67], 0, v[138:139]
	s_add_i32 m0, s28, 0xc000
	ds_read_b128 v[178:181], v141
	ds_read_b128 v[182:185], v141 offset:1024
	ds_read_b128 v[186:189], v141 offset:2048
	ds_read_b128 v[190:193], v141 offset:3072
	ds_read_b128 v[194:197], v141 offset:4096
	ds_read_b128 v[198:201], v141 offset:5120
	ds_read_b128 v[202:205], v141 offset:6144
	ds_read_b128 v[206:209], v141 offset:7168
	global_load_lds_dwordx4 v[154:155], off
	v_lshl_add_u64 v[154:155], s[66:67], 0, v[128:129]
	s_add_i32 m0, s28, 0xe000
	s_nop 0
	global_load_lds_dwordx4 v[154:155], off
	s_waitcnt vmcnt(8)
	s_waitcnt lgkmcnt(0)
	s_setprio 1
	s_barrier
	v_mfma_f32_16x16x32_bf16 v[118:121], v[142:145], v[178:181], v[118:121]
	v_mfma_f32_16x16x32_bf16 v[114:117], v[150:153], v[178:181], v[114:117]
	v_mfma_f32_16x16x32_bf16 v[110:113], v[142:145], v[186:189], v[110:113]
	v_mfma_f32_16x16x32_bf16 v[106:109], v[150:153], v[186:189], v[106:109]
	v_mfma_f32_16x16x32_bf16 v[86:89], v[142:145], v[194:197], v[86:89]
	v_mfma_f32_16x16x32_bf16 v[82:85], v[150:153], v[194:197], v[82:85]
	v_mfma_f32_16x16x32_bf16 v[78:81], v[142:145], v[202:205], v[78:81]
	v_mfma_f32_16x16x32_bf16 v[74:77], v[150:153], v[202:205], v[74:77]
	v_mfma_f32_16x16x32_bf16 v[118:121], v[146:149], v[182:185], v[118:121]
	v_mfma_f32_16x16x32_bf16 v[114:117], v[158:161], v[182:185], v[114:117]
	v_mfma_f32_16x16x32_bf16 v[110:113], v[146:149], v[190:193], v[110:113]
	v_mfma_f32_16x16x32_bf16 v[106:109], v[158:161], v[190:193], v[106:109]
	v_mfma_f32_16x16x32_bf16 v[86:89], v[146:149], v[198:201], v[86:89]
	v_mfma_f32_16x16x32_bf16 v[82:85], v[158:161], v[198:201], v[82:85]
	v_mfma_f32_16x16x32_bf16 v[78:81], v[146:149], v[206:209], v[78:81]
	v_mfma_f32_16x16x32_bf16 v[74:77], v[158:161], v[206:209], v[74:77]
	s_setprio 0
	s_setprio 1
	v_mfma_f32_16x16x32_bf16 v[98:101], v[162:165], v[178:181], v[98:101]
	v_mfma_f32_16x16x32_bf16 v[102:105], v[170:173], v[178:181], v[102:105]
	v_mfma_f32_16x16x32_bf16 v[90:93], v[162:165], v[186:189], v[90:93]
	v_mfma_f32_16x16x32_bf16 v[94:97], v[170:173], v[186:189], v[94:97]
	v_mfma_f32_16x16x32_bf16 v[66:69], v[162:165], v[194:197], v[66:69]
	v_mfma_f32_16x16x32_bf16 v[70:73], v[170:173], v[194:197], v[70:73]
	v_mfma_f32_16x16x32_bf16 v[50:53], v[162:165], v[202:205], v[50:53]
	v_mfma_f32_16x16x32_bf16 v[54:57], v[170:173], v[202:205], v[54:57]
	v_mfma_f32_16x16x32_bf16 v[98:101], v[166:169], v[182:185], v[98:101]
	v_mfma_f32_16x16x32_bf16 v[102:105], v[174:177], v[182:185], v[102:105]
	v_mfma_f32_16x16x32_bf16 v[90:93], v[166:169], v[190:193], v[90:93]
	v_mfma_f32_16x16x32_bf16 v[94:97], v[174:177], v[190:193], v[94:97]
	v_mfma_f32_16x16x32_bf16 v[66:69], v[166:169], v[198:201], v[66:69]
	v_mfma_f32_16x16x32_bf16 v[70:73], v[174:177], v[198:201], v[70:73]
	v_mfma_f32_16x16x32_bf16 v[50:53], v[166:169], v[206:209], v[50:53]
	v_mfma_f32_16x16x32_bf16 v[54:57], v[174:177], v[206:209], v[54:57]
	s_barrier
	s_setprio 0
	s_add_i32 s16, s92, s95
	v_lshl_add_u64 v[154:155], s[52:53], 0, v[0:1]
	s_mov_b32 m0, s16
	ds_read_b128 v[178:181], v141 offset:16384
	ds_read_b128 v[182:185], v141 offset:17408
	ds_read_b128 v[186:189], v141 offset:18432
	ds_read_b128 v[190:193], v141 offset:19456
	ds_read_b128 v[194:197], v141 offset:20480
	ds_read_b128 v[198:201], v141 offset:21504
	ds_read_b128 v[202:205], v141 offset:22528
	ds_read_b128 v[206:209], v141 offset:23552
	global_load_lds_dwordx4 v[154:155], off
	s_add_i32 m0, s16, 0x2000
	s_add_u32 s16, s52, 0x200000
	v_lshl_add_u64 v[210:211], s[52:53], 0, v[122:123]
	s_addc_u32 s17, s53, 0
	s_add_i32 s92, s93, s95
	global_load_lds_dwordx4 v[210:211], off
	v_lshl_add_u64 v[212:213], s[16:17], 0, v[0:1]
	s_mov_b32 m0, s92
	v_lshl_add_u64 v[214:215], s[56:57], 0, v[122:123]
	global_load_lds_dwordx4 v[212:213], off
	v_lshl_add_u64 v[212:213], s[16:17], 0, v[122:123]
	s_add_i32 m0, s92, 0x2000
	s_nop 0
	global_load_lds_dwordx4 v[212:213], off
	v_lshl_add_u64 v[212:213], s[56:57], 0, v[0:1]
	s_mov_b32 m0, s28
	s_nop 0
	global_load_lds_dwordx4 v[212:213], off
	s_mov_b32 m0, s29
	s_nop 0
	global_load_lds_dwordx4 v[214:215], off
	s_waitcnt vmcnt(8)
	s_waitcnt lgkmcnt(0)
	s_setprio 1
	s_barrier
; #define PG8_STAGE(bufoff, gbase, voff) do { _Pragma("unroll") for (int _i = 0; _i < 2; ++_i) \
;         __builtin_amdgcn_global_load_lds((const unsigned*)((const char*)(gbase) + (voff)[_i]), (LAS unsigned*)(lds + (bufoff) + ldsw + _i * 8192), 16, 0, 0); } while (0)
; #define PG8_LDA(dst, b, h) do { _Pragma("unroll") for (int m = 0; m < 4; ++m) _Pragma("unroll") for (int k = 0; k < 2; ++k) dst[m][k] = *(const LAS bf16x8*)(lds + PG8_SA(b, h) + aoff + m * 2048 + k * 1024); } while (0)
; #define PG8_LDB(dst, b, h) do { _Pragma("unroll") for (int n = 0; n < 2; ++n) _Pragma("unroll") for (int k = 0; k < 2; ++k) dst[n][k] = *(const LAS bf16x8*)(lds + PG8_SB(b, h) + boff + n * 2048 + k * 1024); } while (0)
; #define PG8_MMA(ai, bj, At, Bt) do { __builtin_amdgcn_s_setprio(1); _Pragma("unroll") for (int m = 0; m < 4; ++m) _Pragma("unroll") for (int n = 0; n < 2; ++n) _Pragma("unroll") for (int k = 0; k < 2; ++k) \
;         acc[ai][bj][m][n] = __builtin_amdgcn_mfma_f32_16x16x32_bf16(Bt[n][k], At[m][k], acc[ai][bj][m][n], 0, 0, 0); __builtin_amdgcn_s_setprio(0); } while (0)
; #define PG8_WAIT_V(n) asm volatile("s_waitcnt vmcnt(" #n ")" ::: "memory")
; #define PG8_WAIT_L(n) asm volatile("s_waitcnt lgkmcnt(" #n ")" ::: "memory")
; #define PG8_BAR __builtin_amdgcn_s_barrier()
; #define PG8_SCHED __builtin_amdgcn_sched_barrier(0)
; template <class Epi, class Sched, bool ALIGN_EPI, bool LAST_FUSED = false, bool PERM = false, bool CARRY = false>
; __device__ __forceinline__ void gemm_phase(LAS unsigned char* lds, const int tid, const int K, const int lda, const int ldb, const Sched& S, const Epi& E) {
;     ...
;             PG8_WAIT_V(8); PG8_WAIT_L(0); PG8_BAR; PG8_MMA(1, 0, At, B0); PG8_MMA(1, 1, At, B1); PG8_BAR; PG8_SCHED;
;             PG8_LDB(B0, 1, 0); PG8_LDB(B1, 1, 1); PG8_SCHED; PG8_LDA(At, 1, 0); PG8_STAGE(PG8_SA(0, 1), a2 + hstepA, voffA);
;             PG8_WAIT_V(8); PG8_WAIT_L(0); PG8_BAR; PG8_MMA(0, 0, At, B0); PG8_MMA(0, 1, At, B1); PG8_BAR; PG8_SCHED;
;             PG8_LDA(At, 1, 1); PG8_STAGE(PG8_SB(1, 0), b3, voffB); PG8_STAGE(PG8_SB(1, 1), b3 + hstepB, voffB); PG8_STAGE(PG8_SA(1, 0), a3, voffA);
;             PG8_WAIT_V(8); PG8_WAIT_L(0); PG8_BAR; PG8_MMA(1, 0, At, B0); PG8_MMA(1, 1, At, B1); PG8_BAR; PG8_SCHED;
	v_mfma_f32_16x16x32_bf16 v[62:65], v[142:145], v[178:181], v[62:65]
	v_mfma_f32_16x16x32_bf16 v[58:61], v[150:153], v[178:181], v[58:61]
	v_mfma_f32_16x16x32_bf16 v[38:41], v[142:145], v[186:189], v[38:41]
	v_mfma_f32_16x16x32_bf16 v[34:37], v[150:153], v[186:189], v[34:37]
	v_mfma_f32_16x16x32_bf16 v[22:25], v[142:145], v[194:197], v[22:25]
	v_mfma_f32_16x16x32_bf16 v[18:21], v[150:153], v[194:197], v[18:21]
	v_mfma_f32_16x16x32_bf16 v[134:137], v[142:145], v[202:205], v[134:137]
	v_mfma_f32_16x16x32_bf16 v[130:133], v[150:153], v[202:205], v[130:133]
	v_mfma_f32_16x16x32_bf16 v[62:65], v[146:149], v[182:185], v[62:65]
	v_mfma_f32_16x16x32_bf16 v[58:61], v[158:161], v[182:185], v[58:61]
	v_mfma_f32_16x16x32_bf16 v[38:41], v[146:149], v[190:193], v[38:41]
	v_mfma_f32_16x16x32_bf16 v[34:37], v[158:161], v[190:193], v[34:37]
	v_mfma_f32_16x16x32_bf16 v[22:25], v[146:149], v[198:201], v[22:25]
	v_mfma_f32_16x16x32_bf16 v[18:21], v[158:161], v[198:201], v[18:21]
	v_mfma_f32_16x16x32_bf16 v[134:137], v[146:149], v[206:209], v[134:137]
	v_mfma_f32_16x16x32_bf16 v[130:133], v[158:161], v[206:209], v[130:133]
	s_setprio 0
	s_setprio 1
	v_mfma_f32_16x16x32_bf16 v[42:45], v[162:165], v[178:181], v[42:45]
	v_mfma_f32_16x16x32_bf16 v[46:49], v[170:173], v[178:181], v[46:49]
	v_mfma_f32_16x16x32_bf16 v[26:29], v[162:165], v[186:189], v[26:29]
	v_mfma_f32_16x16x32_bf16 v[30:33], v[170:173], v[186:189], v[30:33]
	v_mfma_f32_16x16x32_bf16 v[14:17], v[162:165], v[194:197], v[14:17]
	v_mfma_f32_16x16x32_bf16 v[10:13], v[170:173], v[194:197], v[10:13]
	v_mfma_f32_16x16x32_bf16 v[6:9], v[162:165], v[202:205], v[6:9]
	v_mfma_f32_16x16x32_bf16 v[2:5], v[170:173], v[202:205], v[2:5]
	v_mfma_f32_16x16x32_bf16 v[42:45], v[166:169], v[182:185], v[42:45]
	v_mfma_f32_16x16x32_bf16 v[46:49], v[174:177], v[182:185], v[46:49]
	v_mfma_f32_16x16x32_bf16 v[26:29], v[166:169], v[190:193], v[26:29]
	v_mfma_f32_16x16x32_bf16 v[30:33], v[174:177], v[190:193], v[30:33]
	v_mfma_f32_16x16x32_bf16 v[14:17], v[166:169], v[198:201], v[14:17]
	v_mfma_f32_16x16x32_bf16 v[10:13], v[174:177], v[198:201], v[10:13]
	v_mfma_f32_16x16x32_bf16 v[6:9], v[166:169], v[206:209], v[6:9]
	v_mfma_f32_16x16x32_bf16 v[2:5], v[174:177], v[206:209], v[2:5]
	s_barrier
	s_setprio 0
	s_add_i32 s92, 0, 0x18000
	s_add_i32 s93, 0, 0x1c000
	v_add_u32_e32 v158, s92, v140
	v_add_u32_e32 v174, s93, v140
	ds_read_b128 v[142:145], v158
	ds_read_b128 v[146:149], v158 offset:1024
	ds_read_b128 v[150:153], v158 offset:2048
	ds_read_b128 v[158:161], v158 offset:3072
	ds_read_b128 v[162:165], v174
	ds_read_b128 v[166:169], v174 offset:1024
	ds_read_b128 v[170:173], v174 offset:2048
	ds_read_b128 v[174:177], v174 offset:3072
	s_add_u32 s16, s56, 0x200000
	s_addc_u32 s17, s57, 0
	s_mov_b32 m0, s14
	v_lshl_add_u64 v[216:217], s[16:17], 0, v[0:1]
	ds_read_b128 v[178:181], v141 offset:32768
	ds_read_b128 v[182:185], v141 offset:33792
	ds_read_b128 v[186:189], v141 offset:34816
	ds_read_b128 v[190:193], v141 offset:35840
	ds_read_b128 v[194:197], v141 offset:36864
	ds_read_b128 v[198:201], v141 offset:37888
	ds_read_b128 v[202:205], v141 offset:38912
	ds_read_b128 v[206:209], v141 offset:39936
	global_load_lds_dwordx4 v[216:217], off
	v_lshl_add_u64 v[216:217], s[16:17], 0, v[122:123]
	s_mov_b32 m0, s22
	s_nop 0
	global_load_lds_dwordx4 v[216:217], off
	s_waitcnt vmcnt(8)
	s_waitcnt lgkmcnt(0)
	s_setprio 1
	s_barrier
	v_mfma_f32_16x16x32_bf16 v[118:121], v[142:145], v[178:181], v[118:121]
	v_mfma_f32_16x16x32_bf16 v[114:117], v[150:153], v[178:181], v[114:117]
	v_mfma_f32_16x16x32_bf16 v[110:113], v[142:145], v[186:189], v[110:113]
	v_mfma_f32_16x16x32_bf16 v[106:109], v[150:153], v[186:189], v[106:109]
	v_mfma_f32_16x16x32_bf16 v[86:89], v[142:145], v[194:197], v[86:89]
	v_mfma_f32_16x16x32_bf16 v[82:85], v[150:153], v[194:197], v[82:85]
	v_mfma_f32_16x16x32_bf16 v[78:81], v[142:145], v[202:205], v[78:81]
	v_mfma_f32_16x16x32_bf16 v[74:77], v[150:153], v[202:205], v[74:77]
	v_mfma_f32_16x16x32_bf16 v[118:121], v[146:149], v[182:185], v[118:121]
	v_mfma_f32_16x16x32_bf16 v[114:117], v[158:161], v[182:185], v[114:117]
	v_mfma_f32_16x16x32_bf16 v[110:113], v[146:149], v[190:193], v[110:113]
	v_mfma_f32_16x16x32_bf16 v[106:109], v[158:161], v[190:193], v[106:109]
	v_mfma_f32_16x16x32_bf16 v[86:89], v[146:149], v[198:201], v[86:89]
	v_mfma_f32_16x16x32_bf16 v[82:85], v[158:161], v[198:201], v[82:85]
	v_mfma_f32_16x16x32_bf16 v[78:81], v[146:149], v[206:209], v[78:81]
	v_mfma_f32_16x16x32_bf16 v[74:77], v[158:161], v[206:209], v[74:77]
	s_setprio 0
	s_setprio 1
	v_mfma_f32_16x16x32_bf16 v[98:101], v[162:165], v[178:181], v[98:101]
	v_mfma_f32_16x16x32_bf16 v[102:105], v[170:173], v[178:181], v[102:105]
	v_mfma_f32_16x16x32_bf16 v[90:93], v[162:165], v[186:189], v[90:93]
	v_mfma_f32_16x16x32_bf16 v[94:97], v[170:173], v[186:189], v[94:97]
	v_mfma_f32_16x16x32_bf16 v[66:69], v[162:165], v[194:197], v[66:69]
	v_mfma_f32_16x16x32_bf16 v[70:73], v[170:173], v[194:197], v[70:73]
	v_mfma_f32_16x16x32_bf16 v[50:53], v[162:165], v[202:205], v[50:53]
	v_mfma_f32_16x16x32_bf16 v[54:57], v[170:173], v[202:205], v[54:57]
	v_mfma_f32_16x16x32_bf16 v[98:101], v[166:169], v[182:185], v[98:101]
	v_mfma_f32_16x16x32_bf16 v[102:105], v[174:177], v[182:185], v[102:105]
	v_mfma_f32_16x16x32_bf16 v[90:93], v[166:169], v[190:193], v[90:93]
	v_mfma_f32_16x16x32_bf16 v[94:97], v[174:177], v[190:193], v[94:97]
	v_mfma_f32_16x16x32_bf16 v[66:69], v[166:169], v[198:201], v[66:69]
	v_mfma_f32_16x16x32_bf16 v[70:73], v[174:177], v[198:201], v[70:73]
	v_mfma_f32_16x16x32_bf16 v[50:53], v[166:169], v[206:209], v[50:53]
	v_mfma_f32_16x16x32_bf16 v[54:57], v[174:177], v[206:209], v[54:57]
	s_barrier
; #define PG8_STAGE(bufoff, gbase, voff) do { _Pragma("unroll") for (int _i = 0; _i < 2; ++_i) \
;         __builtin_amdgcn_global_load_lds((const unsigned*)((const char*)(gbase) + (voff)[_i]), (LAS unsigned*)(lds + (bufoff) + ldsw + _i * 8192), 16, 0, 0); } while (0)
; #define PG8_LDA(dst, b, h) do { _Pragma("unroll") for (int m = 0; m < 4; ++m) _Pragma("unroll") for (int k = 0; k < 2; ++k) dst[m][k] = *(const LAS bf16x8*)(lds + PG8_SA(b, h) + aoff + m * 2048 + k * 1024); } while (0)
; #define PG8_MMA(ai, bj, At, Bt) do { __builtin_amdgcn_s_setprio(1); _Pragma("unroll") for (int m = 0; m < 4; ++m) _Pragma("unroll") for (int n = 0; n < 2; ++n) _Pragma("unroll") for (int k = 0; k < 2; ++k) \
;         acc[ai][bj][m][n] = __builtin_amdgcn_mfma_f32_16x16x32_bf16(Bt[n][k], At[m][k], acc[ai][bj][m][n], 0, 0, 0); __builtin_amdgcn_s_setprio(0); } while (0)
; #define PG8_WAIT_V(n) asm volatile("s_waitcnt vmcnt(" #n ")" ::: "memory")
; #define PG8_WAIT_L(n) asm volatile("s_waitcnt lgkmcnt(" #n ")" ::: "memory")
; #define PG8_BAR __builtin_amdgcn_s_barrier()
; #define PG8_SCHED __builtin_amdgcn_sched_barrier(0)
; template <class Epi, class Sched, bool ALIGN_EPI, bool LAST_FUSED = false, bool PERM = false, bool CARRY = false>
; __device__ __forceinline__ void gemm_phase(LAS unsigned char* lds, const int tid, const int K, const int lda, const int ldb, const Sched& S, const Epi& E) {
;     ...
;             PG8_LDA(At, 1, 1); PG8_STAGE(PG8_SB(1, 0), b3, voffB); PG8_STAGE(PG8_SB(1, 1), b3 + hstepB, voffB); PG8_STAGE(PG8_SA(1, 0), a3, voffA);
;             PG8_WAIT_V(8); PG8_WAIT_L(0); PG8_BAR; PG8_MMA(1, 0, At, B0); PG8_MMA(1, 1, At, B1); PG8_BAR; PG8_SCHED;
;         }
;         if constexpr (ALIGN_EPI) { if (wr == 0) PG8_BAR; }
	s_setprio 0
	s_add_i32 s16, s92, s95
	v_lshl_add_u64 v[154:155], v[154:155], 0, s[68:69]
	s_mov_b32 m0, s16
	ds_read_b128 v[178:181], v141 offset:49152
	ds_read_b128 v[182:185], v141 offset:50176
	ds_read_b128 v[186:189], v141 offset:51200
	ds_read_b128 v[190:193], v141 offset:52224
	ds_read_b128 v[194:197], v141 offset:53248
	ds_read_b128 v[198:201], v141 offset:54272
	ds_read_b128 v[202:205], v141 offset:55296
	ds_read_b128 v[206:209], v141 offset:56320
	global_load_lds_dwordx4 v[154:155], off
	s_add_i32 m0, s16, 0x2000
	s_add_u32 s16, s52, 0x200080
	v_lshl_add_u64 v[154:155], v[210:211], 0, s[68:69]
	s_addc_u32 s17, s53, 0
	s_add_i32 s52, s93, s95
	global_load_lds_dwordx4 v[154:155], off
	v_lshl_add_u64 v[154:155], s[16:17], 0, v[0:1]
	s_mov_b32 m0, s52
	s_nop 0
	global_load_lds_dwordx4 v[154:155], off
	v_lshl_add_u64 v[154:155], s[16:17], 0, v[122:123]
	s_add_i32 m0, s52, 0x2000
	s_nop 0
	global_load_lds_dwordx4 v[154:155], off
	v_lshl_add_u64 v[154:155], v[212:213], 0, s[68:69]
	s_mov_b32 m0, s96
	s_nop 0
	global_load_lds_dwordx4 v[154:155], off
	v_lshl_add_u64 v[154:155], v[214:215], 0, s[68:69]
	s_mov_b32 m0, s97
	s_nop 0
	global_load_lds_dwordx4 v[154:155], off
	s_waitcnt vmcnt(8)
	s_waitcnt lgkmcnt(0)
	s_setprio 1
	s_barrier
	v_mfma_f32_16x16x32_bf16 v[62:65], v[142:145], v[178:181], v[62:65]
	v_mfma_f32_16x16x32_bf16 v[58:61], v[150:153], v[178:181], v[58:61]
	v_mfma_f32_16x16x32_bf16 v[38:41], v[142:145], v[186:189], v[38:41]
	v_mfma_f32_16x16x32_bf16 v[34:37], v[150:153], v[186:189], v[34:37]
	v_mfma_f32_16x16x32_bf16 v[22:25], v[142:145], v[194:197], v[22:25]
	v_mfma_f32_16x16x32_bf16 v[18:21], v[150:153], v[194:197], v[18:21]
	v_mfma_f32_16x16x32_bf16 v[134:137], v[142:145], v[202:205], v[134:137]
	v_mfma_f32_16x16x32_bf16 v[130:133], v[150:153], v[202:205], v[130:133]
	v_mfma_f32_16x16x32_bf16 v[62:65], v[146:149], v[182:185], v[62:65]
	v_mfma_f32_16x16x32_bf16 v[58:61], v[158:161], v[182:185], v[58:61]
	v_mfma_f32_16x16x32_bf16 v[38:41], v[146:149], v[190:193], v[38:41]
	v_mfma_f32_16x16x32_bf16 v[34:37], v[158:161], v[190:193], v[34:37]
	v_mfma_f32_16x16x32_bf16 v[22:25], v[146:149], v[198:201], v[22:25]
	v_mfma_f32_16x16x32_bf16 v[18:21], v[158:161], v[198:201], v[18:21]
	v_mfma_f32_16x16x32_bf16 v[134:137], v[146:149], v[206:209], v[134:137]
	v_mfma_f32_16x16x32_bf16 v[130:133], v[158:161], v[206:209], v[130:133]
	s_setprio 0
	s_setprio 1
	v_mfma_f32_16x16x32_bf16 v[42:45], v[162:165], v[178:181], v[42:45]
	v_mfma_f32_16x16x32_bf16 v[46:49], v[170:173], v[178:181], v[46:49]
	v_mfma_f32_16x16x32_bf16 v[26:29], v[162:165], v[186:189], v[26:29]
	v_mfma_f32_16x16x32_bf16 v[30:33], v[170:173], v[186:189], v[30:33]
	v_mfma_f32_16x16x32_bf16 v[14:17], v[162:165], v[194:197], v[14:17]
	v_mfma_f32_16x16x32_bf16 v[10:13], v[170:173], v[194:197], v[10:13]
	v_mfma_f32_16x16x32_bf16 v[6:9], v[162:165], v[202:205], v[6:9]
	v_mfma_f32_16x16x32_bf16 v[2:5], v[170:173], v[202:205], v[2:5]
	v_mfma_f32_16x16x32_bf16 v[42:45], v[166:169], v[182:185], v[42:45]
	v_mfma_f32_16x16x32_bf16 v[46:49], v[174:177], v[182:185], v[46:49]
	v_mfma_f32_16x16x32_bf16 v[26:29], v[166:169], v[190:193], v[26:29]
	v_mfma_f32_16x16x32_bf16 v[30:33], v[174:177], v[190:193], v[30:33]
	v_mfma_f32_16x16x32_bf16 v[14:17], v[166:169], v[198:201], v[14:17]
	v_mfma_f32_16x16x32_bf16 v[10:13], v[174:177], v[198:201], v[10:13]
	v_mfma_f32_16x16x32_bf16 v[6:9], v[166:169], v[206:209], v[6:9]
	v_mfma_f32_16x16x32_bf16 v[2:5], v[174:177], v[206:209], v[2:5]
	s_barrier
	s_setprio 0
	s_add_i32 s16, s60, 2
	s_add_u32 vcc_lo, vcc_lo, 0x100
	s_addc_u32 vcc_hi, vcc_hi, 0
	v_lshl_add_u64 v[138:139], v[138:139], 0, s[72:73]
	v_lshl_add_u64 v[128:129], v[128:129], 0, s[72:73]
	s_cmp_ge_i32 s60, s87
	s_mov_b32 s60, s16
	s_cbranch_scc0 .LBB0_1854
	s_and_b64 vcc, exec, s[40:41]
	s_cbranch_vccz .LBB0_1857
	s_barrier
